# lane-permutation moves folded into the consuming max/add (DPP operand), swap outputs combined directly, xor-4 max step via row_half_mirror
# baseline (speedup 1.0000x reference)
.LBB0_211:
	v_lshl_add_u64 v[36:37], s[92:93], 0, v[6:7]
	global_load_dwordx4 v[16:19], v[2:3], off offset:16
	global_load_dwordx4 v[20:23], v[2:3], off
	global_load_dwordx4 v[24:27], v[36:37], off
	global_load_dwordx4 v[28:31], v[36:37], off offset:16
	global_load_dwordx4 v[32:35], v[36:37], off offset:2048
	s_nop 0
	global_load_dwordx4 v[36:39], v[36:37], off offset:2064
	v_min_i32_e32 v1, 0x4000, v0
	v_lshl_add_u64 v[40:41], s[92:93], 0, v[4:5]
	v_ashrrev_i32_e32 v1, 11, v1
	v_add_co_u32_e32 v56, vcc, s28, v40
	v_mul_i32_i24_e32 v40, 0x9000, v1
	s_nop 0
	v_addc_co_u32_e32 v57, vcc, 0, v41, vcc
	v_mul_hi_i32_i24_e32 v41, 0x9000, v1
	v_lshl_add_u64 v[40:41], s[16:17], 0, v[40:41]
	v_lshl_add_u64 v[48:49], v[40:41], 0, s[6:7]
	v_mov_b32_e32 v9, v97
	v_lshl_add_u64 v[58:59], v[40:41], 0, v[96:97]
	v_lshl_add_u64 v[52:53], v[48:49], 0, v[96:97]
	global_load_dwordx4 v[40:43], v[58:59], off offset:16
	global_load_dwordx4 v[44:47], v[58:59], off
	v_lshl_add_u64 v[60:61], v[48:49], 0, v[8:9]
	global_load_dwordx4 v[48:51], v[52:53], off offset:16
	s_nop 0
	global_load_dwordx4 v[52:55], v[52:53], off
	global_load_dwordx4 v[86:89], v[2:3], off offset:2048
	global_load_dwordx4 v[90:93], v[60:61], off
	global_load_dwordx4 v[98:101], v[2:3], off offset:2064
	global_load_dwordx4 v[106:109], v[60:61], off offset:16
	global_load_dwordx4 v[110:113], v[58:59], off offset:2048
	global_load_dwordx4 v[114:117], v[58:59], off offset:2064
	v_add_u32_e32 v0, s8, v0
	v_lshl_add_u64 v[4:5], v[4:5], 0, s[30:31]
	v_lshl_add_u64 v[6:7], v[6:7], 0, s[14:15]
	s_waitcnt vmcnt(13)
	v_mov_b32_e32 v68, v25
	s_waitcnt vmcnt(12)
	v_mov_b32_e32 v69, v29
	v_mov_b32_e32 v66, v24
	v_mov_b32_e32 v67, v28
	s_waitcnt vmcnt(11)
	v_mov_b32_e32 v76, v33
	s_waitcnt vmcnt(10)
	v_mov_b32_e32 v77, v37
	v_pk_mul_f32 v[68:69], v[68:69], v[68:69]
	v_mov_b32_e32 v62, v26
	v_mov_b32_e32 v63, v30
	v_mov_b32_e32 v74, v32
	v_mov_b32_e32 v75, v36
	v_pk_mul_f32 v[76:77], v[76:77], v[76:77]
	v_pk_fma_f32 v[66:67], v[66:67], v[66:67], v[68:69]
	v_mov_b32_e32 v64, v27
	v_mov_b32_e32 v65, v31
	v_mov_b32_e32 v70, v34
	v_mov_b32_e32 v71, v38
	v_pk_fma_f32 v[68:69], v[74:75], v[74:75], v[76:77]
	v_pk_fma_f32 v[62:63], v[62:63], v[62:63], v[66:67]
	v_mov_b32_e32 v72, v35
	v_mov_b32_e32 v73, v39
	v_pk_fma_f32 v[66:67], v[70:71], v[70:71], v[68:69]
	v_pk_fma_f32 v[62:63], v[64:65], v[64:65], v[62:63]
	v_pk_fma_f32 v[64:65], v[72:73], v[72:73], v[66:67]
	v_add_f32_e32 v1, v62, v63
	v_add_f32_e32 v1, v1, v64
	v_add_f32_e32 v1, v1, v65
	v_mov_b32_e32 v9, v1
	v_mov_b32_e32 v255, v1
	s_nop 1
	v_permlane32_swap_b32_e32 v9, v255
	s_nop 1
	s_nop 0
	s_waitcnt vmcnt(7)
	v_pk_add_f32 v[48:49], v[48:49], 1.0 op_sel_hi:[1,0]
	s_waitcnt vmcnt(6)
	v_pk_add_f32 v[54:55], v[54:55], 1.0 op_sel_hi:[1,0]
	v_pk_add_f32 v[52:53], v[52:53], 1.0 op_sel_hi:[1,0]
	v_pk_add_f32 v[50:51], v[50:51], 1.0 op_sel_hi:[1,0]
	s_waitcnt lgkmcnt(0)
	v_add_f32_e32 v1, v9, v255
	v_mov_b32_e32 v9, v1
	v_mov_b32_e32 v255, v1
	s_nop 1
	v_permlane16_swap_b32_e32 v9, v255
	s_nop 1
	v_mov_b32_dpp v9, v255 quad_perm:[0,1,2,3] row_mask:0x5 bank_mask:0xf
	s_nop 0
	v_add_f32_e32 v1, v1, v9
	s_nop 1
	v_mov_b32_dpp v9, v1 row_ror:8 row_mask:0xf bank_mask:0xf
	s_nop 0
	v_add_f32_e32 v1, v1, v9
	s_nop 1
	v_mov_b32_dpp v9, v1 row_shl:4 row_mask:0xf bank_mask:0x5
	v_mov_b32_dpp v9, v1 row_shr:4 row_mask:0xf bank_mask:0xa
	s_nop 0
	v_add_f32_e32 v1, v1, v9
	s_nop 1
	v_mov_b32_dpp v9, v1 quad_perm:[2,3,0,1] row_mask:0xf bank_mask:0xf
	s_nop 0
	v_add_f32_e32 v1, v1, v9
	s_nop 1
	s_nop 0
	s_nop 0
	v_add_f32_dpp v1, v1, v1 quad_perm:[1,0,3,2] row_mask:0xf bank_mask:0xf
	v_fmamk_f32 v1, v1, 0x3a800000, v163
	v_mul_f32_e32 v9, 0x4b800000, v1
	v_cmp_gt_f32_e32 vcc, s86, v1
	s_nop 1
	v_cndmask_b32_e32 v1, v1, v9, vcc
	v_rsq_f32_e32 v1, v1
	s_nop 0
	v_mul_f32_e32 v9, 0x45800000, v1
	v_cndmask_b32_e32 v62, v1, v9, vcc
	v_pk_mul_f32 v[24:25], v[24:25], v[62:63] op_sel_hi:[1,0]
	v_pk_mul_f32 v[26:27], v[26:27], v[62:63] op_sel_hi:[1,0]
	v_pk_mul_f32 v[28:29], v[28:29], v[62:63] op_sel_hi:[1,0]
	v_pk_mul_f32 v[30:31], v[30:31], v[62:63] op_sel_hi:[1,0]
	v_pk_mul_f32 v[20:21], v[20:21], v[24:25]
	v_pk_mul_f32 v[22:23], v[22:23], v[26:27]
	v_pk_mul_f32 v[16:17], v[28:29], v[16:17]
	v_pk_mul_f32 v[18:19], v[30:31], v[18:19]
	v_pk_fma_f32 v[20:21], v[52:53], v[20:21], v[44:45]
	v_pk_fma_f32 v[22:23], v[54:55], v[22:23], v[46:47]
	v_pk_fma_f32 v[24:25], v[16:17], v[48:49], v[40:41]
	v_pk_fma_f32 v[26:27], v[18:19], v[50:51], v[42:43]
	v_cvt_pk_bf16_f32 v16, v20, v21
	v_cvt_pk_bf16_f32 v17, v22, v23
	v_cvt_pk_bf16_f32 v18, v24, v25
	v_cvt_pk_bf16_f32 v19, v26, v27
	global_store_dwordx4 v[56:57], v[16:19], off
	s_nop 0
	v_pk_mul_f32 v[32:33], v[32:33], v[62:63] op_sel_hi:[1,0]
	v_pk_mul_f32 v[34:35], v[34:35], v[62:63] op_sel_hi:[1,0]
	v_pk_mul_f32 v[36:37], v[36:37], v[62:63] op_sel_hi:[1,0]
	v_pk_mul_f32 v[38:39], v[38:39], v[62:63] op_sel_hi:[1,0]
	v_cmp_lt_i32_e32 vcc, s29, v0
	s_or_b64 s[2:3], vcc, s[2:3]
	s_waitcnt vmcnt(6)
	v_pk_mul_f32 v[16:17], v[32:33], v[86:87]
	s_waitcnt vmcnt(5)
	v_pk_add_f32 v[20:21], v[90:91], 1.0 op_sel_hi:[1,0]
	v_pk_mul_f32 v[18:19], v[34:35], v[88:89]
	v_pk_add_f32 v[22:23], v[92:93], 1.0 op_sel_hi:[1,0]
	s_waitcnt vmcnt(4)
	v_pk_mul_f32 v[24:25], v[36:37], v[98:99]
	s_waitcnt vmcnt(3)
	v_pk_add_f32 v[28:29], v[106:107], 1.0 op_sel_hi:[1,0]
	v_pk_mul_f32 v[26:27], v[38:39], v[100:101]
	v_pk_add_f32 v[30:31], v[108:109], 1.0 op_sel_hi:[1,0]
	s_waitcnt vmcnt(2)
	v_pk_fma_f32 v[16:17], v[16:17], v[20:21], v[110:111]
	v_pk_fma_f32 v[18:19], v[18:19], v[22:23], v[112:113]
	s_waitcnt vmcnt(1)
	v_pk_fma_f32 v[20:21], v[24:25], v[28:29], v[114:115]
	v_pk_fma_f32 v[22:23], v[26:27], v[30:31], v[116:117]
	v_cvt_pk_bf16_f32 v16, v16, v17
	v_cvt_pk_bf16_f32 v17, v18, v19
	v_cvt_pk_bf16_f32 v18, v20, v21
	v_cvt_pk_bf16_f32 v19, v22, v23
	global_store_dwordx4 v[56:57], v[16:19], off offset:1024
	s_andn2_b64 exec, exec, s[2:3]
	s_cbranch_execnz .LBB0_211

.LBB0_390:
	v_min_i32_e32 v0, 0x4000, v12
	v_ashrrev_i32_e32 v0, 11, v0
	v_mul_hi_i32_i24_e32 v1, 0x9000, v0
	v_mul_i32_i24_e32 v0, 0x9000, v0
	v_lshl_add_u64 v[0:1], s[2:3], 0, v[0:1]
	v_lshl_add_u64 v[26:27], v[0:1], 0, s[10:11]
	v_lshl_add_u64 v[58:59], s[92:93], 0, v[20:21]
	v_lshl_add_u64 v[4:5], v[26:27], 0, v[96:97]
	v_lshl_add_u64 v[24:25], v[0:1], 0, v[96:97]
	global_load_dwordx4 v[38:41], v[58:59], off offset:16
	global_load_dwordx4 v[8:11], v[58:59], off
	global_load_dwordx4 v[42:45], v[16:17], off offset:16
	global_load_dwordx4 v[46:49], v[16:17], off
	global_load_dwordx4 v[50:53], v[24:25], off offset:16
	global_load_dwordx4 v[54:57], v[24:25], off
	global_load_dwordx4 v[0:3], v[4:5], off offset:16
	s_nop 0
	global_load_dwordx4 v[4:7], v[4:5], off
	v_mov_b32_e32 v23, v97
	v_lshl_add_u64 v[26:27], v[26:27], 0, v[22:23]
	v_lshl_add_u64 v[30:31], s[92:93], 0, v[18:19]
	v_add_u32_e32 v12, s8, v12
	v_lshl_add_u64 v[18:19], v[18:19], 0, s[30:31]
	v_lshl_add_u64 v[20:21], v[20:21], 0, s[14:15]
	s_waitcnt vmcnt(7)
	v_mov_b32_e32 v67, v39
	s_waitcnt vmcnt(6)
	v_mov_b32_e32 v66, v9
	v_pk_mul_f32 v[66:67], v[66:67], v[66:67]
	s_waitcnt vmcnt(1)
	v_pk_add_f32 v[60:61], v[0:1], 1.0 op_sel_hi:[1,0]
	s_waitcnt vmcnt(0)
	v_pk_add_f32 v[62:63], v[6:7], 1.0 op_sel_hi:[1,0]
	v_mov_b32_e32 v6, v8
	v_mov_b32_e32 v7, v38
	v_mov_b32_e32 v0, v10
	v_mov_b32_e32 v1, v40
	v_pk_fma_f32 v[6:7], v[6:7], v[6:7], v[66:67]
	v_pk_add_f32 v[64:65], v[4:5], 1.0 op_sel_hi:[1,0]
	v_mov_b32_e32 v4, v11
	v_mov_b32_e32 v5, v41
	v_pk_fma_f32 v[0:1], v[0:1], v[0:1], v[6:7]
	v_pk_add_f32 v[68:69], v[2:3], 1.0 op_sel_hi:[1,0]
	v_pk_fma_f32 v[66:67], v[4:5], v[4:5], v[0:1]
	global_load_dwordx4 v[0:3], v[58:59], off offset:2064
	global_load_dwordx4 v[4:7], v[58:59], off offset:2048
	global_load_dwordx4 v[86:89], v[14:15], off offset:16
	global_load_dwordx4 v[90:93], v[14:15], off
	global_load_dwordx4 v[98:101], v[24:25], off offset:2064
	global_load_dwordx4 v[106:109], v[24:25], off offset:2048
	global_load_dwordx4 v[110:113], v[26:27], off offset:16
	global_load_dwordx4 v[114:117], v[26:27], off
	v_add_f32_e32 v13, v66, v67
	s_waitcnt vmcnt(7)
	v_mov_b32_e32 v75, v1
	s_waitcnt vmcnt(6)
	v_mov_b32_e32 v74, v5
	v_mov_b32_e32 v72, v4
	v_mov_b32_e32 v73, v0
	v_pk_mul_f32 v[74:75], v[74:75], v[74:75]
	v_mov_b32_e32 v58, v6
	v_mov_b32_e32 v59, v2
	v_pk_fma_f32 v[72:73], v[72:73], v[72:73], v[74:75]
	v_mov_b32_e32 v70, v7
	v_mov_b32_e32 v71, v3
	v_pk_fma_f32 v[58:59], v[58:59], v[58:59], v[72:73]
	s_nop 0
	v_pk_fma_f32 v[58:59], v[70:71], v[70:71], v[58:59]
	s_nop 0
	v_add_f32_e32 v13, v13, v58
	v_add_f32_e32 v13, v13, v59
	v_mov_b32_e32 v23, v13
	v_mov_b32_e32 v255, v13
	s_nop 1
	v_permlane32_swap_b32_e32 v23, v255
	s_nop 1
	s_nop 0
	s_waitcnt lgkmcnt(0)
	v_add_f32_e32 v13, v23, v255
	v_mov_b32_e32 v23, v13
	v_mov_b32_e32 v255, v13
	s_nop 1
	v_permlane16_swap_b32_e32 v23, v255
	s_nop 1
	v_mov_b32_dpp v23, v255 quad_perm:[0,1,2,3] row_mask:0x5 bank_mask:0xf
	s_nop 0
	v_add_f32_e32 v13, v13, v23
	s_nop 1
	v_mov_b32_dpp v23, v13 row_ror:8 row_mask:0xf bank_mask:0xf
	s_nop 0
	v_add_f32_e32 v13, v13, v23
	s_nop 1
	v_mov_b32_dpp v23, v13 row_shl:4 row_mask:0xf bank_mask:0x5
	v_mov_b32_dpp v23, v13 row_shr:4 row_mask:0xf bank_mask:0xa
	s_nop 0
	v_add_f32_e32 v13, v13, v23
	s_nop 1
	v_mov_b32_dpp v23, v13 quad_perm:[2,3,0,1] row_mask:0xf bank_mask:0xf
	s_nop 0
	v_add_f32_e32 v13, v13, v23
	s_nop 1
	s_nop 0
	s_nop 0
	v_add_f32_dpp v13, v13, v13 quad_perm:[1,0,3,2] row_mask:0xf bank_mask:0xf
	v_fmamk_f32 v13, v13, 0x3a800000, v163
	v_cmp_gt_f32_e32 vcc, s86, v13
	v_mul_f32_e32 v23, 0x4b800000, v13
	s_nop 0
	v_cndmask_b32_e32 v13, v13, v23, vcc
	v_rsq_f32_e32 v13, v13
	s_nop 0
	v_mul_f32_e32 v23, 0x45800000, v13
	v_cndmask_b32_e32 v28, v13, v23, vcc
	v_pk_mul_f32 v[8:9], v[8:9], v[28:29] op_sel_hi:[1,0]
	v_pk_mul_f32 v[10:11], v[10:11], v[28:29] op_sel_hi:[1,0]
	v_pk_mul_f32 v[8:9], v[46:47], v[8:9]
	v_pk_mul_f32 v[10:11], v[48:49], v[10:11]
	v_pk_fma_f32 v[8:9], v[64:65], v[8:9], v[54:55]
	v_pk_fma_f32 v[10:11], v[62:63], v[10:11], v[56:57]
	v_cvt_pk_bf16_f32 v8, v8, v9
	v_cvt_pk_bf16_f32 v9, v10, v11
	v_pk_mul_f32 v[10:11], v[38:39], v[28:29] op_sel_hi:[1,0]
	v_pk_mul_f32 v[38:39], v[40:41], v[28:29] op_sel_hi:[1,0]
	v_pk_mul_f32 v[10:11], v[10:11], v[42:43]
	v_pk_mul_f32 v[38:39], v[38:39], v[44:45]
	v_pk_fma_f32 v[10:11], v[10:11], v[60:61], v[50:51]
	v_pk_fma_f32 v[38:39], v[38:39], v[68:69], v[52:53]
	v_add_co_u32_e32 v30, vcc, s28, v30
	v_cvt_pk_bf16_f32 v10, v10, v11
	v_cvt_pk_bf16_f32 v11, v38, v39
	v_addc_co_u32_e32 v31, vcc, 0, v31, vcc
	global_store_dwordx4 v[30:31], v[8:11], off
	s_nop 0
	s_nop 0
	v_pk_mul_f32 v[4:5], v[4:5], v[28:29] op_sel_hi:[1,0]
	v_pk_mul_f32 v[6:7], v[6:7], v[28:29] op_sel_hi:[1,0]
	v_pk_mul_f32 v[0:1], v[0:1], v[28:29] op_sel_hi:[1,0]
	v_pk_mul_f32 v[2:3], v[2:3], v[28:29] op_sel_hi:[1,0]
	v_cmp_lt_i32_e32 vcc, s29, v12
	s_or_b64 s[6:7], vcc, s[6:7]
	s_waitcnt vmcnt(6)
	v_pk_mul_f32 v[0:1], v[0:1], v[86:87]
	s_waitcnt vmcnt(5)
	v_pk_mul_f32 v[4:5], v[4:5], v[90:91]
	v_pk_mul_f32 v[6:7], v[6:7], v[92:93]
	v_pk_mul_f32 v[2:3], v[2:3], v[88:89]
	s_waitcnt vmcnt(1)
	v_pk_add_f32 v[24:25], v[114:115], 1.0 op_sel_hi:[1,0]
	s_nop 0
	v_pk_fma_f32 v[4:5], v[4:5], v[24:25], v[106:107]
	v_pk_add_f32 v[24:25], v[116:117], 1.0 op_sel_hi:[1,0]
	v_cvt_pk_bf16_f32 v4, v4, v5
	v_pk_fma_f32 v[6:7], v[6:7], v[24:25], v[108:109]
	s_nop 0
	v_cvt_pk_bf16_f32 v5, v6, v7
	v_pk_add_f32 v[6:7], v[110:111], 1.0 op_sel_hi:[1,0]
	s_nop 0
	v_pk_fma_f32 v[0:1], v[0:1], v[6:7], v[98:99]
	v_pk_add_f32 v[6:7], v[112:113], 1.0 op_sel_hi:[1,0]
	s_nop 0
	v_pk_fma_f32 v[2:3], v[2:3], v[6:7], v[100:101]
	v_cvt_pk_bf16_f32 v6, v0, v1
	v_cvt_pk_bf16_f32 v7, v2, v3
	global_store_dwordx4 v[30:31], v[4:7], off offset:1024
	s_andn2_b64 exec, exec, s[6:7]
	s_cbranch_execnz .LBB0_390

.LBB0_717:
	s_or_b64 exec, exec, s[6:7]
	ds_write_b128 v70, v[52:55]
	ds_write_b128 v70, v[56:59] offset:4608
	ds_write_b128 v70, v[60:63] offset:9216
	ds_write_b128 v70, v[64:67] offset:13824
	s_waitcnt lgkmcnt(0)
	s_barrier
	ds_read_b128 v[32:35], v158
	ds_read_b128 v[36:39], v158 offset:4608
	s_waitcnt lgkmcnt(1)
	v_mfma_f32_32x32x16_bf16 v[80:95], v[98:101], v[32:35], 0
	s_waitcnt lgkmcnt(0)
	v_mfma_f32_32x32x16_bf16 v[48:63], v[98:101], v[36:39], 0
	ds_read_b128 v[32:35], v158 offset:9216
	ds_read_b128 v[36:39], v158 offset:13824
	s_waitcnt lgkmcnt(1)
	v_mfma_f32_32x32x16_bf16 v[64:79], v[98:101], v[32:35], 0
	s_waitcnt lgkmcnt(0)
	v_mfma_f32_32x32x16_bf16 v[32:47], v[98:101], v[36:39], 0
	ds_read_b128 v[148:151], v158 offset:32
	s_waitcnt lgkmcnt(0)
	v_mfma_f32_32x32x16_bf16 v[80:95], v[102:105], v[148:151], v[80:95]
	ds_read_b128 v[148:151], v158 offset:4640
	s_waitcnt lgkmcnt(0)
	v_mfma_f32_32x32x16_bf16 v[48:63], v[102:105], v[148:151], v[48:63]
	ds_read_b128 v[148:151], v158 offset:9248
	s_waitcnt lgkmcnt(0)
	v_mfma_f32_32x32x16_bf16 v[64:79], v[102:105], v[148:151], v[64:79]
	ds_read_b128 v[148:151], v158 offset:13856
	s_waitcnt lgkmcnt(0)
	v_mfma_f32_32x32x16_bf16 v[32:47], v[102:105], v[148:151], v[32:47]
	ds_read_b128 v[148:151], v158 offset:64
	s_waitcnt lgkmcnt(0)
	v_mfma_f32_32x32x16_bf16 v[80:95], v[106:109], v[148:151], v[80:95]
	ds_read_b128 v[148:151], v158 offset:4672
	s_waitcnt lgkmcnt(0)
	v_mfma_f32_32x32x16_bf16 v[48:63], v[106:109], v[148:151], v[48:63]
	ds_read_b128 v[148:151], v158 offset:9280
	s_waitcnt lgkmcnt(0)
	v_mfma_f32_32x32x16_bf16 v[64:79], v[106:109], v[148:151], v[64:79]
	ds_read_b128 v[148:151], v158 offset:13888
	s_waitcnt lgkmcnt(0)
	v_mfma_f32_32x32x16_bf16 v[32:47], v[106:109], v[148:151], v[32:47]
	ds_read_b128 v[148:151], v158 offset:96
	s_waitcnt lgkmcnt(0)
	v_mfma_f32_32x32x16_bf16 v[80:95], v[110:113], v[148:151], v[80:95]
	ds_read_b128 v[148:151], v158 offset:4704
	s_waitcnt lgkmcnt(0)
	v_mfma_f32_32x32x16_bf16 v[48:63], v[110:113], v[148:151], v[48:63]
	ds_read_b128 v[148:151], v158 offset:9312
	s_waitcnt lgkmcnt(0)
	v_mfma_f32_32x32x16_bf16 v[64:79], v[110:113], v[148:151], v[64:79]
	ds_read_b128 v[148:151], v158 offset:13920
	s_waitcnt lgkmcnt(0)
	v_mfma_f32_32x32x16_bf16 v[32:47], v[110:113], v[148:151], v[32:47]
	s_cmp_eq_u32 s53, 1
	s_cbranch_scc1 .Latt_nm
	s_cmp_gt_u32 s53, 2
	s_cbranch_scc1 .Latt_nm
	s_add_i32 s6, s53, s49
	v_mbcnt_hi_u32_b32 v148, -1, v195
	v_lshl_add_u32 v96, s6, 7, v183
	v_and_b32_e32 v147, 64, v148
	v_add_u32_e32 v149, 64, v147
	v_sub_u32_e32 v147, v96, v159
	v_cmp_gt_u32_e32 vcc, s58, v147
	s_or_b64 vcc, s[2:3], vcc
	v_add_u32_e32 v150, 32, v147
	v_cndmask_b32_e32 v80, v204, v80, vcc
	v_cmp_gt_u32_e32 vcc, s58, v150
	s_or_b64 vcc, s[2:3], vcc
	v_add_u32_e32 v151, 64, v147
	v_cndmask_b32_e32 v48, v204, v48, vcc
	v_cmp_gt_u32_e32 vcc, s58, v151
	s_or_b64 vcc, s[2:3], vcc
	v_add_u32_e32 v147, 0x60, v147
	v_cndmask_b32_e32 v64, v204, v64, vcc
	v_cmp_gt_u32_e32 vcc, s58, v147
	s_or_b64 vcc, s[2:3], vcc
	v_xor_b32_e32 v147, 16, v148
	v_cndmask_b32_e32 v32, v204, v32, vcc
	v_cmp_lt_i32_e32 vcc, v147, v149
	v_max3_f32 v150, v80, s59, v48
	v_max3_f32 v150, v150, v64, v32
	v_cndmask_b32_e32 v147, v148, v147, vcc
	v_lshlrev_b32_e32 v147, 2, v147
	v_mov_b32_e32 v151, v150
	v_mov_b32_e32 v255, v150
	s_nop 1
	v_permlane16_swap_b32_e32 v151, v255
	s_nop 1
	s_nop 0
	v_add_u32_e32 v187, 0x8800, v186
	v_add_u32_e32 v215, 0x9000, v186
	s_nop 0
	s_nop 0
	v_max_f32_e32 v150, v151, v255
	v_xor_b32_e32 v151, 8, v148
	v_cmp_lt_i32_e32 vcc, v151, v149
	s_nop 1
	v_cndmask_b32_e32 v151, v148, v151, vcc
	v_lshlrev_b32_e32 v208, 2, v151
	s_nop 0
	s_nop 0
	s_nop 0
	v_max_f32_dpp v150, v150, v150 row_ror:8 row_mask:0xf bank_mask:0xf
	v_xor_b32_e32 v151, 4, v148
	v_cmp_lt_i32_e32 vcc, v151, v149
	s_nop 1
	v_cndmask_b32_e32 v151, v148, v151, vcc
	v_lshlrev_b32_e32 v209, 2, v151
	s_nop 0
	s_nop 0
	s_nop 0
	s_nop 0
	v_max_f32_dpp v150, v150, v150 row_half_mirror row_mask:0xf bank_mask:0xf
	v_xor_b32_e32 v151, 2, v148
	v_cmp_lt_i32_e32 vcc, v151, v149
	s_nop 1
	v_cndmask_b32_e32 v151, v148, v151, vcc
	v_lshlrev_b32_e32 v210, 2, v151
	s_nop 0
	s_nop 0
	s_nop 0
	v_max_f32_dpp v150, v150, v150 quad_perm:[2,3,0,1] row_mask:0xf bank_mask:0xf
	v_xor_b32_e32 v151, 1, v148
	v_cmp_lt_i32_e32 vcc, v151, v149
	v_sub_u32_e32 v149, v96, v161
	s_nop 0
	v_cndmask_b32_e32 v148, v148, v151, vcc
	v_cmp_gt_u32_e32 vcc, s58, v149
	s_or_b64 vcc, s[2:3], vcc
	v_lshlrev_b32_e32 v211, 2, v148
	v_cndmask_b32_e32 v151, v204, v81, vcc
	v_add_u32_e32 v81, 32, v149
	v_cmp_gt_u32_e32 vcc, s58, v81
	s_or_b64 vcc, s[2:3], vcc
	v_add_u32_e32 v81, 64, v149
	v_cndmask_b32_e32 v152, v204, v49, vcc
	v_cmp_gt_u32_e32 vcc, s58, v81
	s_or_b64 vcc, s[2:3], vcc
	v_max3_f32 v49, v151, s59, v152
	v_cndmask_b32_e32 v153, v204, v65, vcc
	v_add_u32_e32 v65, 0x60, v149
	v_cmp_gt_u32_e32 vcc, s58, v65
	s_or_b64 vcc, s[2:3], vcc
	v_mov_b32_dpp v148, v150 quad_perm:[1,0,3,2] row_mask:0xf bank_mask:0xf
	v_cndmask_b32_e32 v154, v204, v33, vcc
	v_max3_f32 v33, v49, v153, v154
	v_mov_b32_e32 v49, v33
	v_mov_b32_e32 v255, v33
	s_nop 1
	v_permlane16_swap_b32_e32 v49, v255
	s_nop 1
	s_nop 0
	s_nop 0
	v_max3_f32 v207, v130, v150, v148
	v_sub_f32_e32 v48, v48, v207
	v_mul_f32_e32 v48, 0x3fb8aa3b, v48
	s_nop 0
	s_nop 0
	v_max_f32_e32 v49, v49, v255
	s_nop 1
	s_nop 0
	v_sub_f32_e32 v33, v80, v207
	v_sub_f32_e32 v32, v32, v207
	v_mul_f32_e32 v32, 0x3fb8aa3b, v32
	v_sub_f32_e32 v130, v130, v207
	s_nop 0
	s_nop 0
	v_max_f32_dpp v65, v49, v49 row_ror:8 row_mask:0xf bank_mask:0xf
	s_nop 1
	v_mov_b32_dpp v80, v65 row_shl:4 row_mask:0xf bank_mask:0x5
	v_mov_b32_dpp v80, v65 row_shr:4 row_mask:0xf bank_mask:0xa
	v_exp_f32_e32 v49, v48
	v_sub_f32_e32 v48, v64, v207
	v_mul_f32_e32 v48, 0x3fb8aa3b, v48
	v_exp_f32_e32 v81, v48
	s_nop 0
	v_max_f32_e32 v64, v80, v80
	v_max_f32_e32 v64, v65, v64
	s_nop 1
	v_mov_b32_dpp v80, v64 quad_perm:[2,3,0,1] row_mask:0xf bank_mask:0xf
	v_exp_f32_e32 v65, v32
	v_mul_f32_e32 v33, 0x3fb8aa3b, v33
	v_exp_f32_e32 v33, v33
	s_nop 0
	v_max_f32_e32 v32, v80, v80
	v_max_f32_e32 v32, v64, v32
	s_nop 1
	v_mov_b32_dpp v48, v32 quad_perm:[1,0,3,2] row_mask:0xf bank_mask:0xf
	v_mul_f32_e32 v64, 0x3fb8aa3b, v130
	v_exp_f32_e32 v130, v64
	v_cvt_pk_bf16_f32 v148, v33, v49
	v_cvt_pk_bf16_f32 v149, v81, v65
	s_nop 0
	v_max3_f32 v206, v131, v32, v48
	v_sub_u32_e32 v32, v96, v169
	v_cmp_gt_u32_e32 vcc, s58, v32
	s_or_b64 vcc, s[2:3], vcc
	v_add_u32_e32 v48, 32, v32
	v_cndmask_b32_e32 v82, v204, v82, vcc
	v_cmp_gt_u32_e32 vcc, s58, v48
	s_or_b64 vcc, s[2:3], vcc
	v_add_u32_e32 v64, 64, v32
	v_cndmask_b32_e32 v50, v204, v50, vcc
	v_cmp_gt_u32_e32 vcc, s58, v64
	s_or_b64 vcc, s[2:3], vcc
	v_add_u32_e32 v32, 0x60, v32
	v_cndmask_b32_e32 v66, v204, v66, vcc
	v_cmp_gt_u32_e32 vcc, s58, v32
	s_or_b64 vcc, s[2:3], vcc
	v_max3_f32 v48, v82, s59, v50
	v_cndmask_b32_e32 v34, v204, v34, vcc
	v_max3_f32 v48, v48, v66, v34
	v_mov_b32_e32 v64, v48
	v_mov_b32_e32 v255, v48
	s_nop 1
	v_permlane16_swap_b32_e32 v64, v255
	s_nop 1
	s_nop 0
	v_sub_f32_e32 v32, v151, v206
	v_sub_f32_e32 v80, v152, v206
	v_mul_f32_e32 v32, 0x3fb8aa3b, v32
	v_exp_f32_e32 v32, v32
	s_nop 0
	s_nop 0
	v_max_f32_e32 v64, v64, v255
	s_nop 1
	s_nop 0
	v_mul_f32_e32 v48, 0x3fb8aa3b, v80
	v_sub_f32_e32 v80, v153, v206
	v_mul_f32_e32 v80, 0x3fb8aa3b, v80
	v_exp_f32_e32 v48, v48
	s_nop 0
	s_nop 0
	v_max_f32_dpp v150, v64, v64 row_ror:8 row_mask:0xf bank_mask:0xf
	v_sub_f32_e32 v64, v154, v206
	v_sub_u32_e32 v154, v96, v170
	v_cmp_gt_u32_e32 vcc, s58, v154
	s_or_b64 vcc, s[2:3], vcc
	s_nop 0
	s_nop 0
	v_cndmask_b32_e32 v155, v204, v83, vcc
	v_add_u32_e32 v83, 32, v154
	v_cmp_gt_u32_e32 vcc, s58, v83
	s_or_b64 vcc, s[2:3], vcc
	v_add_u32_e32 v83, 64, v154
	v_cndmask_b32_e32 v156, v204, v51, vcc
	v_cmp_gt_u32_e32 vcc, s58, v83
	s_or_b64 vcc, s[2:3], vcc
	v_max3_f32 v51, v155, s59, v156
	v_cndmask_b32_e32 v160, v204, v67, vcc
	v_add_u32_e32 v67, 0x60, v154
	v_cmp_gt_u32_e32 vcc, s58, v67
	s_or_b64 vcc, s[2:3], vcc
	s_nop 0
	s_nop 0
	v_cndmask_b32_e32 v154, v204, v35, vcc
	v_max3_f32 v35, v51, v160, v154
	v_max_f32_dpp v152, v150, v150 row_half_mirror row_mask:0xf bank_mask:0xf
	v_mov_b32_e32 v51, v35
	v_mov_b32_e32 v255, v35
	s_nop 1
	v_permlane16_swap_b32_e32 v51, v255
	s_nop 1
	s_nop 0
	s_nop 1
	v_mov_b32_dpp v153, v152 quad_perm:[2,3,0,1] row_mask:0xf bank_mask:0xf
	v_mul_f32_e32 v64, 0x3fb8aa3b, v64
	v_exp_f32_e32 v80, v80
	v_exp_f32_e32 v64, v64
	s_nop 0
	s_nop 0
	s_nop 0
	v_max_f32_e32 v153, v153, v153
	v_max_f32_e32 v51, v51, v255
	v_max_f32_e32 v152, v152, v153
	s_nop 1
	s_nop 0
	s_nop 1
	v_mov_b32_dpp v153, v152 quad_perm:[1,0,3,2] row_mask:0xf bank_mask:0xf
	v_cvt_pk_bf16_f32 v150, v32, v48
	v_cvt_pk_bf16_f32 v151, v80, v64
	ds_write2_b64 v187, v[148:149], v[150:151] offset0:128 offset1:162
	s_nop 0
	s_nop 0
	s_nop 0
	v_max3_f32 v189, v132, v152, v153
	v_max_f32_dpp v67, v51, v51 row_ror:8 row_mask:0xf bank_mask:0xf
	v_sub_f32_e32 v35, v82, v189
	s_nop 1
	v_mov_b32_dpp v82, v67 row_shl:4 row_mask:0xf bank_mask:0x5
	v_mov_b32_dpp v82, v67 row_shr:4 row_mask:0xf bank_mask:0xa
	v_sub_f32_e32 v50, v50, v189
	v_mul_f32_e32 v50, 0x3fb8aa3b, v50
	v_exp_f32_e32 v51, v50
	v_sub_f32_e32 v50, v66, v189
	s_waitcnt lgkmcnt(0)
	v_max_f32_e32 v66, v82, v82
	v_max_f32_e32 v66, v67, v66
	s_nop 1
	v_mov_b32_dpp v82, v66 quad_perm:[2,3,0,1] row_mask:0xf bank_mask:0xf
	v_sub_f32_e32 v34, v34, v189
	v_mul_f32_e32 v34, 0x3fb8aa3b, v34
	v_exp_f32_e32 v67, v34
	v_mul_f32_e32 v50, 0x3fb8aa3b, v50
	s_nop 0
	v_max_f32_e32 v34, v82, v82
	v_max_f32_e32 v34, v66, v34
	v_exp_f32_e32 v83, v50
	s_nop 1
	v_mov_b32_dpp v50, v34 quad_perm:[1,0,3,2] row_mask:0xf bank_mask:0xf
	v_sub_f32_e32 v132, v132, v189
	v_mul_f32_e32 v66, 0x3fb8aa3b, v132
	v_exp_f32_e32 v132, v66
	v_mul_f32_e32 v35, 0x3fb8aa3b, v35
	s_nop 0
	v_max3_f32 v188, v133, v34, v50
	v_sub_u32_e32 v34, v96, v171
	v_cmp_gt_u32_e32 vcc, s58, v34
	s_or_b64 vcc, s[2:3], vcc
	v_add_u32_e32 v50, 32, v34
	v_cndmask_b32_e32 v84, v204, v84, vcc
	v_cmp_gt_u32_e32 vcc, s58, v50
	s_or_b64 vcc, s[2:3], vcc
	v_add_u32_e32 v66, 64, v34
	v_cndmask_b32_e32 v52, v204, v52, vcc
	v_cmp_gt_u32_e32 vcc, s58, v66
	s_or_b64 vcc, s[2:3], vcc
	v_add_u32_e32 v34, 0x60, v34
	v_cndmask_b32_e32 v68, v204, v68, vcc
	v_cmp_gt_u32_e32 vcc, s58, v34
	s_or_b64 vcc, s[2:3], vcc
	v_max3_f32 v50, v84, s59, v52
	v_cndmask_b32_e32 v150, v204, v36, vcc
	v_max3_f32 v34, v50, v68, v150
	v_mov_b32_e32 v36, v34
	v_mov_b32_e32 v255, v34
	s_nop 1
	v_permlane16_swap_b32_e32 v36, v255
	s_nop 1
	s_nop 0
	v_sub_f32_e32 v151, v154, v188
	v_sub_f32_e32 v50, v133, v188
	v_mul_f32_e32 v133, 0x3fb8aa3b, v50
	v_sub_f32_e32 v50, v155, v188
	s_nop 0
	s_nop 0
	v_max_f32_e32 v36, v36, v255
	s_nop 1
	v_mov_b32_dpp v66, v36 row_ror:8 row_mask:0xf bank_mask:0xf
	v_mul_f32_e32 v50, 0x3fb8aa3b, v50
	v_exp_f32_e32 v34, v50
	v_sub_f32_e32 v50, v156, v188
	v_sub_f32_e32 v82, v160, v188
	s_nop 0
	v_max_f32_e32 v66, v66, v66
	v_max_f32_e32 v36, v36, v66
	s_nop 1
	s_nop 0
	s_nop 0
	v_mul_f32_e32 v50, 0x3fb8aa3b, v50
	v_mul_f32_e32 v82, 0x3fb8aa3b, v82
	v_exp_f32_e32 v35, v35
	v_exp_f32_e32 v50, v50
	s_nop 0
	s_nop 0
	v_max_f32_dpp v152, v36, v36 row_half_mirror row_mask:0xf bank_mask:0xf
	s_nop 1
	v_mov_b32_dpp v153, v152 quad_perm:[2,3,0,1] row_mask:0xf bank_mask:0xf
	v_mul_f32_e32 v36, 0x3fb8aa3b, v151
	v_exp_f32_e32 v82, v82
	v_exp_f32_e32 v66, v36
	v_cvt_pk_bf16_f32 v148, v35, v51
	s_nop 0
	v_max_f32_e32 v151, v153, v153
	v_sub_u32_e32 v153, v96, v172
	v_cmp_gt_u32_e32 vcc, s58, v153
	s_or_b64 vcc, s[2:3], vcc
	v_cvt_pk_bf16_f32 v149, v83, v67
	v_cndmask_b32_e32 v154, v204, v85, vcc
	v_add_u32_e32 v85, 32, v153
	v_cmp_gt_u32_e32 vcc, s58, v85
	s_or_b64 vcc, s[2:3], vcc
	v_add_u32_e32 v85, 64, v153
	v_cndmask_b32_e32 v155, v204, v53, vcc
	v_cmp_gt_u32_e32 vcc, s58, v85
	s_or_b64 vcc, s[2:3], vcc
	v_max3_f32 v53, v154, s59, v155
	v_cndmask_b32_e32 v156, v204, v69, vcc
	v_add_u32_e32 v69, 0x60, v153
	v_cmp_gt_u32_e32 vcc, s58, v69
	s_or_b64 vcc, s[2:3], vcc
	v_cvt_pk_bf16_f32 v36, v34, v50
	v_cndmask_b32_e32 v153, v204, v37, vcc
	v_max3_f32 v53, v53, v156, v153
	v_mov_b32_e32 v69, v53
	v_mov_b32_e32 v255, v53
	s_nop 1
	v_permlane16_swap_b32_e32 v69, v255
	s_nop 1
	v_mov_b32_dpp v69, v255 quad_perm:[0,1,2,3] row_mask:0x5 bank_mask:0xf
	v_cvt_pk_bf16_f32 v37, v82, v66
	ds_write2_b64 v187, v[148:149], v[36:37] offset0:196 offset1:230
	v_max_f32_e32 v151, v152, v151
	s_nop 1
	v_mov_b32_dpp v152, v151 quad_perm:[1,0,3,2] row_mask:0xf bank_mask:0xf
	s_nop 0
	v_max_f32_e32 v37, v69, v69
	v_max_f32_e32 v53, v53, v37
	s_nop 1
	s_nop 0
	v_sub_f32_e32 v131, v131, v206
	s_waitcnt lgkmcnt(0)
	v_max3_f32 v187, v134, v151, v152
	v_sub_f32_e32 v37, v84, v187
	v_sub_f32_e32 v52, v52, v187
	s_nop 0
	s_nop 0
	v_max_f32_dpp v69, v53, v53 row_ror:8 row_mask:0xf bank_mask:0xf
	s_nop 1
	v_mov_b32_dpp v84, v69 row_shl:4 row_mask:0xf bank_mask:0x5
	v_mov_b32_dpp v84, v69 row_shr:4 row_mask:0xf bank_mask:0xa
	v_mul_f32_e32 v52, 0x3fb8aa3b, v52
	v_exp_f32_e32 v53, v52
	v_sub_f32_e32 v52, v68, v187
	v_mul_f32_e32 v52, 0x3fb8aa3b, v52
	s_nop 0
	v_max_f32_e32 v68, v84, v84
	v_max_f32_e32 v68, v69, v68
	s_nop 1
	v_mov_b32_dpp v84, v68 quad_perm:[2,3,0,1] row_mask:0xf bank_mask:0xf
	v_exp_f32_e32 v85, v52
	v_sub_f32_e32 v52, v150, v187
	v_mul_f32_e32 v52, 0x3fb8aa3b, v52
	v_exp_f32_e32 v69, v52
	s_nop 0
	v_max_f32_e32 v52, v84, v84
	v_max_f32_e32 v52, v68, v52
	s_nop 1
	v_mov_b32_dpp v68, v52 quad_perm:[1,0,3,2] row_mask:0xf bank_mask:0xf
	v_sub_f32_e32 v36, v134, v187
	v_mul_f32_e32 v36, 0x3fb8aa3b, v36
	v_exp_f32_e32 v134, v36
	v_sub_u32_e32 v36, v96, v173
	v_cmp_gt_u32_e32 vcc, s58, v36
	s_nop 0
	v_max3_f32 v160, v135, v52, v68
	s_or_b64 vcc, s[2:3], vcc
	v_add_u32_e32 v52, 32, v36
	v_cndmask_b32_e32 v86, v204, v86, vcc
	v_cmp_gt_u32_e32 vcc, s58, v52
	s_or_b64 vcc, s[2:3], vcc
	v_add_u32_e32 v68, 64, v36
	v_cndmask_b32_e32 v54, v204, v54, vcc
	v_cmp_gt_u32_e32 vcc, s58, v68
	s_or_b64 vcc, s[2:3], vcc
	v_add_u32_e32 v36, 0x60, v36
	v_cndmask_b32_e32 v70, v204, v70, vcc
	v_cmp_gt_u32_e32 vcc, s58, v36
	s_or_b64 vcc, s[2:3], vcc
	v_max3_f32 v52, v86, s59, v54
	v_cndmask_b32_e32 v38, v204, v38, vcc
	v_max3_f32 v52, v52, v70, v38
	v_mov_b32_e32 v68, v52
	v_mov_b32_e32 v255, v52
	s_nop 1
	v_permlane16_swap_b32_e32 v68, v255
	s_nop 1
	s_nop 0
	v_sub_f32_e32 v36, v154, v160
	v_sub_u32_e32 v154, v96, v174
	v_cmp_gt_u32_e32 vcc, s58, v154
	s_or_b64 vcc, s[2:3], vcc
	s_nop 0
	s_nop 0
	v_max_f32_e32 v68, v68, v255
	s_nop 1
	s_nop 0
	v_cndmask_b32_e32 v212, v204, v87, vcc
	v_add_u32_e32 v87, 32, v154
	v_cmp_gt_u32_e32 vcc, s58, v87
	s_or_b64 vcc, s[2:3], vcc
	s_nop 0
	s_nop 0
	v_add_u32_e32 v87, 64, v154
	v_max_f32_dpp v150, v68, v68 row_ror:8 row_mask:0xf bank_mask:0xf
	v_cndmask_b32_e32 v213, v204, v55, vcc
	v_cmp_gt_u32_e32 vcc, s58, v87
	s_nop 0
	s_nop 0
	s_or_b64 vcc, s[2:3], vcc
	v_cndmask_b32_e32 v214, v204, v71, vcc
	v_add_u32_e32 v71, 0x60, v154
	v_cmp_gt_u32_e32 vcc, s58, v71
	s_or_b64 vcc, s[2:3], vcc
	v_max3_f32 v55, v212, s59, v213
	v_cndmask_b32_e32 v154, v204, v39, vcc
	s_nop 0
	s_nop 0
	v_max3_f32 v39, v55, v214, v154
	v_max_f32_dpp v152, v150, v150 row_half_mirror row_mask:0xf bank_mask:0xf
	v_mov_b32_e32 v55, v39
	v_mov_b32_e32 v255, v39
	s_nop 1
	v_permlane16_swap_b32_e32 v55, v255
	s_nop 1
	s_nop 0
	v_sub_f32_e32 v68, v153, v160
	v_mov_b32_dpp v153, v152 quad_perm:[2,3,0,1] row_mask:0xf bank_mask:0xf
	v_sub_f32_e32 v84, v155, v160
	v_mul_f32_e32 v52, 0x3fb8aa3b, v84
	s_nop 0
	s_nop 0
	v_max_f32_e32 v55, v55, v255
	s_nop 0
	v_max_f32_e32 v153, v153, v153
	v_max_f32_e32 v152, v152, v153
	s_nop 0
	s_nop 1
	v_mov_b32_dpp v153, v152 quad_perm:[1,0,3,2] row_mask:0xf bank_mask:0xf
	v_sub_f32_e32 v84, v156, v160
	v_mul_f32_e32 v37, 0x3fb8aa3b, v37
	v_mul_f32_e32 v36, 0x3fb8aa3b, v36
	s_nop 0
	s_nop 0
	s_nop 0
	v_max3_f32 v156, v136, v152, v153
	v_max_f32_dpp v71, v55, v55 row_ror:8 row_mask:0xf bank_mask:0xf
	v_sub_f32_e32 v39, v86, v156
	s_nop 1
	v_mov_b32_dpp v86, v71 row_shl:4 row_mask:0xf bank_mask:0x5
	v_mov_b32_dpp v86, v71 row_shr:4 row_mask:0xf bank_mask:0xa
	v_sub_f32_e32 v54, v54, v156
	v_mul_f32_e32 v54, 0x3fb8aa3b, v54
	v_exp_f32_e32 v55, v54
	v_sub_f32_e32 v54, v70, v156
	s_nop 0
	v_max_f32_e32 v70, v86, v86
	v_max_f32_e32 v70, v71, v70
	s_nop 1
	v_mov_b32_dpp v86, v70 quad_perm:[2,3,0,1] row_mask:0xf bank_mask:0xf
	v_sub_f32_e32 v38, v38, v156
	v_mul_f32_e32 v38, 0x3fb8aa3b, v38
	v_exp_f32_e32 v71, v38
	v_mul_f32_e32 v54, 0x3fb8aa3b, v54
	s_nop 0
	v_max_f32_e32 v38, v86, v86
	v_max_f32_e32 v38, v70, v38
	v_exp_f32_e32 v87, v54
	s_nop 1
	v_mov_b32_dpp v54, v38 quad_perm:[1,0,3,2] row_mask:0xf bank_mask:0xf
	v_sub_f32_e32 v136, v136, v156
	v_mul_f32_e32 v84, 0x3fb8aa3b, v84
	v_mul_f32_e32 v68, 0x3fb8aa3b, v68
	v_mul_f32_e32 v70, 0x3fb8aa3b, v136
	s_nop 0
	v_max3_f32 v155, v137, v38, v54
	v_sub_u32_e32 v38, v96, v175
	v_cmp_gt_u32_e32 vcc, s58, v38
	s_or_b64 vcc, s[2:3], vcc
	v_add_u32_e32 v54, 32, v38
	v_cndmask_b32_e32 v88, v204, v88, vcc
	v_cmp_gt_u32_e32 vcc, s58, v54
	v_exp_f32_e32 v37, v37
	v_exp_f32_e32 v36, v36
	v_exp_f32_e32 v52, v52
	v_exp_f32_e32 v84, v84
	v_exp_f32_e32 v68, v68
	v_exp_f32_e32 v136, v70
	s_or_b64 vcc, s[2:3], vcc
	v_add_u32_e32 v70, 64, v38
	v_cndmask_b32_e32 v56, v204, v56, vcc
	v_cmp_gt_u32_e32 vcc, s58, v70
	s_or_b64 vcc, s[2:3], vcc
	v_add_u32_e32 v38, 0x60, v38
	v_cndmask_b32_e32 v72, v204, v72, vcc
	v_cmp_gt_u32_e32 vcc, s58, v38
	v_cvt_pk_bf16_f32 v148, v37, v53
	v_cvt_pk_bf16_f32 v149, v85, v69
	v_cvt_pk_bf16_f32 v150, v36, v52
	v_cvt_pk_bf16_f32 v151, v84, v68
	s_or_b64 vcc, s[2:3], vcc
	ds_write2_b64 v215, v[148:149], v[150:151] offset0:144 offset1:178
	v_max3_f32 v54, v88, s59, v56
	v_cndmask_b32_e32 v150, v204, v40, vcc
	v_max3_f32 v38, v54, v72, v150
	v_mov_b32_e32 v40, v38
	v_mov_b32_e32 v255, v38
	s_nop 1
	v_permlane16_swap_b32_e32 v40, v255
	s_nop 1
	s_nop 0
	v_sub_f32_e32 v151, v154, v155
	v_sub_f32_e32 v54, v137, v155
	v_mul_f32_e32 v137, 0x3fb8aa3b, v54
	v_sub_f32_e32 v54, v212, v155
	s_waitcnt lgkmcnt(0)
	s_nop 0
	v_max_f32_e32 v40, v40, v255
	s_nop 1
	v_mov_b32_dpp v70, v40 row_ror:8 row_mask:0xf bank_mask:0xf
	v_mul_f32_e32 v54, 0x3fb8aa3b, v54
	v_exp_f32_e32 v38, v54
	v_sub_f32_e32 v54, v213, v155
	v_sub_f32_e32 v86, v214, v155
	s_nop 0
	v_max_f32_e32 v70, v70, v70
	v_max_f32_e32 v40, v40, v70
	s_nop 1
	s_nop 0
	s_nop 0
	v_mul_f32_e32 v39, 0x3fb8aa3b, v39
	v_mul_f32_e32 v54, 0x3fb8aa3b, v54
	v_mul_f32_e32 v86, 0x3fb8aa3b, v86
	v_exp_f32_e32 v39, v39
	s_nop 0
	s_nop 0
	v_max_f32_dpp v152, v40, v40 row_half_mirror row_mask:0xf bank_mask:0xf
	s_nop 1
	v_mov_b32_dpp v153, v152 quad_perm:[2,3,0,1] row_mask:0xf bank_mask:0xf
	v_mul_f32_e32 v40, 0x3fb8aa3b, v151
	v_exp_f32_e32 v54, v54
	v_exp_f32_e32 v86, v86
	v_exp_f32_e32 v70, v40
	s_nop 0
	v_max_f32_e32 v151, v153, v153
	v_sub_u32_e32 v153, v96, v176
	v_cmp_gt_u32_e32 vcc, s58, v153
	s_or_b64 vcc, s[2:3], vcc
	v_cvt_pk_bf16_f32 v148, v39, v55
	v_cndmask_b32_e32 v212, v204, v89, vcc
	v_add_u32_e32 v89, 32, v153
	v_cmp_gt_u32_e32 vcc, s58, v89
	s_or_b64 vcc, s[2:3], vcc
	v_add_u32_e32 v89, 64, v153
	v_cndmask_b32_e32 v213, v204, v57, vcc
	v_cmp_gt_u32_e32 vcc, s58, v89
	s_or_b64 vcc, s[2:3], vcc
	v_max3_f32 v57, v212, s59, v213
	v_cndmask_b32_e32 v214, v204, v73, vcc
	v_add_u32_e32 v73, 0x60, v153
	v_cmp_gt_u32_e32 vcc, s58, v73
	s_or_b64 vcc, s[2:3], vcc
	v_cvt_pk_bf16_f32 v149, v87, v71
	v_cndmask_b32_e32 v216, v204, v41, vcc
	v_max3_f32 v57, v57, v214, v216
	v_mov_b32_e32 v73, v57
	v_mov_b32_e32 v255, v57
	s_nop 1
	v_permlane16_swap_b32_e32 v73, v255
	s_nop 1
	v_mov_b32_dpp v73, v255 quad_perm:[0,1,2,3] row_mask:0x5 bank_mask:0xf
	v_cvt_pk_bf16_f32 v40, v38, v54
	v_cvt_pk_bf16_f32 v41, v86, v70
	ds_write2_b64 v215, v[148:149], v[40:41] offset0:212 offset1:246
	v_max_f32_e32 v151, v152, v151
	s_nop 0
	v_max_f32_e32 v41, v73, v73
	v_max_f32_e32 v57, v57, v41
	s_nop 1
	s_nop 0
	v_mov_b32_dpp v152, v151 quad_perm:[1,0,3,2] row_mask:0xf bank_mask:0xf
	v_sub_f32_e32 v135, v135, v160
	v_mul_f32_e32 v131, 0x3fb8aa3b, v131
	v_mul_f32_e32 v135, 0x3fb8aa3b, v135
	s_waitcnt lgkmcnt(0)
	s_nop 0
	s_nop 0
	v_max3_f32 v154, v138, v151, v152
	v_max_f32_dpp v73, v57, v57 row_ror:8 row_mask:0xf bank_mask:0xf
	v_sub_f32_e32 v41, v88, v154
	s_nop 1
	v_mov_b32_dpp v88, v73 row_shl:4 row_mask:0xf bank_mask:0x5
	v_mov_b32_dpp v88, v73 row_shr:4 row_mask:0xf bank_mask:0xa
	v_sub_f32_e32 v56, v56, v154
	v_mul_f32_e32 v56, 0x3fb8aa3b, v56
	v_exp_f32_e32 v57, v56
	v_sub_f32_e32 v56, v72, v154
	s_nop 0
	v_max_f32_e32 v72, v88, v88
	v_max_f32_e32 v72, v73, v72
	s_nop 1
	v_mov_b32_dpp v88, v72 quad_perm:[2,3,0,1] row_mask:0xf bank_mask:0xf
	v_mul_f32_e32 v56, 0x3fb8aa3b, v56
	v_exp_f32_e32 v89, v56
	v_sub_f32_e32 v56, v150, v154
	v_mul_f32_e32 v56, 0x3fb8aa3b, v56
	v_exp_f32_e32 v73, v56
	s_nop 0
	v_max_f32_e32 v56, v88, v88
	v_max_f32_e32 v56, v72, v56
	s_nop 1
	v_mov_b32_dpp v72, v56 quad_perm:[1,0,3,2] row_mask:0xf bank_mask:0xf
	v_sub_f32_e32 v40, v138, v154
	v_mul_f32_e32 v40, 0x3fb8aa3b, v40
	v_exp_f32_e32 v138, v40
	v_sub_u32_e32 v40, v96, v177
	v_cmp_gt_u32_e32 vcc, s58, v40
	s_nop 0
	v_max3_f32 v153, v139, v56, v72
	s_or_b64 vcc, s[2:3], vcc
	v_add_u32_e32 v56, 32, v40
	v_cndmask_b32_e32 v90, v204, v90, vcc
	v_cmp_gt_u32_e32 vcc, s58, v56
	s_or_b64 vcc, s[2:3], vcc
	v_add_u32_e32 v72, 64, v40
	v_cndmask_b32_e32 v58, v204, v58, vcc
	v_cmp_gt_u32_e32 vcc, s58, v72
	s_or_b64 vcc, s[2:3], vcc
	v_add_u32_e32 v40, 0x60, v40
	v_cndmask_b32_e32 v74, v204, v74, vcc
	v_cmp_gt_u32_e32 vcc, s58, v40
	s_or_b64 vcc, s[2:3], vcc
	v_max3_f32 v56, v90, s59, v58
	v_cndmask_b32_e32 v42, v204, v42, vcc
	v_max3_f32 v56, v56, v74, v42
	v_mov_b32_e32 v72, v56
	v_mov_b32_e32 v255, v56
	s_nop 1
	v_permlane16_swap_b32_e32 v72, v255
	s_nop 1
	s_nop 0
	v_sub_f32_e32 v88, v213, v153
	v_sub_u32_e32 v213, v96, v178
	v_cmp_gt_u32_e32 vcc, s58, v213
	s_or_b64 vcc, s[2:3], vcc
	s_nop 0
	s_nop 0
	v_max_f32_e32 v72, v72, v255
	s_nop 1
	s_nop 0
	v_mul_f32_e32 v56, 0x3fb8aa3b, v88
	v_sub_f32_e32 v88, v214, v153
	v_cndmask_b32_e32 v214, v204, v91, vcc
	v_add_u32_e32 v91, 32, v213
	v_cmp_gt_u32_e32 vcc, s58, v91
	s_nop 0
	s_nop 0
	s_or_b64 vcc, s[2:3], vcc
	v_add_u32_e32 v91, 64, v213
	v_max_f32_dpp v150, v72, v72 row_ror:8 row_mask:0xf bank_mask:0xf
	v_cndmask_b32_e32 v215, v204, v59, vcc
	v_cmp_gt_u32_e32 vcc, s58, v91
	s_nop 0
	s_nop 0
	s_or_b64 vcc, s[2:3], vcc
	v_sub_f32_e32 v72, v216, v153
	v_cndmask_b32_e32 v216, v204, v75, vcc
	v_add_u32_e32 v75, 0x60, v213
	v_cmp_gt_u32_e32 vcc, s58, v75
	s_or_b64 vcc, s[2:3], vcc
	v_max3_f32 v59, v214, s59, v215
	v_cndmask_b32_e32 v213, v204, v43, vcc
	s_nop 0
	s_nop 0
	v_max3_f32 v43, v59, v216, v213
	v_sub_f32_e32 v40, v212, v153
	v_max_f32_dpp v152, v150, v150 row_half_mirror row_mask:0xf bank_mask:0xf
	v_mov_b32_e32 v59, v43
	v_mov_b32_e32 v255, v43
	s_nop 1
	v_permlane16_swap_b32_e32 v59, v255
	s_nop 1
	s_nop 0
	v_mul_f32_e32 v41, 0x3fb8aa3b, v41
	v_mul_f32_e32 v40, 0x3fb8aa3b, v40
	v_mul_f32_e32 v88, 0x3fb8aa3b, v88
	v_mul_f32_e32 v72, 0x3fb8aa3b, v72
	v_mov_b32_dpp v212, v152 quad_perm:[2,3,0,1] row_mask:0xf bank_mask:0xf
	v_exp_f32_e32 v41, v41
	v_exp_f32_e32 v40, v40
	v_exp_f32_e32 v56, v56
	v_exp_f32_e32 v88, v88
	v_exp_f32_e32 v72, v72
	s_nop 0
	s_nop 0
	v_cvt_pk_bf16_f32 v148, v41, v57
	v_cvt_pk_bf16_f32 v149, v89, v73
	v_cvt_pk_bf16_f32 v150, v40, v56
	v_cvt_pk_bf16_f32 v151, v88, v72
	s_nop 0
	v_max_f32_e32 v212, v212, v212
	v_add_u32_e32 v75, 0x9800, v186
	v_max_f32_e32 v59, v59, v255
	v_max_f32_e32 v152, v152, v212
	ds_write2_b64 v75, v[148:149], v[150:151] offset0:160 offset1:194
	s_nop 0
	v_mov_b32_dpp v212, v152 quad_perm:[1,0,3,2] row_mask:0xf bank_mask:0xf
	v_sub_f32_e32 v139, v139, v153
	v_mul_f32_e32 v139, 0x3fb8aa3b, v139
	v_exp_f32_e32 v131, v131
	s_waitcnt lgkmcnt(0)
	s_nop 0
	s_nop 0
	v_max3_f32 v152, v140, v152, v212
	v_max_f32_dpp v75, v59, v59 row_ror:8 row_mask:0xf bank_mask:0xf
	v_sub_f32_e32 v43, v90, v152
	s_nop 1
	v_mov_b32_dpp v90, v75 row_shl:4 row_mask:0xf bank_mask:0x5
	v_mov_b32_dpp v90, v75 row_shr:4 row_mask:0xf bank_mask:0xa
	v_sub_f32_e32 v58, v58, v152
	v_mul_f32_e32 v58, 0x3fb8aa3b, v58
	v_exp_f32_e32 v59, v58
	v_sub_f32_e32 v58, v74, v152
	s_nop 0
	v_max_f32_e32 v74, v90, v90
	v_max_f32_e32 v74, v75, v74
	s_nop 1
	v_mov_b32_dpp v90, v74 quad_perm:[2,3,0,1] row_mask:0xf bank_mask:0xf
	v_sub_f32_e32 v42, v42, v152
	v_mul_f32_e32 v42, 0x3fb8aa3b, v42
	v_exp_f32_e32 v75, v42
	v_mul_f32_e32 v58, 0x3fb8aa3b, v58
	s_nop 0
	v_max_f32_e32 v42, v90, v90
	v_max_f32_e32 v42, v74, v42
	v_exp_f32_e32 v91, v58
	s_nop 1
	v_mov_b32_dpp v58, v42 quad_perm:[1,0,3,2] row_mask:0xf bank_mask:0xf
	v_sub_f32_e32 v140, v140, v152
	v_mul_f32_e32 v74, 0x3fb8aa3b, v140
	v_exp_f32_e32 v140, v74
	v_mul_f32_e32 v43, 0x3fb8aa3b, v43
	s_nop 0
	v_max3_f32 v151, v141, v42, v58
	v_sub_u32_e32 v42, v96, v179
	v_cmp_gt_u32_e32 vcc, s58, v42
	s_or_b64 vcc, s[2:3], vcc
	v_add_u32_e32 v58, 32, v42
	v_cndmask_b32_e32 v92, v204, v92, vcc
	v_cmp_gt_u32_e32 vcc, s58, v58
	s_or_b64 vcc, s[2:3], vcc
	v_add_u32_e32 v74, 64, v42
	v_cndmask_b32_e32 v60, v204, v60, vcc
	v_cmp_gt_u32_e32 vcc, s58, v74
	s_or_b64 vcc, s[2:3], vcc
	v_add_u32_e32 v42, 0x60, v42
	v_cndmask_b32_e32 v76, v204, v76, vcc
	v_cmp_gt_u32_e32 vcc, s58, v42
	s_or_b64 vcc, s[2:3], vcc
	v_max3_f32 v58, v92, s59, v60
	v_cndmask_b32_e32 v44, v204, v44, vcc
	v_max3_f32 v58, v58, v76, v44
	v_mov_b32_e32 v74, v58
	v_mov_b32_e32 v255, v58
	s_nop 1
	v_permlane16_swap_b32_e32 v74, v255
	s_nop 1
	s_nop 0
	v_sub_f32_e32 v90, v215, v151
	v_sub_u32_e32 v215, v96, v180
	v_cmp_gt_u32_e32 vcc, s58, v215
	s_or_b64 vcc, s[2:3], vcc
	s_nop 0
	s_nop 0
	v_max_f32_e32 v74, v74, v255
	s_nop 1
	s_nop 0
	v_mul_f32_e32 v58, 0x3fb8aa3b, v90
	v_sub_f32_e32 v90, v216, v151
	v_cndmask_b32_e32 v216, v204, v93, vcc
	v_add_u32_e32 v93, 32, v215
	v_cmp_gt_u32_e32 vcc, s58, v93
	s_nop 0
	s_nop 0
	s_or_b64 vcc, s[2:3], vcc
	v_add_u32_e32 v93, 64, v215
	v_max_f32_dpp v150, v74, v74 row_ror:8 row_mask:0xf bank_mask:0xf
	v_cndmask_b32_e32 v217, v204, v61, vcc
	v_cmp_gt_u32_e32 vcc, s58, v93
	s_nop 0
	s_nop 0
	s_or_b64 vcc, s[2:3], vcc
	v_cndmask_b32_e32 v218, v204, v77, vcc
	v_add_u32_e32 v77, 0x60, v215
	v_cmp_gt_u32_e32 vcc, s58, v77
	s_or_b64 vcc, s[2:3], vcc
	v_max3_f32 v61, v216, s59, v217
	v_cndmask_b32_e32 v215, v204, v45, vcc
	s_nop 0
	s_nop 0
	v_max3_f32 v45, v61, v218, v215
	v_sub_f32_e32 v42, v214, v151
	v_sub_f32_e32 v74, v213, v151
	v_max_f32_dpp v150, v150, v150 row_half_mirror row_mask:0xf bank_mask:0xf
	v_mov_b32_e32 v61, v45
	v_mov_b32_e32 v255, v45
	s_nop 1
	v_permlane16_swap_b32_e32 v61, v255
	s_nop 1
	s_nop 0
	v_mul_f32_e32 v42, 0x3fb8aa3b, v42
	v_mul_f32_e32 v90, 0x3fb8aa3b, v90
	v_mul_f32_e32 v74, 0x3fb8aa3b, v74
	v_mov_b32_dpp v214, v150 quad_perm:[2,3,0,1] row_mask:0xf bank_mask:0xf
	v_exp_f32_e32 v43, v43
	v_exp_f32_e32 v42, v42
	v_exp_f32_e32 v58, v58
	v_exp_f32_e32 v90, v90
	v_exp_f32_e32 v74, v74
	s_nop 0
	s_nop 0
	v_cvt_pk_bf16_f32 v148, v43, v59
	v_cvt_pk_bf16_f32 v149, v91, v75
	v_cvt_pk_bf16_f32 v212, v42, v58
	v_cvt_pk_bf16_f32 v213, v90, v74
	s_nop 0
	v_max_f32_e32 v214, v214, v214
	v_add_u32_e32 v77, 0x9c00, v186
	v_max_f32_e32 v61, v61, v255
	v_max_f32_e32 v150, v150, v214
	ds_write2_b64 v77, v[148:149], v[212:213] offset0:100 offset1:134
	s_nop 0
	v_mov_b32_dpp v214, v150 quad_perm:[1,0,3,2] row_mask:0xf bank_mask:0xf
	v_sub_f32_e32 v141, v141, v151
	v_mul_f32_e32 v141, 0x3fb8aa3b, v141
	v_exp_f32_e32 v133, v133
	s_waitcnt lgkmcnt(0)
	s_nop 0
	s_nop 0
	v_max3_f32 v150, v142, v150, v214
	v_max_f32_dpp v77, v61, v61 row_ror:8 row_mask:0xf bank_mask:0xf
	v_sub_f32_e32 v45, v92, v150
	s_nop 1
	v_mov_b32_dpp v92, v77 row_shl:4 row_mask:0xf bank_mask:0x5
	v_mov_b32_dpp v92, v77 row_shr:4 row_mask:0xf bank_mask:0xa
	v_sub_f32_e32 v60, v60, v150
	v_mul_f32_e32 v60, 0x3fb8aa3b, v60
	v_exp_f32_e32 v61, v60
	v_sub_f32_e32 v60, v76, v150
	s_nop 0
	v_max_f32_e32 v76, v92, v92
	v_max_f32_e32 v76, v77, v76
	s_nop 1
	v_mov_b32_dpp v92, v76 quad_perm:[2,3,0,1] row_mask:0xf bank_mask:0xf
	v_sub_f32_e32 v44, v44, v150
	v_mul_f32_e32 v44, 0x3fb8aa3b, v44
	v_exp_f32_e32 v77, v44
	v_mul_f32_e32 v60, 0x3fb8aa3b, v60
	s_nop 0
	v_max_f32_e32 v44, v92, v92
	v_max_f32_e32 v44, v76, v44
	v_exp_f32_e32 v93, v60
	s_nop 1
	v_mov_b32_dpp v60, v44 quad_perm:[1,0,3,2] row_mask:0xf bank_mask:0xf
	v_sub_f32_e32 v142, v142, v150
	v_mul_f32_e32 v76, 0x3fb8aa3b, v142
	v_exp_f32_e32 v142, v76
	v_mul_f32_e32 v45, 0x3fb8aa3b, v45
	s_nop 0
	v_max3_f32 v149, v143, v44, v60
	v_sub_u32_e32 v44, v96, v181
	v_cmp_gt_u32_e32 vcc, s58, v44
	s_or_b64 vcc, s[2:3], vcc
	v_add_u32_e32 v60, 32, v44
	v_cndmask_b32_e32 v94, v204, v94, vcc
	v_cmp_gt_u32_e32 vcc, s58, v60
	s_or_b64 vcc, s[2:3], vcc
	v_add_u32_e32 v76, 64, v44
	v_cndmask_b32_e32 v62, v204, v62, vcc
	v_cmp_gt_u32_e32 vcc, s58, v76
	s_or_b64 vcc, s[2:3], vcc
	v_add_u32_e32 v44, 0x60, v44
	v_cndmask_b32_e32 v78, v204, v78, vcc
	v_cmp_gt_u32_e32 vcc, s58, v44
	s_or_b64 vcc, s[2:3], vcc
	v_max3_f32 v60, v94, s59, v62
	v_cndmask_b32_e32 v46, v204, v46, vcc
	v_max3_f32 v60, v60, v78, v46
	v_mov_b32_e32 v76, v60
	v_mov_b32_e32 v255, v60
	s_nop 1
	v_permlane16_swap_b32_e32 v76, v255
	s_nop 1
	s_nop 0
	v_sub_u32_e32 v96, v96, v182
	v_cmp_gt_u32_e32 vcc, s58, v96
	s_or_b64 vcc, s[2:3], vcc
	v_sub_f32_e32 v92, v217, v149
	s_nop 0
	s_nop 0
	v_max_f32_e32 v76, v76, v255
	s_nop 1
	s_nop 0
	v_cndmask_b32_e32 v217, v204, v95, vcc
	v_add_u32_e32 v95, 32, v96
	v_cmp_gt_u32_e32 vcc, s58, v95
	s_or_b64 vcc, s[2:3], vcc
	s_nop 0
	s_nop 0
	v_add_u32_e32 v95, 64, v96
	v_mul_f32_e32 v60, 0x3fb8aa3b, v92
	v_sub_f32_e32 v92, v218, v149
	v_max_f32_dpp v148, v76, v76 row_ror:8 row_mask:0xf bank_mask:0xf
	v_cndmask_b32_e32 v218, v204, v63, vcc
	v_cmp_gt_u32_e32 vcc, s58, v95
	s_nop 0
	s_nop 0
	s_or_b64 vcc, s[2:3], vcc
	v_cndmask_b32_e32 v219, v204, v79, vcc
	v_add_u32_e32 v79, 0x60, v96
	v_cmp_gt_u32_e32 vcc, s58, v79
	s_or_b64 vcc, s[2:3], vcc
	v_max3_f32 v63, v217, s59, v218
	v_cndmask_b32_e32 v96, v204, v47, vcc
	s_nop 0
	s_nop 0
	v_max3_f32 v47, v63, v219, v96
	v_sub_f32_e32 v44, v216, v149
	v_sub_f32_e32 v76, v215, v149
	v_max_f32_dpp v148, v148, v148 row_half_mirror row_mask:0xf bank_mask:0xf
	v_mov_b32_e32 v63, v47
	v_mov_b32_e32 v255, v47
	s_nop 1
	v_permlane16_swap_b32_e32 v63, v255
	s_nop 1
	s_nop 0
	v_mul_f32_e32 v44, 0x3fb8aa3b, v44
	v_mul_f32_e32 v92, 0x3fb8aa3b, v92
	v_mul_f32_e32 v76, 0x3fb8aa3b, v76
	v_mov_b32_dpp v216, v148 quad_perm:[2,3,0,1] row_mask:0xf bank_mask:0xf
	v_exp_f32_e32 v45, v45
	v_exp_f32_e32 v44, v44
	v_exp_f32_e32 v60, v60
	v_exp_f32_e32 v92, v92
	v_exp_f32_e32 v76, v76
	s_nop 0
	s_nop 0
	v_cvt_pk_bf16_f32 v212, v45, v61
	v_cvt_pk_bf16_f32 v213, v93, v77
	v_cvt_pk_bf16_f32 v214, v44, v60
	v_cvt_pk_bf16_f32 v215, v92, v76
	s_nop 0
	v_max_f32_e32 v216, v216, v216
	v_add_u32_e32 v79, 0xa000, v186
	v_max_f32_e32 v63, v63, v255
	v_max_f32_e32 v148, v148, v216
	ds_write2_b64 v79, v[212:213], v[214:215] offset0:176 offset1:210
	s_nop 0
	v_mov_b32_dpp v216, v148 quad_perm:[1,0,3,2] row_mask:0xf bank_mask:0xf
	v_sub_f32_e32 v143, v143, v149
	v_mul_f32_e32 v143, 0x3fb8aa3b, v143
	v_exp_f32_e32 v135, v135
	s_waitcnt lgkmcnt(0)
	s_nop 0
	s_nop 0
	v_max3_f32 v148, v144, v148, v216
	v_max_f32_dpp v79, v63, v63 row_ror:8 row_mask:0xf bank_mask:0xf
	v_sub_f32_e32 v47, v94, v148
	s_nop 1
	v_mov_b32_dpp v94, v79 row_shl:4 row_mask:0xf bank_mask:0x5
	v_mov_b32_dpp v94, v79 row_shr:4 row_mask:0xf bank_mask:0xa
	v_sub_f32_e32 v62, v62, v148
	v_mul_f32_e32 v62, 0x3fb8aa3b, v62
	v_exp_f32_e32 v63, v62
	v_sub_f32_e32 v62, v78, v148
	s_nop 0
	v_max_f32_e32 v78, v94, v94
	v_max_f32_e32 v78, v79, v78
	s_nop 1
	v_mov_b32_dpp v94, v78 quad_perm:[2,3,0,1] row_mask:0xf bank_mask:0xf
	v_sub_f32_e32 v46, v46, v148
	v_mul_f32_e32 v46, 0x3fb8aa3b, v46
	v_exp_f32_e32 v79, v46
	v_mul_f32_e32 v62, 0x3fb8aa3b, v62
	s_nop 0
	v_max_f32_e32 v46, v94, v94
	v_max_f32_e32 v46, v78, v46
	v_exp_f32_e32 v95, v62
	s_nop 1
	v_mov_b32_dpp v62, v46 quad_perm:[1,0,3,2] row_mask:0xf bank_mask:0xf
	v_sub_f32_e32 v144, v144, v148
	v_mul_f32_e32 v78, 0x3fb8aa3b, v144
	v_exp_f32_e32 v144, v78
	v_mul_f32_e32 v47, 0x3fb8aa3b, v47
	s_nop 0
	v_max3_f32 v147, v145, v46, v62
	v_sub_f32_e32 v78, v219, v147
	v_mul_f32_e32 v78, 0x3fb8aa3b, v78
	v_sub_f32_e32 v46, v217, v147
	v_sub_f32_e32 v62, v218, v147
	v_exp_f32_e32 v94, v78
	v_sub_f32_e32 v78, v96, v147
	v_sub_f32_e32 v145, v145, v147
	v_mul_f32_e32 v46, 0x3fb8aa3b, v46
	v_mul_f32_e32 v62, 0x3fb8aa3b, v62
	v_mul_f32_e32 v78, 0x3fb8aa3b, v78
	v_exp_f32_e32 v47, v47
	v_exp_f32_e32 v46, v46
	v_exp_f32_e32 v62, v62
	v_exp_f32_e32 v78, v78
	v_mul_f32_e32 v96, 0x3fb8aa3b, v145
	v_exp_f32_e32 v137, v137
	v_exp_f32_e32 v139, v139
	v_exp_f32_e32 v141, v141
	v_exp_f32_e32 v143, v143
	v_exp_f32_e32 v145, v96
	v_cvt_pk_bf16_f32 v208, v47, v63
	v_cvt_pk_bf16_f32 v209, v95, v79
	v_cvt_pk_bf16_f32 v210, v46, v62
	v_cvt_pk_bf16_f32 v211, v94, v78
	v_add_u32_e32 v96, 0xa400, v186
	ds_write2_b64 v96, v[208:209], v[210:211] offset0:116 offset1:150
	v_pk_mul_f32 v[14:15], v[14:15], v[144:145]
	v_pk_mul_f32 v[12:13], v[12:13], v[142:143]
	v_pk_mul_f32 v[10:11], v[10:11], v[140:141]
	v_pk_mul_f32 v[8:9], v[8:9], v[138:139]
	v_pk_mul_f32 v[6:7], v[6:7], v[136:137]
	v_pk_mul_f32 v[4:5], v[4:5], v[134:135]
	v_pk_mul_f32 v[2:3], v[2:3], v[132:133]
	v_pk_mul_f32 v[0:1], v[0:1], v[130:131]
	v_pk_mul_f32 v[30:31], v[30:31], v[144:145]
	v_pk_mul_f32 v[28:29], v[28:29], v[142:143]
	v_pk_mul_f32 v[26:27], v[26:27], v[140:141]
	v_pk_mul_f32 v[24:25], v[24:25], v[138:139]
	v_pk_mul_f32 v[22:23], v[22:23], v[136:137]
	v_pk_mul_f32 v[20:21], v[20:21], v[134:135]
	v_pk_mul_f32 v[18:19], v[18:19], v[132:133]
	v_pk_mul_f32 v[16:17], v[16:17], v[130:131]
	s_mov_b32 s2, -16
	v_mov_b32_e32 v96, v185
	v_mov_b32_e32 v208, v184

.Latt_nm:
	s_nop 7
	s_nop 7
	s_nop 7
	s_add_i32 s6, s53, s49
	v_mbcnt_hi_u32_b32 v148, -1, v195
	v_lshl_add_u32 v96, s6, 7, v183
	v_and_b32_e32 v147, 64, v148
	v_add_u32_e32 v149, 64, v147
	v_xor_b32_e32 v147, 16, v148
	v_cmp_lt_i32_e32 vcc, v147, v149
	v_max3_f32 v150, v80, s59, v48
	v_max3_f32 v150, v150, v64, v32
	v_mov_b32_e32 v151, v150
	v_mov_b32_e32 v255, v150
	s_nop 1
	v_permlane16_swap_b32_e32 v151, v255
	s_nop 1
	s_nop 0
	v_add_u32_e32 v187, 0x8800, v186
	v_add_u32_e32 v215, 0x9000, v186
	s_nop 0
	s_nop 0
	v_max_f32_e32 v150, v151, v255
	v_xor_b32_e32 v151, 8, v148
	v_cmp_lt_i32_e32 vcc, v151, v149
	s_nop 1
	v_cndmask_b32_e32 v151, v148, v151, vcc
	s_nop 1
	s_nop 0
	s_nop 0
	s_nop 0
	v_max_f32_dpp v150, v150, v150 row_ror:8 row_mask:0xf bank_mask:0xf
	v_xor_b32_e32 v151, 4, v148
	v_cmp_lt_i32_e32 vcc, v151, v149
	s_nop 1
	v_cndmask_b32_e32 v151, v148, v151, vcc
	s_nop 1
	v_mov_b32_dpp v151, v150 row_shl:4 row_mask:0xf bank_mask:0x5
	s_nop 1
	v_mov_b32_dpp v151, v150 row_shr:4 row_mask:0xf bank_mask:0xa
	s_nop 0
	s_nop 0
	v_max_f32_e32 v150, v150, v151
	v_xor_b32_e32 v151, 2, v148
	v_cmp_lt_i32_e32 vcc, v151, v149
	s_nop 1
	v_cndmask_b32_e32 v151, v148, v151, vcc
	s_nop 1
	s_nop 0
	s_nop 0
	s_nop 0
	v_max_f32_dpp v150, v150, v150 quad_perm:[2,3,0,1] row_mask:0xf bank_mask:0xf
	v_xor_b32_e32 v151, 1, v148
	v_cmp_lt_i32_e32 vcc, v151, v149
	v_sub_u32_e32 v149, v96, v161
	s_nop 0
	v_cndmask_b32_e32 v148, v148, v151, vcc
	v_mov_b32_e32 v151, v81
	v_mov_b32_e32 v152, v49
	v_max3_f32 v49, v151, s59, v152
	v_mov_b32_e32 v153, v65
	v_add_u32_e32 v65, 0x60, v149
	v_mov_b32_dpp v148, v150 quad_perm:[1,0,3,2] row_mask:0xf bank_mask:0xf
	v_mov_b32_e32 v154, v33
	v_max3_f32 v33, v49, v153, v154
	v_mov_b32_e32 v49, v33
	v_mov_b32_e32 v255, v33
	s_nop 1
	v_permlane16_swap_b32_e32 v49, v255
	s_nop 1
	s_nop 0
	s_nop 0
	v_max3_f32 v207, v130, v150, v148
	v_sub_f32_e32 v48, v48, v207
	v_mul_f32_e32 v48, 0x3fb8aa3b, v48
	s_nop 0
	s_nop 0
	v_max_f32_e32 v49, v49, v255
	s_nop 1
	s_nop 0
	v_sub_f32_e32 v33, v80, v207
	v_sub_f32_e32 v32, v32, v207
	v_mul_f32_e32 v32, 0x3fb8aa3b, v32
	v_sub_f32_e32 v130, v130, v207
	s_nop 0
	s_nop 0
	v_max_f32_dpp v65, v49, v49 row_ror:8 row_mask:0xf bank_mask:0xf
	s_nop 1
	v_mov_b32_dpp v80, v65 row_shl:4 row_mask:0xf bank_mask:0x5
	s_nop 1
	v_mov_b32_dpp v80, v65 row_shr:4 row_mask:0xf bank_mask:0xa
	v_exp_f32_e32 v49, v48
	v_sub_f32_e32 v48, v64, v207
	v_mul_f32_e32 v48, 0x3fb8aa3b, v48
	v_exp_f32_e32 v81, v48
	s_nop 0
	v_max_f32_e32 v64, v80, v80
	v_max_f32_e32 v64, v65, v64
	s_nop 1
	v_mov_b32_dpp v80, v64 quad_perm:[2,3,0,1] row_mask:0xf bank_mask:0xf
	v_exp_f32_e32 v65, v32
	v_mul_f32_e32 v33, 0x3fb8aa3b, v33
	v_exp_f32_e32 v33, v33
	s_nop 0
	v_max_f32_e32 v32, v80, v80
	v_max_f32_e32 v32, v64, v32
	s_nop 1
	v_mov_b32_dpp v48, v32 quad_perm:[1,0,3,2] row_mask:0xf bank_mask:0xf
	v_mul_f32_e32 v64, 0x3fb8aa3b, v130
	v_exp_f32_e32 v130, v64
	v_cvt_pk_bf16_f32 v148, v33, v49
	v_cvt_pk_bf16_f32 v149, v81, v65
	s_nop 0
	v_max3_f32 v206, v131, v32, v48
	v_max3_f32 v48, v82, s59, v50
	v_max3_f32 v48, v48, v66, v34
	v_mov_b32_e32 v64, v48
	v_mov_b32_e32 v255, v48
	s_nop 1
	v_permlane16_swap_b32_e32 v64, v255
	s_nop 1
	s_nop 0
	v_sub_f32_e32 v32, v151, v206
	v_sub_f32_e32 v80, v152, v206
	v_mul_f32_e32 v32, 0x3fb8aa3b, v32
	v_exp_f32_e32 v32, v32
	s_nop 0
	s_nop 0
	v_max_f32_e32 v64, v64, v255
	s_nop 1
	s_nop 0
	v_mul_f32_e32 v48, 0x3fb8aa3b, v80
	v_sub_f32_e32 v80, v153, v206
	v_mul_f32_e32 v80, 0x3fb8aa3b, v80
	v_exp_f32_e32 v48, v48
	s_nop 0
	s_nop 0
	v_max_f32_dpp v150, v64, v64 row_ror:8 row_mask:0xf bank_mask:0xf
	v_sub_f32_e32 v64, v154, v206
	v_sub_u32_e32 v154, v96, v170
	v_mov_b32_dpp v151, v150 row_shl:4 row_mask:0xf bank_mask:0x5
	s_nop 1
	v_mov_b32_dpp v151, v150 row_shr:4 row_mask:0xf bank_mask:0xa
	v_mov_b32_e32 v155, v83
	v_mov_b32_e32 v156, v51
	v_max3_f32 v51, v155, s59, v156
	v_mov_b32_e32 v160, v67
	v_add_u32_e32 v67, 0x60, v154
	s_nop 0
	v_max_f32_e32 v151, v151, v151
	v_mov_b32_e32 v154, v35
	v_max3_f32 v35, v51, v160, v154
	v_max_f32_e32 v152, v150, v151
	v_mov_b32_e32 v51, v35
	v_mov_b32_e32 v255, v35
	s_nop 1
	v_permlane16_swap_b32_e32 v51, v255
	s_nop 1
	s_nop 0
	s_nop 1
	v_mov_b32_dpp v153, v152 quad_perm:[2,3,0,1] row_mask:0xf bank_mask:0xf
	v_mul_f32_e32 v64, 0x3fb8aa3b, v64
	v_exp_f32_e32 v80, v80
	v_exp_f32_e32 v64, v64
	s_nop 0
	s_nop 0
	s_nop 0
	v_max_f32_e32 v153, v153, v153
	v_max_f32_e32 v51, v51, v255
	v_max_f32_e32 v152, v152, v153
	s_nop 1
	s_nop 0
	s_nop 1
	v_mov_b32_dpp v153, v152 quad_perm:[1,0,3,2] row_mask:0xf bank_mask:0xf
	v_cvt_pk_bf16_f32 v150, v32, v48
	v_cvt_pk_bf16_f32 v151, v80, v64
	ds_write2_b64 v187, v[148:149], v[150:151] offset0:128 offset1:162
	s_nop 0
	s_nop 0
	s_nop 0
	v_max3_f32 v189, v132, v152, v153
	v_max_f32_dpp v67, v51, v51 row_ror:8 row_mask:0xf bank_mask:0xf
	v_sub_f32_e32 v35, v82, v189
	s_nop 1
	v_mov_b32_dpp v82, v67 row_shl:4 row_mask:0xf bank_mask:0x5
	s_nop 1
	v_mov_b32_dpp v82, v67 row_shr:4 row_mask:0xf bank_mask:0xa
	v_sub_f32_e32 v50, v50, v189
	v_mul_f32_e32 v50, 0x3fb8aa3b, v50
	v_exp_f32_e32 v51, v50
	v_sub_f32_e32 v50, v66, v189
	s_waitcnt lgkmcnt(0)
	v_max_f32_e32 v66, v82, v82
	v_max_f32_e32 v66, v67, v66
	s_nop 1
	v_mov_b32_dpp v82, v66 quad_perm:[2,3,0,1] row_mask:0xf bank_mask:0xf
	v_sub_f32_e32 v34, v34, v189
	v_mul_f32_e32 v34, 0x3fb8aa3b, v34
	v_exp_f32_e32 v67, v34
	v_mul_f32_e32 v50, 0x3fb8aa3b, v50
	s_nop 0
	v_max_f32_e32 v34, v82, v82
	v_max_f32_e32 v34, v66, v34
	v_exp_f32_e32 v83, v50
	s_nop 1
	v_mov_b32_dpp v50, v34 quad_perm:[1,0,3,2] row_mask:0xf bank_mask:0xf
	v_sub_f32_e32 v132, v132, v189
	v_mul_f32_e32 v66, 0x3fb8aa3b, v132
	v_exp_f32_e32 v132, v66
	v_mul_f32_e32 v35, 0x3fb8aa3b, v35
	s_nop 0
	v_max3_f32 v188, v133, v34, v50
	v_sub_u32_e32 v34, v96, v171
	v_add_u32_e32 v66, 64, v34
	v_max3_f32 v50, v84, s59, v52
	v_mov_b32_e32 v150, v36
	v_max3_f32 v34, v50, v68, v150
	v_mov_b32_e32 v36, v34
	v_mov_b32_e32 v255, v34
	s_nop 1
	v_permlane16_swap_b32_e32 v36, v255
	s_nop 1
	s_nop 0
	v_sub_f32_e32 v151, v154, v188
	v_sub_f32_e32 v50, v133, v188
	v_mul_f32_e32 v133, 0x3fb8aa3b, v50
	v_sub_f32_e32 v50, v155, v188
	s_nop 0
	s_nop 0
	v_max_f32_e32 v36, v36, v255
	s_nop 1
	v_mov_b32_dpp v66, v36 row_ror:8 row_mask:0xf bank_mask:0xf
	v_mul_f32_e32 v50, 0x3fb8aa3b, v50
	v_exp_f32_e32 v34, v50
	v_sub_f32_e32 v50, v156, v188
	v_sub_f32_e32 v82, v160, v188
	s_nop 0
	v_max_f32_e32 v66, v66, v66
	v_max_f32_e32 v36, v36, v66
	s_nop 1
	v_mov_b32_dpp v66, v36 row_shl:4 row_mask:0xf bank_mask:0x5
	s_nop 1
	v_mov_b32_dpp v66, v36 row_shr:4 row_mask:0xf bank_mask:0xa
	v_mul_f32_e32 v50, 0x3fb8aa3b, v50
	v_mul_f32_e32 v82, 0x3fb8aa3b, v82
	v_exp_f32_e32 v35, v35
	v_exp_f32_e32 v50, v50
	s_nop 0
	v_max_f32_e32 v66, v66, v66
	v_max_f32_e32 v152, v36, v66
	s_nop 1
	v_mov_b32_dpp v153, v152 quad_perm:[2,3,0,1] row_mask:0xf bank_mask:0xf
	v_mul_f32_e32 v36, 0x3fb8aa3b, v151
	v_exp_f32_e32 v82, v82
	v_exp_f32_e32 v66, v36
	v_cvt_pk_bf16_f32 v148, v35, v51
	s_nop 0
	v_max_f32_e32 v151, v153, v153
	v_cvt_pk_bf16_f32 v149, v83, v67
	v_mov_b32_e32 v154, v85
	v_mov_b32_e32 v155, v53
	v_max3_f32 v53, v154, s59, v155
	v_mov_b32_e32 v156, v69
	v_cvt_pk_bf16_f32 v36, v34, v50
	v_mov_b32_e32 v153, v37
	v_max3_f32 v53, v53, v156, v153
	v_mov_b32_e32 v69, v53
	v_mov_b32_e32 v255, v53
	s_nop 1
	v_permlane16_swap_b32_e32 v69, v255
	s_nop 1
	v_mov_b32_dpp v69, v255 quad_perm:[0,1,2,3] row_mask:0x5 bank_mask:0xf
	v_cvt_pk_bf16_f32 v37, v82, v66
	ds_write2_b64 v187, v[148:149], v[36:37] offset0:196 offset1:230
	v_max_f32_e32 v151, v152, v151
	s_nop 1
	v_mov_b32_dpp v152, v151 quad_perm:[1,0,3,2] row_mask:0xf bank_mask:0xf
	s_nop 0
	v_max_f32_e32 v37, v69, v69
	v_max_f32_e32 v53, v53, v37
	s_nop 1
	s_nop 0
	v_sub_f32_e32 v131, v131, v206
	s_waitcnt lgkmcnt(0)
	v_max3_f32 v187, v134, v151, v152
	v_sub_f32_e32 v37, v84, v187
	v_sub_f32_e32 v52, v52, v187
	s_nop 0
	s_nop 0
	v_max_f32_dpp v69, v53, v53 row_ror:8 row_mask:0xf bank_mask:0xf
	s_nop 1
	v_mov_b32_dpp v84, v69 row_shl:4 row_mask:0xf bank_mask:0x5
	s_nop 1
	v_mov_b32_dpp v84, v69 row_shr:4 row_mask:0xf bank_mask:0xa
	v_mul_f32_e32 v52, 0x3fb8aa3b, v52
	v_exp_f32_e32 v53, v52
	v_sub_f32_e32 v52, v68, v187
	v_mul_f32_e32 v52, 0x3fb8aa3b, v52
	s_nop 0
	v_max_f32_e32 v68, v84, v84
	v_max_f32_e32 v68, v69, v68
	s_nop 1
	v_mov_b32_dpp v84, v68 quad_perm:[2,3,0,1] row_mask:0xf bank_mask:0xf
	v_exp_f32_e32 v85, v52
	v_sub_f32_e32 v52, v150, v187
	v_mul_f32_e32 v52, 0x3fb8aa3b, v52
	v_exp_f32_e32 v69, v52
	s_nop 0
	v_max_f32_e32 v52, v84, v84
	v_max_f32_e32 v52, v68, v52
	s_nop 1
	v_mov_b32_dpp v68, v52 quad_perm:[1,0,3,2] row_mask:0xf bank_mask:0xf
	v_sub_f32_e32 v36, v134, v187
	v_mul_f32_e32 v36, 0x3fb8aa3b, v36
	v_exp_f32_e32 v134, v36
	s_nop 0
	v_max3_f32 v160, v135, v52, v68
	v_max3_f32 v52, v86, s59, v54
	v_max3_f32 v52, v52, v70, v38
	v_mov_b32_e32 v68, v52
	v_mov_b32_e32 v255, v52
	s_nop 1
	v_permlane16_swap_b32_e32 v68, v255
	s_nop 1
	s_nop 0
	v_sub_f32_e32 v36, v154, v160
	v_sub_u32_e32 v154, v96, v174
	s_nop 0
	s_nop 0
	v_max_f32_e32 v68, v68, v255
	s_nop 1
	s_nop 0
	v_mov_b32_e32 v212, v87
	s_nop 0
	s_nop 0
	v_max_f32_dpp v150, v68, v68 row_ror:8 row_mask:0xf bank_mask:0xf
	v_mov_b32_e32 v213, v55
	s_nop 0
	v_mov_b32_dpp v151, v150 row_shl:4 row_mask:0xf bank_mask:0x5
	s_nop 1
	v_mov_b32_dpp v151, v150 row_shr:4 row_mask:0xf bank_mask:0xa
	v_mov_b32_e32 v214, v71
	v_add_u32_e32 v71, 0x60, v154
	v_max3_f32 v55, v212, s59, v213
	v_mov_b32_e32 v154, v39
	s_nop 0
	v_max_f32_e32 v151, v151, v151
	v_max3_f32 v39, v55, v214, v154
	v_max_f32_e32 v152, v150, v151
	v_mov_b32_e32 v55, v39
	v_mov_b32_e32 v255, v39
	s_nop 1
	v_permlane16_swap_b32_e32 v55, v255
	s_nop 1
	s_nop 0
	v_sub_f32_e32 v68, v153, v160
	v_mov_b32_dpp v153, v152 quad_perm:[2,3,0,1] row_mask:0xf bank_mask:0xf
	v_sub_f32_e32 v84, v155, v160
	v_mul_f32_e32 v52, 0x3fb8aa3b, v84
	s_nop 0
	s_nop 0
	v_max_f32_e32 v55, v55, v255
	s_nop 0
	v_max_f32_e32 v153, v153, v153
	v_max_f32_e32 v152, v152, v153
	s_nop 0
	s_nop 1
	v_mov_b32_dpp v153, v152 quad_perm:[1,0,3,2] row_mask:0xf bank_mask:0xf
	v_sub_f32_e32 v84, v156, v160
	v_mul_f32_e32 v37, 0x3fb8aa3b, v37
	v_mul_f32_e32 v36, 0x3fb8aa3b, v36
	s_nop 0
	s_nop 0
	s_nop 0
	v_max3_f32 v156, v136, v152, v153
	v_max_f32_dpp v71, v55, v55 row_ror:8 row_mask:0xf bank_mask:0xf
	v_sub_f32_e32 v39, v86, v156
	s_nop 1
	v_mov_b32_dpp v86, v71 row_shl:4 row_mask:0xf bank_mask:0x5
	s_nop 1
	v_mov_b32_dpp v86, v71 row_shr:4 row_mask:0xf bank_mask:0xa
	v_sub_f32_e32 v54, v54, v156
	v_mul_f32_e32 v54, 0x3fb8aa3b, v54
	v_exp_f32_e32 v55, v54
	v_sub_f32_e32 v54, v70, v156
	s_nop 0
	v_max_f32_e32 v70, v86, v86
	v_max_f32_e32 v70, v71, v70
	s_nop 1
	v_mov_b32_dpp v86, v70 quad_perm:[2,3,0,1] row_mask:0xf bank_mask:0xf
	v_sub_f32_e32 v38, v38, v156
	v_mul_f32_e32 v38, 0x3fb8aa3b, v38
	v_exp_f32_e32 v71, v38
	v_mul_f32_e32 v54, 0x3fb8aa3b, v54
	s_nop 0
	v_max_f32_e32 v38, v86, v86
	v_max_f32_e32 v38, v70, v38
	v_exp_f32_e32 v87, v54
	s_nop 1
	v_mov_b32_dpp v54, v38 quad_perm:[1,0,3,2] row_mask:0xf bank_mask:0xf
	v_sub_f32_e32 v136, v136, v156
	v_mul_f32_e32 v84, 0x3fb8aa3b, v84
	v_mul_f32_e32 v68, 0x3fb8aa3b, v68
	v_mul_f32_e32 v70, 0x3fb8aa3b, v136
	s_nop 0
	v_max3_f32 v155, v137, v38, v54
	v_sub_u32_e32 v38, v96, v175
	v_exp_f32_e32 v37, v37
	v_exp_f32_e32 v36, v36
	v_exp_f32_e32 v52, v52
	v_exp_f32_e32 v84, v84
	v_exp_f32_e32 v68, v68
	v_exp_f32_e32 v136, v70
	v_add_u32_e32 v70, 64, v38
	v_cvt_pk_bf16_f32 v148, v37, v53
	v_cvt_pk_bf16_f32 v149, v85, v69
	v_cvt_pk_bf16_f32 v150, v36, v52
	v_cvt_pk_bf16_f32 v151, v84, v68
	ds_write2_b64 v215, v[148:149], v[150:151] offset0:144 offset1:178
	v_max3_f32 v54, v88, s59, v56
	v_mov_b32_e32 v150, v40
	v_max3_f32 v38, v54, v72, v150
	v_mov_b32_e32 v40, v38
	v_mov_b32_e32 v255, v38
	s_nop 1
	v_permlane16_swap_b32_e32 v40, v255
	s_nop 1
	s_nop 0
	v_sub_f32_e32 v151, v154, v155
	v_sub_f32_e32 v54, v137, v155
	v_mul_f32_e32 v137, 0x3fb8aa3b, v54
	v_sub_f32_e32 v54, v212, v155
	s_waitcnt lgkmcnt(0)
	s_nop 0
	v_max_f32_e32 v40, v40, v255
	s_nop 1
	v_mov_b32_dpp v70, v40 row_ror:8 row_mask:0xf bank_mask:0xf
	v_mul_f32_e32 v54, 0x3fb8aa3b, v54
	v_exp_f32_e32 v38, v54
	v_sub_f32_e32 v54, v213, v155
	v_sub_f32_e32 v86, v214, v155
	s_nop 0
	v_max_f32_e32 v70, v70, v70
	v_max_f32_e32 v40, v40, v70
	s_nop 1
	v_mov_b32_dpp v70, v40 row_shl:4 row_mask:0xf bank_mask:0x5
	s_nop 1
	v_mov_b32_dpp v70, v40 row_shr:4 row_mask:0xf bank_mask:0xa
	v_mul_f32_e32 v39, 0x3fb8aa3b, v39
	v_mul_f32_e32 v54, 0x3fb8aa3b, v54
	v_mul_f32_e32 v86, 0x3fb8aa3b, v86
	v_exp_f32_e32 v39, v39
	s_nop 0
	v_max_f32_e32 v70, v70, v70
	v_max_f32_e32 v152, v40, v70
	s_nop 1
	v_mov_b32_dpp v153, v152 quad_perm:[2,3,0,1] row_mask:0xf bank_mask:0xf
	v_mul_f32_e32 v40, 0x3fb8aa3b, v151
	v_exp_f32_e32 v54, v54
	v_exp_f32_e32 v86, v86
	v_exp_f32_e32 v70, v40
	s_nop 0
	v_max_f32_e32 v151, v153, v153
	v_cvt_pk_bf16_f32 v148, v39, v55
	v_mov_b32_e32 v212, v89
	v_mov_b32_e32 v213, v57
	v_max3_f32 v57, v212, s59, v213
	v_mov_b32_e32 v214, v73
	v_cvt_pk_bf16_f32 v149, v87, v71
	v_mov_b32_e32 v216, v41
	v_max3_f32 v57, v57, v214, v216
	v_mov_b32_e32 v73, v57
	v_mov_b32_e32 v255, v57
	s_nop 1
	v_permlane16_swap_b32_e32 v73, v255
	s_nop 1
	v_mov_b32_dpp v73, v255 quad_perm:[0,1,2,3] row_mask:0x5 bank_mask:0xf
	v_cvt_pk_bf16_f32 v40, v38, v54
	v_cvt_pk_bf16_f32 v41, v86, v70
	ds_write2_b64 v215, v[148:149], v[40:41] offset0:212 offset1:246
	v_max_f32_e32 v151, v152, v151
	s_nop 0
	v_max_f32_e32 v41, v73, v73
	v_max_f32_e32 v57, v57, v41
	s_nop 1
	s_nop 0
	v_mov_b32_dpp v152, v151 quad_perm:[1,0,3,2] row_mask:0xf bank_mask:0xf
	v_sub_f32_e32 v135, v135, v160
	v_mul_f32_e32 v131, 0x3fb8aa3b, v131
	v_mul_f32_e32 v135, 0x3fb8aa3b, v135
	s_waitcnt lgkmcnt(0)
	s_nop 0
	s_nop 0
	v_max3_f32 v154, v138, v151, v152
	v_max_f32_dpp v73, v57, v57 row_ror:8 row_mask:0xf bank_mask:0xf
	v_sub_f32_e32 v41, v88, v154
	s_nop 1
	v_mov_b32_dpp v88, v73 row_shl:4 row_mask:0xf bank_mask:0x5
	s_nop 1
	v_mov_b32_dpp v88, v73 row_shr:4 row_mask:0xf bank_mask:0xa
	v_sub_f32_e32 v56, v56, v154
	v_mul_f32_e32 v56, 0x3fb8aa3b, v56
	v_exp_f32_e32 v57, v56
	v_sub_f32_e32 v56, v72, v154
	s_nop 0
	v_max_f32_e32 v72, v88, v88
	v_max_f32_e32 v72, v73, v72
	s_nop 1
	v_mov_b32_dpp v88, v72 quad_perm:[2,3,0,1] row_mask:0xf bank_mask:0xf
	v_mul_f32_e32 v56, 0x3fb8aa3b, v56
	v_exp_f32_e32 v89, v56
	v_sub_f32_e32 v56, v150, v154
	v_mul_f32_e32 v56, 0x3fb8aa3b, v56
	v_exp_f32_e32 v73, v56
	s_nop 0
	v_max_f32_e32 v56, v88, v88
	v_max_f32_e32 v56, v72, v56
	s_nop 1
	v_mov_b32_dpp v72, v56 quad_perm:[1,0,3,2] row_mask:0xf bank_mask:0xf
	v_sub_f32_e32 v40, v138, v154
	v_mul_f32_e32 v40, 0x3fb8aa3b, v40
	v_exp_f32_e32 v138, v40
	s_nop 0
	v_max3_f32 v153, v139, v56, v72
	v_max3_f32 v56, v90, s59, v58
	v_max3_f32 v56, v56, v74, v42
	v_mov_b32_e32 v72, v56
	v_mov_b32_e32 v255, v56
	s_nop 1
	v_permlane16_swap_b32_e32 v72, v255
	s_nop 1
	s_nop 0
	v_sub_f32_e32 v88, v213, v153
	s_nop 0
	s_nop 0
	v_max_f32_e32 v72, v72, v255
	s_nop 1
	s_nop 0
	v_mul_f32_e32 v56, 0x3fb8aa3b, v88
	v_sub_f32_e32 v88, v214, v153
	v_mov_b32_e32 v214, v91
	s_nop 0
	s_nop 0
	v_max_f32_dpp v150, v72, v72 row_ror:8 row_mask:0xf bank_mask:0xf
	v_mov_b32_e32 v215, v59
	s_nop 0
	v_mov_b32_dpp v151, v150 row_shl:4 row_mask:0xf bank_mask:0x5
	s_nop 1
	v_mov_b32_dpp v151, v150 row_shr:4 row_mask:0xf bank_mask:0xa
	v_sub_f32_e32 v72, v216, v153
	v_mov_b32_e32 v216, v75
	v_max3_f32 v59, v214, s59, v215
	v_mov_b32_e32 v213, v43
	s_nop 0
	v_max_f32_e32 v151, v151, v151
	v_max3_f32 v43, v59, v216, v213
	v_sub_f32_e32 v40, v212, v153
	v_max_f32_e32 v152, v150, v151
	v_mov_b32_e32 v59, v43
	v_mov_b32_e32 v255, v43
	s_nop 1
	v_permlane16_swap_b32_e32 v59, v255
	s_nop 1
	s_nop 0
	v_mul_f32_e32 v41, 0x3fb8aa3b, v41
	v_mul_f32_e32 v40, 0x3fb8aa3b, v40
	v_mul_f32_e32 v88, 0x3fb8aa3b, v88
	v_mul_f32_e32 v72, 0x3fb8aa3b, v72
	v_mov_b32_dpp v212, v152 quad_perm:[2,3,0,1] row_mask:0xf bank_mask:0xf
	v_exp_f32_e32 v41, v41
	v_exp_f32_e32 v40, v40
	v_exp_f32_e32 v56, v56
	v_exp_f32_e32 v88, v88
	v_exp_f32_e32 v72, v72
	s_nop 0
	s_nop 0
	v_cvt_pk_bf16_f32 v148, v41, v57
	v_cvt_pk_bf16_f32 v149, v89, v73
	v_cvt_pk_bf16_f32 v150, v40, v56
	v_cvt_pk_bf16_f32 v151, v88, v72
	s_nop 0
	v_max_f32_e32 v212, v212, v212
	v_add_u32_e32 v75, 0x9800, v186
	v_max_f32_e32 v59, v59, v255
	v_max_f32_e32 v152, v152, v212
	ds_write2_b64 v75, v[148:149], v[150:151] offset0:160 offset1:194
	s_nop 0
	v_mov_b32_dpp v212, v152 quad_perm:[1,0,3,2] row_mask:0xf bank_mask:0xf
	v_sub_f32_e32 v139, v139, v153
	v_mul_f32_e32 v139, 0x3fb8aa3b, v139
	v_exp_f32_e32 v131, v131
	s_waitcnt lgkmcnt(0)
	s_nop 0
	s_nop 0
	v_max3_f32 v152, v140, v152, v212
	v_max_f32_dpp v75, v59, v59 row_ror:8 row_mask:0xf bank_mask:0xf
	v_sub_f32_e32 v43, v90, v152
	s_nop 1
	v_mov_b32_dpp v90, v75 row_shl:4 row_mask:0xf bank_mask:0x5
	s_nop 1
	v_mov_b32_dpp v90, v75 row_shr:4 row_mask:0xf bank_mask:0xa
	v_sub_f32_e32 v58, v58, v152
	v_mul_f32_e32 v58, 0x3fb8aa3b, v58
	v_exp_f32_e32 v59, v58
	v_sub_f32_e32 v58, v74, v152
	s_nop 0
	v_max_f32_e32 v74, v90, v90
	v_max_f32_e32 v74, v75, v74
	s_nop 1
	v_mov_b32_dpp v90, v74 quad_perm:[2,3,0,1] row_mask:0xf bank_mask:0xf
	v_sub_f32_e32 v42, v42, v152
	v_mul_f32_e32 v42, 0x3fb8aa3b, v42
	v_exp_f32_e32 v75, v42
	v_mul_f32_e32 v58, 0x3fb8aa3b, v58
	s_nop 0
	v_max_f32_e32 v42, v90, v90
	v_max_f32_e32 v42, v74, v42
	v_exp_f32_e32 v91, v58
	s_nop 1
	v_mov_b32_dpp v58, v42 quad_perm:[1,0,3,2] row_mask:0xf bank_mask:0xf
	v_sub_f32_e32 v140, v140, v152
	v_mul_f32_e32 v74, 0x3fb8aa3b, v140
	v_exp_f32_e32 v140, v74
	v_mul_f32_e32 v43, 0x3fb8aa3b, v43
	s_nop 0
	v_max3_f32 v151, v141, v42, v58
	v_max3_f32 v58, v92, s59, v60
	v_max3_f32 v58, v58, v76, v44
	v_mov_b32_e32 v74, v58
	v_mov_b32_e32 v255, v58
	s_nop 1
	v_permlane16_swap_b32_e32 v74, v255
	s_nop 1
	s_nop 0
	v_sub_f32_e32 v90, v215, v151
	s_nop 0
	s_nop 0
	v_max_f32_e32 v74, v74, v255
	s_nop 1
	s_nop 0
	v_mul_f32_e32 v58, 0x3fb8aa3b, v90
	v_sub_f32_e32 v90, v216, v151
	v_mov_b32_e32 v216, v93
	s_nop 0
	s_nop 0
	v_max_f32_dpp v150, v74, v74 row_ror:8 row_mask:0xf bank_mask:0xf
	v_mov_b32_e32 v217, v61
	s_nop 0
	v_mov_b32_dpp v212, v150 row_shl:4 row_mask:0xf bank_mask:0x5
	s_nop 1
	v_mov_b32_dpp v212, v150 row_shr:4 row_mask:0xf bank_mask:0xa
	v_mov_b32_e32 v218, v77
	v_max3_f32 v61, v216, s59, v217
	v_mov_b32_e32 v215, v45
	s_nop 0
	v_max_f32_e32 v212, v212, v212
	v_max3_f32 v45, v61, v218, v215
	v_sub_f32_e32 v42, v214, v151
	v_sub_f32_e32 v74, v213, v151
	v_max_f32_e32 v150, v150, v212
	v_mov_b32_e32 v61, v45
	v_mov_b32_e32 v255, v45
	s_nop 1
	v_permlane16_swap_b32_e32 v61, v255
	s_nop 1
	s_nop 0
	v_mul_f32_e32 v42, 0x3fb8aa3b, v42
	v_mul_f32_e32 v90, 0x3fb8aa3b, v90
	v_mul_f32_e32 v74, 0x3fb8aa3b, v74
	v_mov_b32_dpp v214, v150 quad_perm:[2,3,0,1] row_mask:0xf bank_mask:0xf
	v_exp_f32_e32 v43, v43
	v_exp_f32_e32 v42, v42
	v_exp_f32_e32 v58, v58
	v_exp_f32_e32 v90, v90
	v_exp_f32_e32 v74, v74
	s_nop 0
	s_nop 0
	v_cvt_pk_bf16_f32 v148, v43, v59
	v_cvt_pk_bf16_f32 v149, v91, v75
	v_cvt_pk_bf16_f32 v212, v42, v58
	v_cvt_pk_bf16_f32 v213, v90, v74
	s_nop 0
	v_max_f32_e32 v214, v214, v214
	v_add_u32_e32 v77, 0x9c00, v186
	v_max_f32_e32 v61, v61, v255
	v_max_f32_e32 v150, v150, v214
	ds_write2_b64 v77, v[148:149], v[212:213] offset0:100 offset1:134
	s_nop 0
	v_mov_b32_dpp v214, v150 quad_perm:[1,0,3,2] row_mask:0xf bank_mask:0xf
	v_sub_f32_e32 v141, v141, v151
	v_mul_f32_e32 v141, 0x3fb8aa3b, v141
	v_exp_f32_e32 v133, v133
	s_waitcnt lgkmcnt(0)
	s_nop 0
	s_nop 0
	v_max3_f32 v150, v142, v150, v214
	v_max_f32_dpp v77, v61, v61 row_ror:8 row_mask:0xf bank_mask:0xf
	v_sub_f32_e32 v45, v92, v150
	s_nop 1
	v_mov_b32_dpp v92, v77 row_shl:4 row_mask:0xf bank_mask:0x5
	s_nop 1
	v_mov_b32_dpp v92, v77 row_shr:4 row_mask:0xf bank_mask:0xa
	v_sub_f32_e32 v60, v60, v150
	v_mul_f32_e32 v60, 0x3fb8aa3b, v60
	v_exp_f32_e32 v61, v60
	v_sub_f32_e32 v60, v76, v150
	s_nop 0
	v_max_f32_e32 v76, v92, v92
	v_max_f32_e32 v76, v77, v76
	s_nop 1
	v_mov_b32_dpp v92, v76 quad_perm:[2,3,0,1] row_mask:0xf bank_mask:0xf
	v_sub_f32_e32 v44, v44, v150
	v_mul_f32_e32 v44, 0x3fb8aa3b, v44
	v_exp_f32_e32 v77, v44
	v_mul_f32_e32 v60, 0x3fb8aa3b, v60
	s_nop 0
	v_max_f32_e32 v44, v92, v92
	v_max_f32_e32 v44, v76, v44
	v_exp_f32_e32 v93, v60
	s_nop 1
	v_mov_b32_dpp v60, v44 quad_perm:[1,0,3,2] row_mask:0xf bank_mask:0xf
	v_sub_f32_e32 v142, v142, v150
	v_mul_f32_e32 v76, 0x3fb8aa3b, v142
	v_exp_f32_e32 v142, v76
	v_mul_f32_e32 v45, 0x3fb8aa3b, v45
	s_nop 0
	v_max3_f32 v149, v143, v44, v60
	v_max3_f32 v60, v94, s59, v62
	v_max3_f32 v60, v60, v78, v46
	v_mov_b32_e32 v76, v60
	v_mov_b32_e32 v255, v60
	s_nop 1
	v_permlane16_swap_b32_e32 v76, v255
	s_nop 1
	s_nop 0
	v_sub_f32_e32 v92, v217, v149
	s_nop 0
	s_nop 0
	v_max_f32_e32 v76, v76, v255
	s_nop 1
	s_nop 0
	v_mov_b32_e32 v217, v95
	s_nop 0
	s_nop 0
	v_mul_f32_e32 v60, 0x3fb8aa3b, v92
	v_sub_f32_e32 v92, v218, v149
	v_max_f32_dpp v148, v76, v76 row_ror:8 row_mask:0xf bank_mask:0xf
	v_mov_b32_e32 v218, v63
	s_nop 0
	v_mov_b32_dpp v214, v148 row_shl:4 row_mask:0xf bank_mask:0x5
	s_nop 1
	v_mov_b32_dpp v214, v148 row_shr:4 row_mask:0xf bank_mask:0xa
	v_mov_b32_e32 v219, v79
	v_max3_f32 v63, v217, s59, v218
	v_mov_b32_e32 v96, v47
	s_nop 0
	v_max_f32_e32 v214, v214, v214
	v_max3_f32 v47, v63, v219, v96
	v_sub_f32_e32 v44, v216, v149
	v_sub_f32_e32 v76, v215, v149
	v_max_f32_e32 v148, v148, v214
	v_mov_b32_e32 v63, v47
	v_mov_b32_e32 v255, v47
	s_nop 1
	v_permlane16_swap_b32_e32 v63, v255
	s_nop 1
	s_nop 0
	v_mul_f32_e32 v44, 0x3fb8aa3b, v44
	v_mul_f32_e32 v92, 0x3fb8aa3b, v92
	v_mul_f32_e32 v76, 0x3fb8aa3b, v76
	v_mov_b32_dpp v216, v148 quad_perm:[2,3,0,1] row_mask:0xf bank_mask:0xf
	v_exp_f32_e32 v45, v45
	v_exp_f32_e32 v44, v44
	v_exp_f32_e32 v60, v60
	v_exp_f32_e32 v92, v92
	v_exp_f32_e32 v76, v76
	s_nop 0
	s_nop 0
	v_cvt_pk_bf16_f32 v212, v45, v61
	v_cvt_pk_bf16_f32 v213, v93, v77
	v_cvt_pk_bf16_f32 v214, v44, v60
	v_cvt_pk_bf16_f32 v215, v92, v76
	s_nop 0
	v_max_f32_e32 v216, v216, v216
	v_add_u32_e32 v79, 0xa000, v186
	v_max_f32_e32 v63, v63, v255
	v_max_f32_e32 v148, v148, v216
	ds_write2_b64 v79, v[212:213], v[214:215] offset0:176 offset1:210
	s_nop 0
	v_mov_b32_dpp v216, v148 quad_perm:[1,0,3,2] row_mask:0xf bank_mask:0xf
	v_sub_f32_e32 v143, v143, v149
	v_mul_f32_e32 v143, 0x3fb8aa3b, v143
	v_exp_f32_e32 v135, v135
	s_waitcnt lgkmcnt(0)
	s_nop 0
	s_nop 0
	v_max3_f32 v148, v144, v148, v216
	v_max_f32_dpp v79, v63, v63 row_ror:8 row_mask:0xf bank_mask:0xf
	v_sub_f32_e32 v47, v94, v148
	s_nop 1
	v_mov_b32_dpp v94, v79 row_shl:4 row_mask:0xf bank_mask:0x5
	s_nop 1
	v_mov_b32_dpp v94, v79 row_shr:4 row_mask:0xf bank_mask:0xa
	v_sub_f32_e32 v62, v62, v148
	v_mul_f32_e32 v62, 0x3fb8aa3b, v62
	v_exp_f32_e32 v63, v62
	v_sub_f32_e32 v62, v78, v148
	s_nop 0
	v_max_f32_e32 v78, v94, v94
	v_max_f32_e32 v78, v79, v78
	s_nop 1
	v_mov_b32_dpp v94, v78 quad_perm:[2,3,0,1] row_mask:0xf bank_mask:0xf
	v_sub_f32_e32 v46, v46, v148
	v_mul_f32_e32 v46, 0x3fb8aa3b, v46
	v_exp_f32_e32 v79, v46
	v_mul_f32_e32 v62, 0x3fb8aa3b, v62
	s_nop 0
	v_max_f32_e32 v46, v94, v94
	v_max_f32_e32 v46, v78, v46
	v_exp_f32_e32 v95, v62
	s_nop 1
	v_mov_b32_dpp v62, v46 quad_perm:[1,0,3,2] row_mask:0xf bank_mask:0xf
	v_sub_f32_e32 v144, v144, v148
	v_mul_f32_e32 v78, 0x3fb8aa3b, v144
	v_exp_f32_e32 v144, v78
	v_mul_f32_e32 v47, 0x3fb8aa3b, v47
	s_nop 0
	v_max3_f32 v147, v145, v46, v62
	v_sub_f32_e32 v78, v219, v147
	v_mul_f32_e32 v78, 0x3fb8aa3b, v78
	v_sub_f32_e32 v46, v217, v147
	v_sub_f32_e32 v62, v218, v147
	v_exp_f32_e32 v94, v78
	v_sub_f32_e32 v78, v96, v147
	v_sub_f32_e32 v145, v145, v147
	v_mul_f32_e32 v46, 0x3fb8aa3b, v46
	v_mul_f32_e32 v62, 0x3fb8aa3b, v62
	v_mul_f32_e32 v78, 0x3fb8aa3b, v78
	v_exp_f32_e32 v47, v47
	v_exp_f32_e32 v46, v46
	v_exp_f32_e32 v62, v62
	v_exp_f32_e32 v78, v78
	v_mul_f32_e32 v96, 0x3fb8aa3b, v145
	v_exp_f32_e32 v137, v137
	v_exp_f32_e32 v139, v139
	v_exp_f32_e32 v141, v141
	v_exp_f32_e32 v143, v143
	v_exp_f32_e32 v145, v96
	v_cvt_pk_bf16_f32 v208, v47, v63
	v_cvt_pk_bf16_f32 v209, v95, v79
	v_cvt_pk_bf16_f32 v210, v46, v62
	v_cvt_pk_bf16_f32 v211, v94, v78
	v_add_u32_e32 v96, 0xa400, v186
	ds_write2_b64 v96, v[208:209], v[210:211] offset0:116 offset1:150
	v_pk_mul_f32 v[14:15], v[14:15], v[144:145]
	v_pk_mul_f32 v[12:13], v[12:13], v[142:143]
	v_pk_mul_f32 v[10:11], v[10:11], v[140:141]
	v_pk_mul_f32 v[8:9], v[8:9], v[138:139]
	v_pk_mul_f32 v[6:7], v[6:7], v[136:137]
	v_pk_mul_f32 v[4:5], v[4:5], v[134:135]
	v_pk_mul_f32 v[2:3], v[2:3], v[132:133]
	v_pk_mul_f32 v[0:1], v[0:1], v[130:131]
	v_pk_mul_f32 v[30:31], v[30:31], v[144:145]
	v_pk_mul_f32 v[28:29], v[28:29], v[142:143]
	v_pk_mul_f32 v[26:27], v[26:27], v[140:141]
	v_pk_mul_f32 v[24:25], v[24:25], v[138:139]
	v_pk_mul_f32 v[22:23], v[22:23], v[136:137]
	v_pk_mul_f32 v[20:21], v[20:21], v[134:135]
	v_pk_mul_f32 v[18:19], v[18:19], v[132:133]
	v_pk_mul_f32 v[16:17], v[16:17], v[130:131]
	s_mov_b32 s2, -16
	v_mov_b32_e32 v96, v185
	v_mov_b32_e32 v208, v184
	s_branch .Latt_join
.LBB0_722:
	v_mbcnt_hi_u32_b32 v35, -1, v195
	v_and_b32_e32 v32, 64, v35
	v_add_u32_e32 v36, 64, v32
	v_xor_b32_e32 v37, 16, v35
	v_cmp_lt_i32_e32 vcc, v37, v36
	v_xor_b32_e32 v38, 8, v35
	s_lshl_b32 s0, s42, 1
	v_cndmask_b32_e32 v37, v35, v37, vcc
	v_lshlrev_b32_e32 v39, 2, v37
	v_mov_b32_e32 v37, v129
	v_mov_b32_e32 v255, v129
	s_nop 1
	v_permlane16_swap_b32_e32 v37, v255
	s_nop 1
	s_nop 0
	v_cmp_lt_i32_e32 vcc, v38, v36
	v_readlane_b32 s1, v249, 25
	s_add_u32 s0, s1, s0
	v_cndmask_b32_e32 v38, v35, v38, vcc
	s_waitcnt lgkmcnt(0)
	v_add_f32_e32 v37, v37, v255
	v_lshlrev_b32_e32 v40, 2, v38
	s_nop 1
	s_nop 0
	v_readlane_b32 s1, v249, 26
	s_addc_u32 s1, s1, 0
	v_lshlrev_b32_e32 v96, 1, v157
	v_lshl_add_u64 v[32:33], s[0:1], 0, v[96:97]
	s_nop 0
	v_add_f32_dpp v37, v37, v37 row_ror:8 row_mask:0xf bank_mask:0xf
	v_xor_b32_e32 v38, 4, v35
	v_cmp_lt_i32_e32 vcc, v38, v36
	v_add_u32_e32 v34, s4, v159
	s_nop 0
	v_cndmask_b32_e32 v38, v35, v38, vcc
	v_lshlrev_b32_e32 v38, 2, v38
	v_mov_b32_dpp v41, v37 row_shl:4 row_mask:0xf bank_mask:0x5
	v_mov_b32_dpp v41, v37 row_shr:4 row_mask:0xf bank_mask:0xa
	s_nop 0
	v_add_f32_e32 v41, v37, v41
	v_xor_b32_e32 v37, 2, v35
	v_cmp_lt_i32_e32 vcc, v37, v36
	s_nop 1
	v_cndmask_b32_e32 v37, v35, v37, vcc
	v_lshlrev_b32_e32 v37, 2, v37
	s_nop 0
	s_nop 0
	v_add_f32_dpp v41, v41, v41 quad_perm:[2,3,0,1] row_mask:0xf bank_mask:0xf
	v_xor_b32_e32 v42, 1, v35
	v_cmp_lt_i32_e32 vcc, v42, v36
	s_nop 1
	v_cndmask_b32_e32 v35, v35, v42, vcc
	v_lshlrev_b32_e32 v36, 2, v35
	s_nop 0
	s_nop 0
	v_add_f32_dpp v35, v41, v41 quad_perm:[1,0,3,2] row_mask:0xf bank_mask:0xf
	v_sub_f32_e32 v41, v146, v207
	v_mul_f32_e32 v41, 0x3fb8aa3b, v41
	v_exp_f32_e32 v41, v41
	s_nop 0
	v_add_f32_e32 v35, v41, v35
	v_div_scale_f32 v41, s[0:1], v35, v35, 1.0
	v_rcp_f32_e32 v42, v41
	s_nop 0
	v_fma_f32 v43, -v41, v42, 1.0
	v_fmac_f32_e32 v42, v43, v42
	v_div_scale_f32 v43, vcc, 1.0, v35, 1.0
	v_mul_f32_e32 v44, v43, v42
	v_fma_f32 v45, -v41, v44, v43
	v_fmac_f32_e32 v44, v45, v42
	v_fma_f32 v41, -v41, v44, v43
	v_div_fmas_f32 v41, v41, v42, v44
	v_div_fixup_f32 v41, v41, v35, 1.0
	v_ashrrev_i32_e32 v35, 31, v34
	v_mul_f32_e32 v0, v0, v41
	v_lshlrev_b64 v[42:43], 10, v[34:35]
	v_cvt_pk_bf16_f32 v0, v0, s0
	v_lshl_add_u64 v[42:43], v[32:33], 0, v[42:43]
	global_store_short v[42:43], v0, off
	v_mul_f32_e32 v0, v16, v41
	v_cvt_pk_bf16_f32 v0, v0, s0
	global_store_short v[42:43], v0, off offset:64
	v_mov_b32_e32 v0, v128
	v_mov_b32_e32 v255, v128
	s_nop 1
	v_permlane16_swap_b32_e32 v0, v255
	s_nop 1
	s_nop 0
	s_nop 0
	v_add_f32_e32 v0, v0, v255
	s_nop 1
	v_mov_b32_dpp v16, v0 row_ror:8 row_mask:0xf bank_mask:0xf
	s_nop 0
	v_add_f32_e32 v0, v0, v16
	s_nop 1
	v_mov_b32_dpp v16, v0 row_shl:4 row_mask:0xf bank_mask:0x5
	v_mov_b32_dpp v16, v0 row_shr:4 row_mask:0xf bank_mask:0xa
	s_nop 0
	v_add_f32_e32 v0, v0, v16
	s_nop 1
	v_mov_b32_dpp v16, v0 quad_perm:[2,3,0,1] row_mask:0xf bank_mask:0xf
	s_nop 0
	v_add_f32_e32 v0, v0, v16
	s_nop 1
	s_nop 0
	s_nop 0
	v_add_f32_dpp v0, v0, v0 quad_perm:[1,0,3,2] row_mask:0xf bank_mask:0xf
	v_sub_f32_e32 v16, v146, v206
	v_mul_f32_e32 v16, 0x3fb8aa3b, v16
	v_exp_f32_e32 v16, v16
	s_nop 0
	v_add_f32_e32 v0, v16, v0
	v_div_scale_f32 v16, s[0:1], v0, v0, 1.0
	v_rcp_f32_e32 v35, v16
	s_nop 0
	v_fma_f32 v41, -v16, v35, 1.0
	v_fmac_f32_e32 v35, v41, v35
	v_div_scale_f32 v41, vcc, 1.0, v0, 1.0
	v_mul_f32_e32 v42, v41, v35
	v_fma_f32 v43, -v16, v42, v41
	v_fmac_f32_e32 v42, v43, v35
	v_fma_f32 v16, -v16, v42, v41
	v_div_fmas_f32 v16, v16, v35, v42
	v_div_fixup_f32 v16, v16, v0, 1.0
	v_add_u32_e32 v0, 1, v34
	v_mul_f32_e32 v1, v1, v16
	v_cvt_pk_bf16_f32 v35, v1, s0
	v_ashrrev_i32_e32 v1, 31, v0
	v_lshlrev_b64 v[0:1], 10, v[0:1]
	v_mul_f32_e32 v16, v17, v16
	v_lshl_add_u64 v[0:1], v[32:33], 0, v[0:1]
	v_cvt_pk_bf16_f32 v16, v16, s0
	global_store_short v[0:1], v35, off
	global_store_short v[0:1], v16, off offset:64
	v_mov_b32_e32 v0, v127
	v_mov_b32_e32 v255, v127
	s_nop 1
	v_permlane16_swap_b32_e32 v0, v255
	s_nop 1
	s_nop 0
	s_nop 0
	v_add_f32_e32 v0, v0, v255
	s_nop 1
	v_mov_b32_dpp v1, v0 row_ror:8 row_mask:0xf bank_mask:0xf
	s_nop 0
	v_add_f32_e32 v0, v0, v1
	s_nop 1
	v_mov_b32_dpp v1, v0 row_shl:4 row_mask:0xf bank_mask:0x5
	v_mov_b32_dpp v1, v0 row_shr:4 row_mask:0xf bank_mask:0xa
	s_nop 0
	v_add_f32_e32 v0, v0, v1
	s_nop 1
	v_mov_b32_dpp v1, v0 quad_perm:[2,3,0,1] row_mask:0xf bank_mask:0xf
	s_nop 0
	v_add_f32_e32 v0, v0, v1
	s_nop 1
	s_nop 0
	s_nop 0
	v_add_f32_dpp v0, v0, v0 quad_perm:[1,0,3,2] row_mask:0xf bank_mask:0xf
	v_sub_f32_e32 v1, v146, v189
	v_mul_f32_e32 v1, 0x3fb8aa3b, v1
	v_exp_f32_e32 v1, v1
	s_nop 0
	v_add_f32_e32 v0, v1, v0
	v_div_scale_f32 v1, s[0:1], v0, v0, 1.0
	v_rcp_f32_e32 v16, v1
	s_nop 0
	v_fma_f32 v17, -v1, v16, 1.0
	v_fmac_f32_e32 v16, v17, v16
	v_div_scale_f32 v17, vcc, 1.0, v0, 1.0
	v_mul_f32_e32 v35, v17, v16
	v_fma_f32 v41, -v1, v35, v17
	v_fmac_f32_e32 v35, v41, v16
	v_fma_f32 v1, -v1, v35, v17
	v_div_fmas_f32 v1, v1, v16, v35
	v_div_fixup_f32 v16, v1, v0, 1.0
	v_add_u32_e32 v0, 2, v34
	v_mul_f32_e32 v1, v2, v16
	v_cvt_pk_bf16_f32 v2, v1, s0
	v_ashrrev_i32_e32 v1, 31, v0
	v_lshlrev_b64 v[0:1], 10, v[0:1]
	v_lshl_add_u64 v[0:1], v[32:33], 0, v[0:1]
	global_store_short v[0:1], v2, off
	v_mul_f32_e32 v2, v18, v16
	v_cvt_pk_bf16_f32 v2, v2, s0
	global_store_short v[0:1], v2, off offset:64
	v_mov_b32_e32 v0, v126
	v_mov_b32_e32 v255, v126
	s_nop 1
	v_permlane16_swap_b32_e32 v0, v255
	s_nop 1
	s_nop 0
	s_nop 0
	v_add_f32_e32 v0, v0, v255
	s_nop 1
	v_mov_b32_dpp v1, v0 row_ror:8 row_mask:0xf bank_mask:0xf
	s_nop 0
	v_add_f32_e32 v0, v0, v1
	s_nop 1
	v_mov_b32_dpp v1, v0 row_shl:4 row_mask:0xf bank_mask:0x5
	v_mov_b32_dpp v1, v0 row_shr:4 row_mask:0xf bank_mask:0xa
	s_nop 0
	v_add_f32_e32 v0, v0, v1
	s_nop 1
	v_mov_b32_dpp v1, v0 quad_perm:[2,3,0,1] row_mask:0xf bank_mask:0xf
	s_nop 0
	v_add_f32_e32 v0, v0, v1
	s_nop 1
	s_nop 0
	s_nop 0
	v_add_f32_dpp v0, v0, v0 quad_perm:[1,0,3,2] row_mask:0xf bank_mask:0xf
	v_sub_f32_e32 v1, v146, v188
	v_mul_f32_e32 v1, 0x3fb8aa3b, v1
	v_exp_f32_e32 v1, v1
	s_nop 0
	v_add_f32_e32 v0, v1, v0
	v_div_scale_f32 v1, s[0:1], v0, v0, 1.0
	v_rcp_f32_e32 v2, v1
	s_nop 0
	v_fma_f32 v16, -v1, v2, 1.0
	v_fmac_f32_e32 v2, v16, v2
	v_div_scale_f32 v16, vcc, 1.0, v0, 1.0
	v_mul_f32_e32 v17, v16, v2
	v_fma_f32 v18, -v1, v17, v16
	v_fmac_f32_e32 v17, v18, v2
	v_fma_f32 v1, -v1, v17, v16
	v_div_fmas_f32 v1, v1, v2, v17
	v_div_fixup_f32 v2, v1, v0, 1.0
	v_add_u32_e32 v0, 3, v34
	v_mul_f32_e32 v1, v3, v2
	v_cvt_pk_bf16_f32 v3, v1, s0
	v_ashrrev_i32_e32 v1, 31, v0
	v_lshlrev_b64 v[0:1], 10, v[0:1]
	v_mul_f32_e32 v2, v19, v2
	v_lshl_add_u64 v[0:1], v[32:33], 0, v[0:1]
	v_cvt_pk_bf16_f32 v2, v2, s0
	global_store_short v[0:1], v3, off
	global_store_short v[0:1], v2, off offset:64
	v_mov_b32_e32 v0, v125
	v_mov_b32_e32 v255, v125
	s_nop 1
	v_permlane16_swap_b32_e32 v0, v255
	s_nop 1
	s_nop 0
	s_nop 0
	v_add_f32_e32 v0, v0, v255
	s_nop 1
	v_mov_b32_dpp v1, v0 row_ror:8 row_mask:0xf bank_mask:0xf
	s_nop 0
	v_add_f32_e32 v0, v0, v1
	s_nop 1
	v_mov_b32_dpp v1, v0 row_shl:4 row_mask:0xf bank_mask:0x5
	v_mov_b32_dpp v1, v0 row_shr:4 row_mask:0xf bank_mask:0xa
	s_nop 0
	v_add_f32_e32 v0, v0, v1
	s_nop 1
	v_mov_b32_dpp v1, v0 quad_perm:[2,3,0,1] row_mask:0xf bank_mask:0xf
	s_nop 0
	v_add_f32_e32 v0, v0, v1
	s_nop 1
	s_nop 0
	s_nop 0
	v_add_f32_dpp v0, v0, v0 quad_perm:[1,0,3,2] row_mask:0xf bank_mask:0xf
	v_sub_f32_e32 v1, v146, v187
	v_mul_f32_e32 v1, 0x3fb8aa3b, v1
	v_exp_f32_e32 v1, v1
	s_nop 0
	v_add_f32_e32 v0, v1, v0
	v_div_scale_f32 v1, s[0:1], v0, v0, 1.0
	v_rcp_f32_e32 v2, v1
	s_nop 0
	v_fma_f32 v3, -v1, v2, 1.0
	v_fmac_f32_e32 v2, v3, v2
	v_div_scale_f32 v3, vcc, 1.0, v0, 1.0
	v_mul_f32_e32 v16, v3, v2
	v_fma_f32 v17, -v1, v16, v3
	v_fmac_f32_e32 v16, v17, v2
	v_fma_f32 v1, -v1, v16, v3
	v_div_fmas_f32 v1, v1, v2, v16
	v_div_fixup_f32 v2, v1, v0, 1.0
	v_add_u32_e32 v0, 8, v34
	v_mul_f32_e32 v1, v4, v2
	v_cvt_pk_bf16_f32 v3, v1, s0
	v_ashrrev_i32_e32 v1, 31, v0
	v_lshlrev_b64 v[0:1], 10, v[0:1]
	v_mul_f32_e32 v2, v20, v2
	v_lshl_add_u64 v[0:1], v[32:33], 0, v[0:1]
	v_cvt_pk_bf16_f32 v2, v2, s0
	global_store_short v[0:1], v3, off
	global_store_short v[0:1], v2, off offset:64
	v_mov_b32_e32 v0, v124
	v_mov_b32_e32 v255, v124
	s_nop 1
	v_permlane16_swap_b32_e32 v0, v255
	s_nop 1
	s_nop 0
	s_nop 0
	v_add_f32_e32 v0, v0, v255
	s_nop 1
	v_mov_b32_dpp v1, v0 row_ror:8 row_mask:0xf bank_mask:0xf
	s_nop 0
	v_add_f32_e32 v0, v0, v1
	s_nop 1
	v_mov_b32_dpp v1, v0 row_shl:4 row_mask:0xf bank_mask:0x5
	v_mov_b32_dpp v1, v0 row_shr:4 row_mask:0xf bank_mask:0xa
	s_nop 0
	v_add_f32_e32 v0, v0, v1
	s_nop 1
	v_mov_b32_dpp v1, v0 quad_perm:[2,3,0,1] row_mask:0xf bank_mask:0xf
	s_nop 0
	v_add_f32_e32 v0, v0, v1
	s_nop 1
	s_nop 0
	s_nop 0
	v_add_f32_dpp v0, v0, v0 quad_perm:[1,0,3,2] row_mask:0xf bank_mask:0xf
	v_sub_f32_e32 v1, v146, v160
	v_mul_f32_e32 v1, 0x3fb8aa3b, v1
	v_exp_f32_e32 v1, v1
	s_nop 0
	v_add_f32_e32 v0, v1, v0
	v_div_scale_f32 v1, s[0:1], v0, v0, 1.0
	v_rcp_f32_e32 v2, v1
	s_nop 0
	v_fma_f32 v3, -v1, v2, 1.0
	v_fmac_f32_e32 v2, v3, v2
	v_div_scale_f32 v3, vcc, 1.0, v0, 1.0
	v_mul_f32_e32 v4, v3, v2
	v_fma_f32 v16, -v1, v4, v3
	v_fmac_f32_e32 v4, v16, v2
	v_fma_f32 v1, -v1, v4, v3
	v_div_fmas_f32 v1, v1, v2, v4
	v_div_fixup_f32 v2, v1, v0, 1.0
	v_add_u32_e32 v0, 9, v34
	v_mul_f32_e32 v1, v5, v2
	v_cvt_pk_bf16_f32 v3, v1, s0
	v_ashrrev_i32_e32 v1, 31, v0
	v_lshlrev_b64 v[0:1], 10, v[0:1]
	v_mul_f32_e32 v2, v21, v2
	v_lshl_add_u64 v[0:1], v[32:33], 0, v[0:1]
	v_cvt_pk_bf16_f32 v2, v2, s0
	global_store_short v[0:1], v3, off
	global_store_short v[0:1], v2, off offset:64
	v_mov_b32_e32 v0, v123
	v_mov_b32_e32 v255, v123
	s_nop 1
	v_permlane16_swap_b32_e32 v0, v255
	s_nop 1
	s_nop 0
	s_nop 0
	v_add_f32_e32 v0, v0, v255
	s_nop 1
	v_mov_b32_dpp v1, v0 row_ror:8 row_mask:0xf bank_mask:0xf
	s_nop 0
	v_add_f32_e32 v0, v0, v1
	s_nop 1
	v_mov_b32_dpp v1, v0 row_shl:4 row_mask:0xf bank_mask:0x5
	v_mov_b32_dpp v1, v0 row_shr:4 row_mask:0xf bank_mask:0xa
	s_nop 0
	v_add_f32_e32 v0, v0, v1
	s_nop 1
	v_mov_b32_dpp v1, v0 quad_perm:[2,3,0,1] row_mask:0xf bank_mask:0xf
	s_nop 0
	v_add_f32_e32 v0, v0, v1
	s_nop 1
	s_nop 0
	s_nop 0
	v_add_f32_dpp v0, v0, v0 quad_perm:[1,0,3,2] row_mask:0xf bank_mask:0xf
	v_sub_f32_e32 v1, v146, v156
	v_mul_f32_e32 v1, 0x3fb8aa3b, v1
	v_exp_f32_e32 v1, v1
	s_nop 0
	v_add_f32_e32 v0, v1, v0
	v_div_scale_f32 v1, s[0:1], v0, v0, 1.0
	v_rcp_f32_e32 v2, v1
	s_nop 0
	v_fma_f32 v3, -v1, v2, 1.0
	v_fmac_f32_e32 v2, v3, v2
	v_div_scale_f32 v3, vcc, 1.0, v0, 1.0
	v_mul_f32_e32 v4, v3, v2
	v_fma_f32 v5, -v1, v4, v3
	v_fmac_f32_e32 v4, v5, v2
	v_fma_f32 v1, -v1, v4, v3
	v_div_fmas_f32 v1, v1, v2, v4
	v_div_fixup_f32 v2, v1, v0, 1.0
	v_add_u32_e32 v0, 10, v34
	v_mul_f32_e32 v1, v6, v2
	v_cvt_pk_bf16_f32 v3, v1, s0
	v_ashrrev_i32_e32 v1, 31, v0
	v_lshlrev_b64 v[0:1], 10, v[0:1]
	v_mul_f32_e32 v2, v22, v2
	v_lshl_add_u64 v[0:1], v[32:33], 0, v[0:1]
	v_cvt_pk_bf16_f32 v2, v2, s0
	global_store_short v[0:1], v3, off
	global_store_short v[0:1], v2, off offset:64
	v_mov_b32_e32 v0, v122
	v_mov_b32_e32 v255, v122
	s_nop 1
	v_permlane16_swap_b32_e32 v0, v255
	s_nop 1
	s_nop 0
	s_nop 0
	v_add_f32_e32 v0, v0, v255
	s_nop 1
	v_mov_b32_dpp v1, v0 row_ror:8 row_mask:0xf bank_mask:0xf
	s_nop 0
	v_add_f32_e32 v0, v0, v1
	s_nop 1
	v_mov_b32_dpp v1, v0 row_shl:4 row_mask:0xf bank_mask:0x5
	v_mov_b32_dpp v1, v0 row_shr:4 row_mask:0xf bank_mask:0xa
	s_nop 0
	v_add_f32_e32 v0, v0, v1
	s_nop 1
	v_mov_b32_dpp v1, v0 quad_perm:[2,3,0,1] row_mask:0xf bank_mask:0xf
	s_nop 0
	v_add_f32_e32 v0, v0, v1
	s_nop 1
	s_nop 0
	s_nop 0
	v_add_f32_dpp v0, v0, v0 quad_perm:[1,0,3,2] row_mask:0xf bank_mask:0xf
	v_sub_f32_e32 v1, v146, v155
	v_mul_f32_e32 v1, 0x3fb8aa3b, v1
	v_exp_f32_e32 v1, v1
	s_nop 0
	v_add_f32_e32 v0, v1, v0
	v_div_scale_f32 v1, s[0:1], v0, v0, 1.0
	v_rcp_f32_e32 v2, v1
	s_nop 0
	v_fma_f32 v3, -v1, v2, 1.0
	v_fmac_f32_e32 v2, v3, v2
	v_div_scale_f32 v3, vcc, 1.0, v0, 1.0
	v_mul_f32_e32 v4, v3, v2
	v_fma_f32 v5, -v1, v4, v3
	v_fmac_f32_e32 v4, v5, v2
	v_fma_f32 v1, -v1, v4, v3
	v_div_fmas_f32 v1, v1, v2, v4
	v_div_fixup_f32 v2, v1, v0, 1.0
	v_add_u32_e32 v0, 11, v34
	v_mul_f32_e32 v1, v7, v2
	v_cvt_pk_bf16_f32 v3, v1, s0
	v_ashrrev_i32_e32 v1, 31, v0
	v_lshlrev_b64 v[0:1], 10, v[0:1]
	v_mul_f32_e32 v2, v23, v2
	v_lshl_add_u64 v[0:1], v[32:33], 0, v[0:1]
	v_cvt_pk_bf16_f32 v2, v2, s0
	global_store_short v[0:1], v3, off
	global_store_short v[0:1], v2, off offset:64
	v_mov_b32_e32 v0, v121
	v_mov_b32_e32 v255, v121
	s_nop 1
	v_permlane16_swap_b32_e32 v0, v255
	s_nop 1
	s_nop 0
	s_nop 0
	v_add_f32_e32 v0, v0, v255
	s_nop 1
	v_mov_b32_dpp v1, v0 row_ror:8 row_mask:0xf bank_mask:0xf
	s_nop 0
	v_add_f32_e32 v0, v0, v1
	s_nop 1
	v_mov_b32_dpp v1, v0 row_shl:4 row_mask:0xf bank_mask:0x5
	v_mov_b32_dpp v1, v0 row_shr:4 row_mask:0xf bank_mask:0xa
	s_nop 0
	v_add_f32_e32 v0, v0, v1
	s_nop 1
	v_mov_b32_dpp v1, v0 quad_perm:[2,3,0,1] row_mask:0xf bank_mask:0xf
	s_nop 0
	v_add_f32_e32 v0, v0, v1
	s_nop 1
	s_nop 0
	s_nop 0
	v_add_f32_dpp v0, v0, v0 quad_perm:[1,0,3,2] row_mask:0xf bank_mask:0xf
	v_sub_f32_e32 v1, v146, v154
	v_mul_f32_e32 v1, 0x3fb8aa3b, v1
	v_exp_f32_e32 v1, v1
	s_nop 0
	v_add_f32_e32 v0, v1, v0
	v_div_scale_f32 v1, s[0:1], v0, v0, 1.0
	v_rcp_f32_e32 v2, v1
	s_nop 0
	v_fma_f32 v3, -v1, v2, 1.0
	v_fmac_f32_e32 v2, v3, v2
	v_div_scale_f32 v3, vcc, 1.0, v0, 1.0
	v_mul_f32_e32 v4, v3, v2
	v_fma_f32 v5, -v1, v4, v3
	v_fmac_f32_e32 v4, v5, v2
	v_fma_f32 v1, -v1, v4, v3
	v_div_fmas_f32 v1, v1, v2, v4
	v_div_fixup_f32 v2, v1, v0, 1.0
	v_add_u32_e32 v0, 16, v34
	v_mul_f32_e32 v1, v8, v2
	v_cvt_pk_bf16_f32 v3, v1, s0
	v_ashrrev_i32_e32 v1, 31, v0
	v_lshlrev_b64 v[0:1], 10, v[0:1]
	v_mul_f32_e32 v2, v24, v2
	v_lshl_add_u64 v[0:1], v[32:33], 0, v[0:1]
	v_cvt_pk_bf16_f32 v2, v2, s0
	global_store_short v[0:1], v3, off
	global_store_short v[0:1], v2, off offset:64
	v_mov_b32_e32 v0, v120
	v_mov_b32_e32 v255, v120
	s_nop 1
	v_permlane16_swap_b32_e32 v0, v255
	s_nop 1
	s_nop 0
	s_nop 0
	v_add_f32_e32 v0, v0, v255
	s_nop 1
	v_mov_b32_dpp v1, v0 row_ror:8 row_mask:0xf bank_mask:0xf
	s_nop 0
	v_add_f32_e32 v0, v0, v1
	s_nop 1
	v_mov_b32_dpp v1, v0 row_shl:4 row_mask:0xf bank_mask:0x5
	v_mov_b32_dpp v1, v0 row_shr:4 row_mask:0xf bank_mask:0xa
	s_nop 0
	v_add_f32_e32 v0, v0, v1
	s_nop 1
	v_mov_b32_dpp v1, v0 quad_perm:[2,3,0,1] row_mask:0xf bank_mask:0xf
	s_nop 0
	v_add_f32_e32 v0, v0, v1
	s_nop 1
	s_nop 0
	s_nop 0
	v_add_f32_dpp v0, v0, v0 quad_perm:[1,0,3,2] row_mask:0xf bank_mask:0xf
	v_sub_f32_e32 v1, v146, v153
	v_mul_f32_e32 v1, 0x3fb8aa3b, v1
	v_exp_f32_e32 v1, v1
	s_nop 0
	v_add_f32_e32 v0, v1, v0
	v_div_scale_f32 v1, s[0:1], v0, v0, 1.0
	v_rcp_f32_e32 v2, v1
	s_nop 0
	v_fma_f32 v3, -v1, v2, 1.0
	v_fmac_f32_e32 v2, v3, v2
	v_div_scale_f32 v3, vcc, 1.0, v0, 1.0
	v_mul_f32_e32 v4, v3, v2
	v_fma_f32 v5, -v1, v4, v3
	v_fmac_f32_e32 v4, v5, v2
	v_fma_f32 v1, -v1, v4, v3
	v_div_fmas_f32 v1, v1, v2, v4
	v_div_fixup_f32 v2, v1, v0, 1.0
	v_add_u32_e32 v0, 17, v34
	v_mul_f32_e32 v1, v9, v2
	v_cvt_pk_bf16_f32 v3, v1, s0
	v_ashrrev_i32_e32 v1, 31, v0
	v_lshlrev_b64 v[0:1], 10, v[0:1]
	v_mul_f32_e32 v2, v25, v2
	v_lshl_add_u64 v[0:1], v[32:33], 0, v[0:1]
	v_cvt_pk_bf16_f32 v2, v2, s0
	global_store_short v[0:1], v3, off
	global_store_short v[0:1], v2, off offset:64
	v_mov_b32_e32 v0, v119
	v_mov_b32_e32 v255, v119
	s_nop 1
	v_permlane16_swap_b32_e32 v0, v255
	s_nop 1
	s_nop 0
	s_nop 0
	v_add_f32_e32 v0, v0, v255
	s_nop 1
	v_mov_b32_dpp v1, v0 row_ror:8 row_mask:0xf bank_mask:0xf
	s_nop 0
	v_add_f32_e32 v0, v0, v1
	s_nop 1
	v_mov_b32_dpp v1, v0 row_shl:4 row_mask:0xf bank_mask:0x5
	v_mov_b32_dpp v1, v0 row_shr:4 row_mask:0xf bank_mask:0xa
	s_nop 0
	v_add_f32_e32 v0, v0, v1
	s_nop 1
	v_mov_b32_dpp v1, v0 quad_perm:[2,3,0,1] row_mask:0xf bank_mask:0xf
	s_nop 0
	v_add_f32_e32 v0, v0, v1
	s_nop 1
	s_nop 0
	s_nop 0
	v_add_f32_dpp v0, v0, v0 quad_perm:[1,0,3,2] row_mask:0xf bank_mask:0xf
	v_sub_f32_e32 v1, v146, v152
	v_mul_f32_e32 v1, 0x3fb8aa3b, v1
	v_exp_f32_e32 v1, v1
	s_nop 0
	v_add_f32_e32 v0, v1, v0
	v_div_scale_f32 v1, s[0:1], v0, v0, 1.0
	v_rcp_f32_e32 v2, v1
	s_nop 0
	v_fma_f32 v3, -v1, v2, 1.0
	v_fmac_f32_e32 v2, v3, v2
	v_div_scale_f32 v3, vcc, 1.0, v0, 1.0
	v_mul_f32_e32 v4, v3, v2
	v_fma_f32 v5, -v1, v4, v3
	v_fmac_f32_e32 v4, v5, v2
	v_fma_f32 v1, -v1, v4, v3
	v_div_fmas_f32 v1, v1, v2, v4
	v_div_fixup_f32 v2, v1, v0, 1.0
	v_add_u32_e32 v0, 18, v34
	v_mul_f32_e32 v1, v10, v2
	v_cvt_pk_bf16_f32 v3, v1, s0
	v_ashrrev_i32_e32 v1, 31, v0
	v_lshlrev_b64 v[0:1], 10, v[0:1]
	v_mul_f32_e32 v2, v26, v2
	v_lshl_add_u64 v[0:1], v[32:33], 0, v[0:1]
	v_cvt_pk_bf16_f32 v2, v2, s0
	global_store_short v[0:1], v3, off
	global_store_short v[0:1], v2, off offset:64
	v_mov_b32_e32 v0, v118
	v_mov_b32_e32 v255, v118
	s_nop 1
	v_permlane16_swap_b32_e32 v0, v255
	s_nop 1
	s_nop 0
	s_nop 0
	v_add_f32_e32 v0, v0, v255
	s_nop 1
	v_mov_b32_dpp v1, v0 row_ror:8 row_mask:0xf bank_mask:0xf
	s_nop 0
	v_add_f32_e32 v0, v0, v1
	s_nop 1
	v_mov_b32_dpp v1, v0 row_shl:4 row_mask:0xf bank_mask:0x5
	v_mov_b32_dpp v1, v0 row_shr:4 row_mask:0xf bank_mask:0xa
	s_nop 0
	v_add_f32_e32 v0, v0, v1
	s_nop 1
	v_mov_b32_dpp v1, v0 quad_perm:[2,3,0,1] row_mask:0xf bank_mask:0xf
	s_nop 0
	v_add_f32_e32 v0, v0, v1
	s_nop 1
	s_nop 0
	s_nop 0
	v_add_f32_dpp v0, v0, v0 quad_perm:[1,0,3,2] row_mask:0xf bank_mask:0xf
	v_sub_f32_e32 v1, v146, v151
	v_mul_f32_e32 v1, 0x3fb8aa3b, v1
	v_exp_f32_e32 v1, v1
	s_nop 0
	v_add_f32_e32 v0, v1, v0
	v_div_scale_f32 v1, s[0:1], v0, v0, 1.0
	v_rcp_f32_e32 v2, v1
	s_nop 0
	v_fma_f32 v3, -v1, v2, 1.0
	v_fmac_f32_e32 v2, v3, v2
	v_div_scale_f32 v3, vcc, 1.0, v0, 1.0
	v_mul_f32_e32 v4, v3, v2
	v_fma_f32 v5, -v1, v4, v3
	v_fmac_f32_e32 v4, v5, v2
	v_fma_f32 v1, -v1, v4, v3
	v_div_fmas_f32 v1, v1, v2, v4
	v_div_fixup_f32 v2, v1, v0, 1.0
	v_add_u32_e32 v0, 19, v34
	v_mul_f32_e32 v1, v11, v2
	v_cvt_pk_bf16_f32 v3, v1, s0
	v_ashrrev_i32_e32 v1, 31, v0
	v_lshlrev_b64 v[0:1], 10, v[0:1]
	v_mul_f32_e32 v2, v27, v2
	v_lshl_add_u64 v[0:1], v[32:33], 0, v[0:1]
	v_cvt_pk_bf16_f32 v2, v2, s0
	global_store_short v[0:1], v3, off
	global_store_short v[0:1], v2, off offset:64
	v_mov_b32_e32 v0, v117
	v_mov_b32_e32 v255, v117
	s_nop 1
	v_permlane16_swap_b32_e32 v0, v255
	s_nop 1
	s_nop 0
	s_nop 0
	v_add_f32_e32 v0, v0, v255
	s_nop 1
	v_mov_b32_dpp v1, v0 row_ror:8 row_mask:0xf bank_mask:0xf
	s_nop 0
	v_add_f32_e32 v0, v0, v1
	s_nop 1
	v_mov_b32_dpp v1, v0 row_shl:4 row_mask:0xf bank_mask:0x5
	v_mov_b32_dpp v1, v0 row_shr:4 row_mask:0xf bank_mask:0xa
	s_nop 0
	v_add_f32_e32 v0, v0, v1
	s_nop 1
	v_mov_b32_dpp v1, v0 quad_perm:[2,3,0,1] row_mask:0xf bank_mask:0xf
	s_nop 0
	v_add_f32_e32 v0, v0, v1
	s_nop 1
	s_nop 0
	s_nop 0
	v_add_f32_dpp v0, v0, v0 quad_perm:[1,0,3,2] row_mask:0xf bank_mask:0xf
	v_sub_f32_e32 v1, v146, v150
	v_mul_f32_e32 v1, 0x3fb8aa3b, v1
	v_exp_f32_e32 v1, v1
	s_nop 0
	v_add_f32_e32 v0, v1, v0
	v_div_scale_f32 v1, s[0:1], v0, v0, 1.0
	v_rcp_f32_e32 v2, v1
	s_nop 0
	v_fma_f32 v3, -v1, v2, 1.0
	v_fmac_f32_e32 v2, v3, v2
	v_div_scale_f32 v3, vcc, 1.0, v0, 1.0
	v_mul_f32_e32 v4, v3, v2
	v_fma_f32 v5, -v1, v4, v3
	v_fmac_f32_e32 v4, v5, v2
	v_fma_f32 v1, -v1, v4, v3
	v_div_fmas_f32 v1, v1, v2, v4
	v_div_fixup_f32 v2, v1, v0, 1.0
	v_add_u32_e32 v0, 24, v34
	v_mul_f32_e32 v1, v12, v2
	v_cvt_pk_bf16_f32 v3, v1, s0
	v_ashrrev_i32_e32 v1, 31, v0
	v_lshlrev_b64 v[0:1], 10, v[0:1]
	v_mul_f32_e32 v2, v28, v2
	v_lshl_add_u64 v[0:1], v[32:33], 0, v[0:1]
	v_cvt_pk_bf16_f32 v2, v2, s0
	global_store_short v[0:1], v3, off
	global_store_short v[0:1], v2, off offset:64
	v_mov_b32_e32 v0, v116
	v_mov_b32_e32 v255, v116
	s_nop 1
	v_permlane16_swap_b32_e32 v0, v255
	s_nop 1
	s_nop 0
	s_nop 0
	v_add_f32_e32 v0, v0, v255
	s_nop 1
	v_mov_b32_dpp v1, v0 row_ror:8 row_mask:0xf bank_mask:0xf
	s_nop 0
	v_add_f32_e32 v0, v0, v1
	s_nop 1
	v_mov_b32_dpp v1, v0 row_shl:4 row_mask:0xf bank_mask:0x5
	v_mov_b32_dpp v1, v0 row_shr:4 row_mask:0xf bank_mask:0xa
	s_nop 0
	v_add_f32_e32 v0, v0, v1
	s_nop 1
	v_mov_b32_dpp v1, v0 quad_perm:[2,3,0,1] row_mask:0xf bank_mask:0xf
	s_nop 0
	v_add_f32_e32 v0, v0, v1
	s_nop 1
	s_nop 0
	s_nop 0
	v_add_f32_dpp v0, v0, v0 quad_perm:[1,0,3,2] row_mask:0xf bank_mask:0xf
	v_sub_f32_e32 v1, v146, v149
	v_mul_f32_e32 v1, 0x3fb8aa3b, v1
	v_exp_f32_e32 v1, v1
	s_nop 0
	v_add_f32_e32 v0, v1, v0
	v_div_scale_f32 v1, s[0:1], v0, v0, 1.0
	v_rcp_f32_e32 v2, v1
	s_nop 0
	v_fma_f32 v3, -v1, v2, 1.0
	v_fmac_f32_e32 v2, v3, v2
	v_div_scale_f32 v3, vcc, 1.0, v0, 1.0
	v_mul_f32_e32 v4, v3, v2
	v_fma_f32 v5, -v1, v4, v3
	v_fmac_f32_e32 v4, v5, v2
	v_fma_f32 v1, -v1, v4, v3
	v_div_fmas_f32 v1, v1, v2, v4
	v_div_fixup_f32 v2, v1, v0, 1.0
	v_add_u32_e32 v0, 25, v34
	v_mul_f32_e32 v1, v13, v2
	v_cvt_pk_bf16_f32 v3, v1, s0
	v_ashrrev_i32_e32 v1, 31, v0
	v_lshlrev_b64 v[0:1], 10, v[0:1]
	v_mul_f32_e32 v2, v29, v2
	v_lshl_add_u64 v[0:1], v[32:33], 0, v[0:1]
	v_cvt_pk_bf16_f32 v2, v2, s0
	global_store_short v[0:1], v3, off
	global_store_short v[0:1], v2, off offset:64
	v_mov_b32_e32 v0, v115
	v_mov_b32_e32 v255, v115
	s_nop 1
	v_permlane16_swap_b32_e32 v0, v255
	s_nop 1
	s_nop 0
	s_nop 0
	v_add_f32_e32 v0, v0, v255
	s_nop 1
	v_mov_b32_dpp v1, v0 row_ror:8 row_mask:0xf bank_mask:0xf
	s_nop 0
	v_add_f32_e32 v0, v0, v1
	s_nop 1
	v_mov_b32_dpp v1, v0 row_shl:4 row_mask:0xf bank_mask:0x5
	v_mov_b32_dpp v1, v0 row_shr:4 row_mask:0xf bank_mask:0xa
	s_nop 0
	v_add_f32_e32 v0, v0, v1
	s_nop 1
	v_mov_b32_dpp v1, v0 quad_perm:[2,3,0,1] row_mask:0xf bank_mask:0xf
	s_nop 0
	v_add_f32_e32 v0, v0, v1
	s_nop 1
	s_nop 0
	s_nop 0
	v_add_f32_dpp v0, v0, v0 quad_perm:[1,0,3,2] row_mask:0xf bank_mask:0xf
	v_sub_f32_e32 v1, v146, v148
	v_mul_f32_e32 v1, 0x3fb8aa3b, v1
	v_exp_f32_e32 v1, v1
	s_nop 0
	v_add_f32_e32 v0, v1, v0
	v_div_scale_f32 v1, s[0:1], v0, v0, 1.0
	v_rcp_f32_e32 v2, v1
	s_nop 0
	v_fma_f32 v3, -v1, v2, 1.0
	v_fmac_f32_e32 v2, v3, v2
	v_div_scale_f32 v3, vcc, 1.0, v0, 1.0
	v_mul_f32_e32 v4, v3, v2
	v_fma_f32 v5, -v1, v4, v3
	v_fmac_f32_e32 v4, v5, v2
	v_fma_f32 v1, -v1, v4, v3
	v_div_fmas_f32 v1, v1, v2, v4
	v_div_fixup_f32 v2, v1, v0, 1.0
	v_add_u32_e32 v0, 26, v34
	v_mul_f32_e32 v1, v14, v2
	v_cvt_pk_bf16_f32 v3, v1, s0
	v_ashrrev_i32_e32 v1, 31, v0
	v_lshlrev_b64 v[0:1], 10, v[0:1]
	v_mul_f32_e32 v2, v30, v2
	v_lshl_add_u64 v[0:1], v[32:33], 0, v[0:1]
	v_cvt_pk_bf16_f32 v2, v2, s0
	global_store_short v[0:1], v3, off
	global_store_short v[0:1], v2, off offset:64
	v_mov_b32_e32 v0, v114
	v_mov_b32_e32 v255, v114
	s_nop 1
	v_permlane16_swap_b32_e32 v0, v255
	s_nop 1
	s_nop 0
	s_nop 0
	v_add_f32_e32 v0, v0, v255
	s_nop 1
	v_mov_b32_dpp v1, v0 row_ror:8 row_mask:0xf bank_mask:0xf
	s_nop 0
	v_add_f32_e32 v0, v0, v1
	s_nop 1
	v_mov_b32_dpp v1, v0 row_shl:4 row_mask:0xf bank_mask:0x5
	v_mov_b32_dpp v1, v0 row_shr:4 row_mask:0xf bank_mask:0xa
	s_nop 0
	v_add_f32_e32 v0, v0, v1
	s_nop 1
	v_mov_b32_dpp v1, v0 quad_perm:[2,3,0,1] row_mask:0xf bank_mask:0xf
	s_nop 0
	v_add_f32_e32 v0, v0, v1
	s_nop 1
	s_nop 0
	s_nop 0
	v_add_f32_dpp v0, v0, v0 quad_perm:[1,0,3,2] row_mask:0xf bank_mask:0xf
	v_sub_f32_e32 v1, v146, v147
	v_mul_f32_e32 v1, 0x3fb8aa3b, v1
	v_exp_f32_e32 v1, v1
	s_nop 0
	v_add_f32_e32 v0, v1, v0
	v_div_scale_f32 v1, s[0:1], v0, v0, 1.0
	v_rcp_f32_e32 v2, v1
	s_nop 0
	v_fma_f32 v3, -v1, v2, 1.0
	v_fmac_f32_e32 v2, v3, v2
	v_div_scale_f32 v3, vcc, 1.0, v0, 1.0
	v_mul_f32_e32 v4, v3, v2
	v_fma_f32 v5, -v1, v4, v3
	v_fmac_f32_e32 v4, v5, v2
	v_fma_f32 v1, -v1, v4, v3
	v_div_fmas_f32 v1, v1, v2, v4
	v_div_fixup_f32 v2, v1, v0, 1.0
	v_add_u32_e32 v0, 27, v34
	v_mul_f32_e32 v1, v15, v2
	v_cvt_pk_bf16_f32 v3, v1, s0
	v_ashrrev_i32_e32 v1, 31, v0
	v_lshlrev_b64 v[0:1], 10, v[0:1]
	v_mul_f32_e32 v2, v31, v2
	v_lshl_add_u64 v[0:1], v[32:33], 0, v[0:1]
	v_cvt_pk_bf16_f32 v2, v2, s0
	s_mov_b64 s[0:1], 0
	global_store_short v[0:1], v3, off
	global_store_short v[0:1], v2, off offset:64

.LBB0_947:
	s_or_b64 exec, exec, s[0:1]
	v_add_f32_e32 v0, 0, v110
	v_add_f32_e32 v0, v0, v111
	v_add_f32_e32 v0, v0, v109
	v_cvt_pk_bf16_f32 v110, v110, v111
	v_cvt_pk_bf16_f32 v111, v109, v112
	v_xor_b32_e32 v109, 16, v105
	v_cmp_lt_i32_e64 s[0:1], v109, v106
	v_add_f32_e32 v118, v0, v112
	v_lshl_add_u32 v113, v99, 3, 0
	v_cndmask_b32_e64 v109, v105, v109, s[0:1]
	v_lshlrev_b32_e32 v229, 2, v109
	v_mul_lo_u32 v0, v100, s87
	v_mov_b32_e32 v109, v118
	v_mov_b32_e32 v255, v118
	s_nop 1
	v_permlane16_swap_b32_e32 v109, v255
	s_nop 1
	s_nop 0
	v_add_u32_e32 v0, v113, v0
	ds_write_b64 v0, v[110:111] offset:34816
	v_xor_b32_e32 v110, 8, v105
	v_cmp_lt_i32_e64 s[0:1], v110, v106
	s_waitcnt lgkmcnt(1)
	v_add_f32_e32 v109, v109, v255
	v_cmp_eq_u32_e32 vcc, 0, v99
	v_cndmask_b32_e64 v110, v105, v110, s[0:1]
	v_lshlrev_b32_e32 v230, 2, v110
	s_nop 0
	s_waitcnt lgkmcnt(0)
	v_add_f32_dpp v109, v109, v109 row_ror:8 row_mask:0xf bank_mask:0xf
	v_xor_b32_e32 v110, 4, v105
	v_cmp_lt_i32_e64 s[0:1], v110, v106
	s_nop 1
	v_cndmask_b32_e64 v110, v105, v110, s[0:1]
	v_lshlrev_b32_e32 v231, 2, v110
	v_mov_b32_dpp v110, v109 row_shl:4 row_mask:0xf bank_mask:0x5
	v_mov_b32_dpp v110, v109 row_shr:4 row_mask:0xf bank_mask:0xa
	s_nop 0
	v_add_f32_e32 v109, v109, v110
	v_xor_b32_e32 v110, 2, v105
	v_cmp_lt_i32_e64 s[0:1], v110, v106
	s_nop 1
	v_cndmask_b32_e64 v110, v105, v110, s[0:1]
	v_lshlrev_b32_e32 v232, 2, v110
	s_nop 0
	s_nop 0
	v_add_f32_dpp v109, v109, v109 quad_perm:[2,3,0,1] row_mask:0xf bank_mask:0xf
	v_xor_b32_e32 v110, 1, v105
	v_cmp_lt_i32_e64 s[0:1], v110, v106
	s_nop 1
	v_cndmask_b32_e64 v105, v105, v110, s[0:1]
	v_lshlrev_b32_e32 v233, 2, v105
	v_mov_b32_dpp v105, v109 quad_perm:[1,0,3,2] row_mask:0xf bank_mask:0xf
	s_and_saveexec_b64 s[0:1], vcc
	s_cbranch_execz .LBB0_949
	s_waitcnt lgkmcnt(0)
	v_add_f32_e32 v105, v109, v105
	s_waitcnt vmcnt(0)
	v_sub_f32_e32 v106, v96, v108
	v_add_u32_e32 v109, 0x11c00, v107
	v_mul_f32_e32 v106, 0x3fb8aa3b, v106
	ds_read_b32 v109, v109
	v_exp_f32_e32 v106, v106
	s_waitcnt lgkmcnt(0)
	v_fmac_f32_e32 v105, v106, v109
	v_add_u32_e32 v109, 0x11e00, v107
	ds_write_b32 v109, v105
	v_add_u32_e32 v105, 0x12000, v107
	ds_write_b32 v105, v106
	v_add_u32_e32 v105, 0x11800, v107
	ds_read_b32 v105, v105
	v_add_u32_e32 v106, 0x12200, v107
	s_waitcnt lgkmcnt(0)
	v_add_f32_e32 v105, v108, v105
	v_mul_f32_e32 v105, 0xbfb8aa3b, v105
	v_exp_f32_e32 v105, v105
	ds_write_b32 v106, v105

.LBB0_987:
	s_or_b64 exec, exec, s[68:69]
	v_add_f32_e32 v4, 0, v17
	v_add_f32_e32 v4, v4, v3
	v_add_f32_e32 v4, v4, v19
	v_add_f32_e32 v4, v4, v18
	v_cvt_pk_bf16_f32 v34, v17, v3
	v_mov_b32_e32 v3, v4
	v_mov_b32_e32 v255, v4
	s_nop 1
	v_permlane16_swap_b32_e32 v3, v255
	s_nop 1
	s_nop 0
	v_cvt_pk_bf16_f32 v35, v19, v18
	ds_write_b64 v0, v[34:35] offset:36992
	s_waitcnt lgkmcnt(1)
	v_add_f32_e32 v3, v3, v255
	s_nop 1
	v_mov_b32_dpp v4, v3 row_ror:8 row_mask:0xf bank_mask:0xf
	s_waitcnt lgkmcnt(0)
	v_add_f32_e32 v3, v3, v4
	s_nop 1
	v_mov_b32_dpp v4, v3 row_shl:4 row_mask:0xf bank_mask:0x5
	v_mov_b32_dpp v4, v3 row_shr:4 row_mask:0xf bank_mask:0xa
	s_nop 0
	v_add_f32_e32 v3, v3, v4
	s_nop 1
	v_mov_b32_dpp v4, v3 quad_perm:[2,3,0,1] row_mask:0xf bank_mask:0xf
	s_nop 0
	v_add_f32_e32 v3, v3, v4
	s_nop 1
	v_mov_b32_dpp v4, v3 quad_perm:[1,0,3,2] row_mask:0xf bank_mask:0xf
	s_and_saveexec_b64 s[0:1], vcc
	s_cbranch_execz .LBB0_989
	v_lshl_add_u32 v2, v2, 2, 0
	s_waitcnt lgkmcnt(0)
	v_add_f32_e32 v3, v3, v4
	s_waitcnt vmcnt(0)
	v_sub_f32_e32 v4, v96, v1
	v_add_u32_e32 v17, 0x11c00, v2
	v_mul_f32_e32 v4, 0x3fb8aa3b, v4
	ds_read_b32 v17, v17
	v_exp_f32_e32 v4, v4
	s_waitcnt lgkmcnt(0)
	v_fmac_f32_e32 v3, v4, v17
	v_add_u32_e32 v17, 0x11e00, v2
	ds_write_b32 v17, v3
	v_add_u32_e32 v3, 0x12000, v2
	ds_write_b32 v3, v4
	v_add_u32_e32 v3, 0x11800, v2
	ds_read_b32 v3, v3
	v_add_u32_e32 v2, 0x12200, v2
	s_waitcnt lgkmcnt(0)
	v_add_f32_e32 v1, v1, v3
	v_mul_f32_e32 v1, 0xbfb8aa3b, v1
	v_exp_f32_e32 v1, v1
	ds_write_b32 v2, v1

.LBB0_997:
	s_or_b64 exec, exec, s[68:69]
	v_add_f32_e32 v5, 0, v4
	v_add_f32_e32 v5, v5, v3
	v_add_f32_e32 v5, v5, v18
	v_add_f32_e32 v19, v5, v17
	v_cvt_pk_bf16_f32 v4, v4, v3
	v_mov_b32_e32 v3, v19
	v_mov_b32_e32 v255, v19
	s_nop 1
	v_permlane16_swap_b32_e32 v3, v255
	s_nop 1
	s_nop 0
	v_cvt_pk_bf16_f32 v5, v18, v17
	ds_write_b64 v0, v[4:5] offset:37264
	s_waitcnt lgkmcnt(1)
	v_add_f32_e32 v3, v3, v255
	s_nop 1
	v_mov_b32_dpp v4, v3 row_ror:8 row_mask:0xf bank_mask:0xf
	s_waitcnt lgkmcnt(0)
	v_add_f32_e32 v3, v3, v4
	s_nop 1
	v_mov_b32_dpp v4, v3 row_shl:4 row_mask:0xf bank_mask:0x5
	v_mov_b32_dpp v4, v3 row_shr:4 row_mask:0xf bank_mask:0xa
	s_nop 0
	v_add_f32_e32 v3, v3, v4
	s_nop 1
	v_mov_b32_dpp v4, v3 quad_perm:[2,3,0,1] row_mask:0xf bank_mask:0xf
	s_nop 0
	v_add_f32_e32 v3, v3, v4
	s_nop 1
	v_mov_b32_dpp v4, v3 quad_perm:[1,0,3,2] row_mask:0xf bank_mask:0xf
	s_and_saveexec_b64 s[0:1], vcc
	s_cbranch_execz .LBB0_999
	v_lshl_add_u32 v2, v2, 2, 0
	s_waitcnt lgkmcnt(0)
	v_add_f32_e32 v3, v3, v4
	s_waitcnt vmcnt(0)
	v_sub_f32_e32 v4, v96, v1
	v_add_u32_e32 v5, 0x11c00, v2
	v_mul_f32_e32 v4, 0x3fb8aa3b, v4
	ds_read_b32 v5, v5
	v_exp_f32_e32 v4, v4
	s_waitcnt lgkmcnt(0)
	v_fmac_f32_e32 v3, v4, v5
	v_add_u32_e32 v5, 0x11e00, v2
	ds_write_b32 v5, v3
	v_add_u32_e32 v3, 0x12000, v2
	ds_write_b32 v3, v4
	v_add_u32_e32 v3, 0x11800, v2
	ds_read_b32 v3, v3
	v_add_u32_e32 v2, 0x12200, v2
	s_waitcnt lgkmcnt(0)
	v_add_f32_e32 v1, v1, v3
	v_mul_f32_e32 v1, 0xbfb8aa3b, v1
	v_exp_f32_e32 v1, v1
	ds_write_b32 v2, v1

.LBB0_1007:
	s_or_b64 exec, exec, s[68:69]
	v_add_f32_e32 v6, 0, v4
	v_add_f32_e32 v6, v6, v3
	v_add_f32_e32 v6, v6, v17
	v_add_f32_e32 v6, v6, v5
	v_cvt_pk_bf16_f32 v4, v4, v3
	v_mov_b32_e32 v3, v6
	v_mov_b32_e32 v255, v6
	s_nop 1
	v_permlane16_swap_b32_e32 v3, v255
	s_nop 1
	s_nop 0
	v_cvt_pk_bf16_f32 v5, v17, v5
	ds_write_b64 v0, v[4:5] offset:37536
	s_waitcnt lgkmcnt(1)
	v_add_f32_e32 v3, v3, v255
	s_nop 1
	v_mov_b32_dpp v4, v3 row_ror:8 row_mask:0xf bank_mask:0xf
	s_waitcnt lgkmcnt(0)
	v_add_f32_e32 v3, v3, v4
	s_nop 1
	v_mov_b32_dpp v4, v3 row_shl:4 row_mask:0xf bank_mask:0x5
	v_mov_b32_dpp v4, v3 row_shr:4 row_mask:0xf bank_mask:0xa
	s_nop 0
	v_add_f32_e32 v3, v3, v4
	s_nop 1
	v_mov_b32_dpp v4, v3 quad_perm:[2,3,0,1] row_mask:0xf bank_mask:0xf
	s_nop 0
	v_add_f32_e32 v3, v3, v4
	s_nop 1
	v_mov_b32_dpp v4, v3 quad_perm:[1,0,3,2] row_mask:0xf bank_mask:0xf
	s_and_saveexec_b64 s[0:1], vcc
	s_cbranch_execz .LBB0_1009
	v_lshl_add_u32 v2, v2, 2, 0
	s_waitcnt lgkmcnt(0)
	v_add_f32_e32 v3, v3, v4
	s_waitcnt vmcnt(0)
	v_sub_f32_e32 v4, v96, v1
	v_add_u32_e32 v5, 0x11c00, v2
	v_mul_f32_e32 v4, 0x3fb8aa3b, v4
	ds_read_b32 v5, v5
	v_exp_f32_e32 v4, v4
	s_waitcnt lgkmcnt(0)
	v_fmac_f32_e32 v3, v4, v5
	v_add_u32_e32 v5, 0x11e00, v2
	ds_write_b32 v5, v3
	v_add_u32_e32 v3, 0x12000, v2
	ds_write_b32 v3, v4
	v_add_u32_e32 v3, 0x11800, v2
	ds_read_b32 v3, v3
	v_add_u32_e32 v2, 0x12200, v2
	s_waitcnt lgkmcnt(0)
	v_add_f32_e32 v1, v1, v3
	v_mul_f32_e32 v1, 0xbfb8aa3b, v1
	v_exp_f32_e32 v1, v1
	ds_write_b32 v2, v1

.LBB0_1017:
	s_or_b64 exec, exec, s[68:69]
	v_add_f32_e32 v7, 0, v4
	v_add_f32_e32 v7, v7, v3
	v_add_f32_e32 v7, v7, v6
	v_add_f32_e32 v7, v7, v5
	v_cvt_pk_bf16_f32 v4, v4, v3
	v_mov_b32_e32 v3, v7
	v_mov_b32_e32 v255, v7
	s_nop 1
	v_permlane16_swap_b32_e32 v3, v255
	s_nop 1
	s_nop 0
	v_cvt_pk_bf16_f32 v5, v6, v5
	ds_write_b64 v0, v[4:5] offset:37808
	s_waitcnt lgkmcnt(1)
	v_add_f32_e32 v3, v3, v255
	s_nop 1
	v_mov_b32_dpp v4, v3 row_ror:8 row_mask:0xf bank_mask:0xf
	s_waitcnt lgkmcnt(0)
	v_add_f32_e32 v3, v3, v4
	s_nop 1
	v_mov_b32_dpp v4, v3 row_shl:4 row_mask:0xf bank_mask:0x5
	v_mov_b32_dpp v4, v3 row_shr:4 row_mask:0xf bank_mask:0xa
	s_nop 0
	v_add_f32_e32 v3, v3, v4
	s_nop 1
	v_mov_b32_dpp v4, v3 quad_perm:[2,3,0,1] row_mask:0xf bank_mask:0xf
	s_nop 0
	v_add_f32_e32 v3, v3, v4
	s_nop 1
	v_mov_b32_dpp v4, v3 quad_perm:[1,0,3,2] row_mask:0xf bank_mask:0xf
	s_and_saveexec_b64 s[0:1], vcc
	s_cbranch_execz .LBB0_1019
	v_lshl_add_u32 v2, v2, 2, 0
	s_waitcnt lgkmcnt(0)
	v_add_f32_e32 v3, v3, v4
	s_waitcnt vmcnt(0)
	v_sub_f32_e32 v4, v96, v1
	v_add_u32_e32 v5, 0x11c00, v2
	v_mul_f32_e32 v4, 0x3fb8aa3b, v4
	ds_read_b32 v5, v5
	v_exp_f32_e32 v4, v4
	s_waitcnt lgkmcnt(0)
	v_fmac_f32_e32 v3, v4, v5
	v_add_u32_e32 v5, 0x11e00, v2
	ds_write_b32 v5, v3
	v_add_u32_e32 v3, 0x12000, v2
	ds_write_b32 v3, v4
	v_add_u32_e32 v3, 0x11800, v2
	ds_read_b32 v3, v3
	v_add_u32_e32 v2, 0x12200, v2
	s_waitcnt lgkmcnt(0)
	v_add_f32_e32 v1, v1, v3
	v_mul_f32_e32 v1, 0xbfb8aa3b, v1
	v_exp_f32_e32 v1, v1
	ds_write_b32 v2, v1

.LBB0_1027:
	s_or_b64 exec, exec, s[68:69]
	v_add_f32_e32 v7, 0, v4
	v_add_f32_e32 v7, v7, v3
	v_add_f32_e32 v7, v7, v6
	v_add_f32_e32 v7, v7, v5
	v_cvt_pk_bf16_f32 v4, v4, v3
	v_mov_b32_e32 v3, v7
	v_mov_b32_e32 v255, v7
	s_nop 1
	v_permlane16_swap_b32_e32 v3, v255
	s_nop 1
	s_nop 0
	v_cvt_pk_bf16_f32 v5, v6, v5
	ds_write_b64 v0, v[4:5] offset:39168
	s_waitcnt lgkmcnt(1)
	v_add_f32_e32 v3, v3, v255
	s_nop 1
	v_mov_b32_dpp v4, v3 row_ror:8 row_mask:0xf bank_mask:0xf
	s_waitcnt lgkmcnt(0)
	v_add_f32_e32 v3, v3, v4
	s_nop 1
	v_mov_b32_dpp v4, v3 row_shl:4 row_mask:0xf bank_mask:0x5
	v_mov_b32_dpp v4, v3 row_shr:4 row_mask:0xf bank_mask:0xa
	s_nop 0
	v_add_f32_e32 v3, v3, v4
	s_nop 1
	v_mov_b32_dpp v4, v3 quad_perm:[2,3,0,1] row_mask:0xf bank_mask:0xf
	s_nop 0
	v_add_f32_e32 v3, v3, v4
	s_nop 1
	v_mov_b32_dpp v4, v3 quad_perm:[1,0,3,2] row_mask:0xf bank_mask:0xf
	s_and_saveexec_b64 s[0:1], vcc
	s_cbranch_execz .LBB0_1029
	v_lshl_add_u32 v2, v2, 2, 0
	s_waitcnt lgkmcnt(0)
	v_add_f32_e32 v3, v3, v4
	s_waitcnt vmcnt(0)
	v_sub_f32_e32 v4, v96, v1
	v_add_u32_e32 v5, 0x11c00, v2
	v_mul_f32_e32 v4, 0x3fb8aa3b, v4
	ds_read_b32 v5, v5
	v_exp_f32_e32 v4, v4
	s_waitcnt lgkmcnt(0)
	v_fmac_f32_e32 v3, v4, v5
	v_add_u32_e32 v5, 0x11e00, v2
	ds_write_b32 v5, v3
	v_add_u32_e32 v3, 0x12000, v2
	ds_write_b32 v3, v4
	v_add_u32_e32 v3, 0x11800, v2
	ds_read_b32 v3, v3
	v_add_u32_e32 v2, 0x12200, v2
	s_waitcnt lgkmcnt(0)
	v_add_f32_e32 v1, v1, v3
	v_mul_f32_e32 v1, 0xbfb8aa3b, v1
	v_exp_f32_e32 v1, v1
	ds_write_b32 v2, v1

.LBB0_1037:
	s_or_b64 exec, exec, s[68:69]
	v_add_f32_e32 v7, 0, v4
	v_add_f32_e32 v7, v7, v3
	v_add_f32_e32 v7, v7, v6
	v_add_f32_e32 v7, v7, v5
	v_cvt_pk_bf16_f32 v4, v4, v3
	v_mov_b32_e32 v3, v7
	v_mov_b32_e32 v255, v7
	s_nop 1
	v_permlane16_swap_b32_e32 v3, v255
	s_nop 1
	s_nop 0
	v_cvt_pk_bf16_f32 v5, v6, v5
	ds_write_b64 v0, v[4:5] offset:39440
	s_waitcnt lgkmcnt(1)
	v_add_f32_e32 v3, v3, v255
	s_nop 1
	v_mov_b32_dpp v4, v3 row_ror:8 row_mask:0xf bank_mask:0xf
	s_waitcnt lgkmcnt(0)
	v_add_f32_e32 v3, v3, v4
	s_nop 1
	v_mov_b32_dpp v4, v3 row_shl:4 row_mask:0xf bank_mask:0x5
	v_mov_b32_dpp v4, v3 row_shr:4 row_mask:0xf bank_mask:0xa
	s_nop 0
	v_add_f32_e32 v3, v3, v4
	s_nop 1
	v_mov_b32_dpp v4, v3 quad_perm:[2,3,0,1] row_mask:0xf bank_mask:0xf
	s_nop 0
	v_add_f32_e32 v3, v3, v4
	s_nop 1
	v_mov_b32_dpp v4, v3 quad_perm:[1,0,3,2] row_mask:0xf bank_mask:0xf
	s_and_saveexec_b64 s[0:1], vcc
	s_cbranch_execz .LBB0_1039
	v_lshl_add_u32 v2, v2, 2, 0
	s_waitcnt lgkmcnt(0)
	v_add_f32_e32 v3, v3, v4
	s_waitcnt vmcnt(0)
	v_sub_f32_e32 v4, v96, v1
	v_add_u32_e32 v5, 0x11c00, v2
	v_mul_f32_e32 v4, 0x3fb8aa3b, v4
	ds_read_b32 v5, v5
	v_exp_f32_e32 v4, v4
	s_waitcnt lgkmcnt(0)
	v_fmac_f32_e32 v3, v4, v5
	v_add_u32_e32 v5, 0x11e00, v2
	ds_write_b32 v5, v3
	v_add_u32_e32 v3, 0x12000, v2
	ds_write_b32 v3, v4
	v_add_u32_e32 v3, 0x11800, v2
	ds_read_b32 v3, v3
	v_add_u32_e32 v2, 0x12200, v2
	s_waitcnt lgkmcnt(0)
	v_add_f32_e32 v1, v1, v3
	v_mul_f32_e32 v1, 0xbfb8aa3b, v1
	v_exp_f32_e32 v1, v1
	ds_write_b32 v2, v1

.LBB0_1047:
	s_or_b64 exec, exec, s[68:69]
	v_add_f32_e32 v7, 0, v4
	v_add_f32_e32 v7, v7, v3
	v_add_f32_e32 v7, v7, v6
	v_add_f32_e32 v7, v7, v5
	v_cvt_pk_bf16_f32 v4, v4, v3
	v_mov_b32_e32 v3, v7
	v_mov_b32_e32 v255, v7
	s_nop 1
	v_permlane16_swap_b32_e32 v3, v255
	s_nop 1
	s_nop 0
	v_cvt_pk_bf16_f32 v5, v6, v5
	ds_write_b64 v0, v[4:5] offset:39712
	s_waitcnt lgkmcnt(1)
	v_add_f32_e32 v3, v3, v255
	s_nop 1
	v_mov_b32_dpp v4, v3 row_ror:8 row_mask:0xf bank_mask:0xf
	s_waitcnt lgkmcnt(0)
	v_add_f32_e32 v3, v3, v4
	s_nop 1
	v_mov_b32_dpp v4, v3 row_shl:4 row_mask:0xf bank_mask:0x5
	v_mov_b32_dpp v4, v3 row_shr:4 row_mask:0xf bank_mask:0xa
	s_nop 0
	v_add_f32_e32 v3, v3, v4
	s_nop 1
	v_mov_b32_dpp v4, v3 quad_perm:[2,3,0,1] row_mask:0xf bank_mask:0xf
	s_nop 0
	v_add_f32_e32 v3, v3, v4
	s_nop 1
	v_mov_b32_dpp v4, v3 quad_perm:[1,0,3,2] row_mask:0xf bank_mask:0xf
	s_and_saveexec_b64 s[0:1], vcc
	s_cbranch_execz .LBB0_1049
	v_lshl_add_u32 v2, v2, 2, 0
	s_waitcnt lgkmcnt(0)
	v_add_f32_e32 v3, v3, v4
	s_waitcnt vmcnt(0)
	v_sub_f32_e32 v4, v96, v1
	v_add_u32_e32 v5, 0x11c00, v2
	v_mul_f32_e32 v4, 0x3fb8aa3b, v4
	ds_read_b32 v5, v5
	v_exp_f32_e32 v4, v4
	s_waitcnt lgkmcnt(0)
	v_fmac_f32_e32 v3, v4, v5
	v_add_u32_e32 v5, 0x11e00, v2
	ds_write_b32 v5, v3
	v_add_u32_e32 v3, 0x12000, v2
	ds_write_b32 v3, v4
	v_add_u32_e32 v3, 0x11800, v2
	ds_read_b32 v3, v3
	v_add_u32_e32 v2, 0x12200, v2
	s_waitcnt lgkmcnt(0)
	v_add_f32_e32 v1, v1, v3
	v_mul_f32_e32 v1, 0xbfb8aa3b, v1
	v_exp_f32_e32 v1, v1
	ds_write_b32 v2, v1

.LBB0_1057:
	s_or_b64 exec, exec, s[68:69]
	v_add_f32_e32 v7, 0, v4
	v_add_f32_e32 v7, v7, v3
	v_add_f32_e32 v7, v7, v6
	v_add_f32_e32 v7, v7, v5
	v_cvt_pk_bf16_f32 v4, v4, v3
	v_mov_b32_e32 v3, v7
	v_mov_b32_e32 v255, v7
	s_nop 1
	v_permlane16_swap_b32_e32 v3, v255
	s_nop 1
	s_nop 0
	v_cvt_pk_bf16_f32 v5, v6, v5
	ds_write_b64 v0, v[4:5] offset:39984
	s_waitcnt lgkmcnt(1)
	v_add_f32_e32 v3, v3, v255
	s_nop 1
	v_mov_b32_dpp v4, v3 row_ror:8 row_mask:0xf bank_mask:0xf
	s_waitcnt lgkmcnt(0)
	v_add_f32_e32 v3, v3, v4
	s_nop 1
	v_mov_b32_dpp v4, v3 row_shl:4 row_mask:0xf bank_mask:0x5
	v_mov_b32_dpp v4, v3 row_shr:4 row_mask:0xf bank_mask:0xa
	s_nop 0
	v_add_f32_e32 v3, v3, v4
	s_nop 1
	v_mov_b32_dpp v4, v3 quad_perm:[2,3,0,1] row_mask:0xf bank_mask:0xf
	s_nop 0
	v_add_f32_e32 v3, v3, v4
	s_nop 1
	v_mov_b32_dpp v4, v3 quad_perm:[1,0,3,2] row_mask:0xf bank_mask:0xf
	s_and_saveexec_b64 s[0:1], vcc
	s_cbranch_execz .LBB0_1059
	v_lshl_add_u32 v2, v2, 2, 0
	s_waitcnt lgkmcnt(0)
	v_add_f32_e32 v3, v3, v4
	s_waitcnt vmcnt(0)
	v_sub_f32_e32 v4, v96, v1
	v_add_u32_e32 v5, 0x11c00, v2
	v_mul_f32_e32 v4, 0x3fb8aa3b, v4
	ds_read_b32 v5, v5
	v_exp_f32_e32 v4, v4
	s_waitcnt lgkmcnt(0)
	v_fmac_f32_e32 v3, v4, v5
	v_add_u32_e32 v5, 0x11e00, v2
	ds_write_b32 v5, v3
	v_add_u32_e32 v3, 0x12000, v2
	ds_write_b32 v3, v4
	v_add_u32_e32 v3, 0x11800, v2
	ds_read_b32 v3, v3
	v_add_u32_e32 v2, 0x12200, v2
	s_waitcnt lgkmcnt(0)
	v_add_f32_e32 v1, v1, v3
	v_mul_f32_e32 v1, 0xbfb8aa3b, v1
	v_exp_f32_e32 v1, v1
	ds_write_b32 v2, v1

.LBB0_1067:
	s_or_b64 exec, exec, s[68:69]
	v_add_f32_e32 v7, 0, v4
	v_add_f32_e32 v7, v7, v3
	v_add_f32_e32 v7, v7, v6
	v_add_f32_e32 v7, v7, v5
	v_cvt_pk_bf16_f32 v4, v4, v3
	v_mov_b32_e32 v3, v7
	v_mov_b32_e32 v255, v7
	s_nop 1
	v_permlane16_swap_b32_e32 v3, v255
	s_nop 1
	s_nop 0
	v_cvt_pk_bf16_f32 v5, v6, v5
	ds_write_b64 v0, v[4:5] offset:41344
	s_waitcnt lgkmcnt(1)
	v_add_f32_e32 v3, v3, v255
	s_nop 1
	v_mov_b32_dpp v4, v3 row_ror:8 row_mask:0xf bank_mask:0xf
	s_waitcnt lgkmcnt(0)
	v_add_f32_e32 v3, v3, v4
	s_nop 1
	v_mov_b32_dpp v4, v3 row_shl:4 row_mask:0xf bank_mask:0x5
	v_mov_b32_dpp v4, v3 row_shr:4 row_mask:0xf bank_mask:0xa
	s_nop 0
	v_add_f32_e32 v3, v3, v4
	s_nop 1
	v_mov_b32_dpp v4, v3 quad_perm:[2,3,0,1] row_mask:0xf bank_mask:0xf
	s_nop 0
	v_add_f32_e32 v3, v3, v4
	s_nop 1
	v_mov_b32_dpp v4, v3 quad_perm:[1,0,3,2] row_mask:0xf bank_mask:0xf
	s_and_saveexec_b64 s[0:1], vcc
	s_cbranch_execz .LBB0_1069
	v_lshl_add_u32 v2, v2, 2, 0
	s_waitcnt lgkmcnt(0)
	v_add_f32_e32 v3, v3, v4
	s_waitcnt vmcnt(0)
	v_sub_f32_e32 v4, v96, v1
	v_add_u32_e32 v5, 0x11c00, v2
	v_mul_f32_e32 v4, 0x3fb8aa3b, v4
	ds_read_b32 v5, v5
	v_exp_f32_e32 v4, v4
	s_waitcnt lgkmcnt(0)
	v_fmac_f32_e32 v3, v4, v5
	v_add_u32_e32 v5, 0x11e00, v2
	ds_write_b32 v5, v3
	v_add_u32_e32 v3, 0x12000, v2
	ds_write_b32 v3, v4
	v_add_u32_e32 v3, 0x11800, v2
	ds_read_b32 v3, v3
	v_add_u32_e32 v2, 0x12200, v2
	s_waitcnt lgkmcnt(0)
	v_add_f32_e32 v1, v1, v3
	v_mul_f32_e32 v1, 0xbfb8aa3b, v1
	v_exp_f32_e32 v1, v1
	ds_write_b32 v2, v1

.LBB0_1077:
	s_or_b64 exec, exec, s[68:69]
	v_add_f32_e32 v7, 0, v4
	v_add_f32_e32 v7, v7, v3
	v_add_f32_e32 v7, v7, v6
	v_add_f32_e32 v7, v7, v5
	v_cvt_pk_bf16_f32 v4, v4, v3
	v_mov_b32_e32 v3, v7
	v_mov_b32_e32 v255, v7
	s_nop 1
	v_permlane16_swap_b32_e32 v3, v255
	s_nop 1
	s_nop 0
	v_cvt_pk_bf16_f32 v5, v6, v5
	ds_write_b64 v0, v[4:5] offset:41616
	s_waitcnt lgkmcnt(1)
	v_add_f32_e32 v3, v3, v255
	s_nop 1
	v_mov_b32_dpp v4, v3 row_ror:8 row_mask:0xf bank_mask:0xf
	s_waitcnt lgkmcnt(0)
	v_add_f32_e32 v3, v3, v4
	s_nop 1
	v_mov_b32_dpp v4, v3 row_shl:4 row_mask:0xf bank_mask:0x5
	v_mov_b32_dpp v4, v3 row_shr:4 row_mask:0xf bank_mask:0xa
	s_nop 0
	v_add_f32_e32 v3, v3, v4
	s_nop 1
	v_mov_b32_dpp v4, v3 quad_perm:[2,3,0,1] row_mask:0xf bank_mask:0xf
	s_nop 0
	v_add_f32_e32 v3, v3, v4
	s_nop 1
	v_mov_b32_dpp v4, v3 quad_perm:[1,0,3,2] row_mask:0xf bank_mask:0xf
	s_and_saveexec_b64 s[0:1], vcc
	s_cbranch_execz .LBB0_1079
	v_lshl_add_u32 v2, v2, 2, 0
	s_waitcnt lgkmcnt(0)
	v_add_f32_e32 v3, v3, v4
	s_waitcnt vmcnt(0)
	v_sub_f32_e32 v4, v96, v1
	v_add_u32_e32 v5, 0x11c00, v2
	v_mul_f32_e32 v4, 0x3fb8aa3b, v4
	ds_read_b32 v5, v5
	v_exp_f32_e32 v4, v4
	s_waitcnt lgkmcnt(0)
	v_fmac_f32_e32 v3, v4, v5
	v_add_u32_e32 v5, 0x11e00, v2
	ds_write_b32 v5, v3
	v_add_u32_e32 v3, 0x12000, v2
	ds_write_b32 v3, v4
	v_add_u32_e32 v3, 0x11800, v2
	ds_read_b32 v3, v3
	v_add_u32_e32 v2, 0x12200, v2
	s_waitcnt lgkmcnt(0)
	v_add_f32_e32 v1, v1, v3
	v_mul_f32_e32 v1, 0xbfb8aa3b, v1
	v_exp_f32_e32 v1, v1
	ds_write_b32 v2, v1

.LBB0_1087:
	s_or_b64 exec, exec, s[68:69]
	v_add_f32_e32 v7, 0, v4
	v_add_f32_e32 v7, v7, v3
	v_add_f32_e32 v7, v7, v6
	v_add_f32_e32 v7, v7, v5
	v_cvt_pk_bf16_f32 v4, v4, v3
	v_mov_b32_e32 v3, v7
	v_mov_b32_e32 v255, v7
	s_nop 1
	v_permlane16_swap_b32_e32 v3, v255
	s_nop 1
	s_nop 0
	v_cvt_pk_bf16_f32 v5, v6, v5
	ds_write_b64 v0, v[4:5] offset:41888
	s_waitcnt lgkmcnt(1)
	v_add_f32_e32 v3, v3, v255
	s_nop 1
	v_mov_b32_dpp v4, v3 row_ror:8 row_mask:0xf bank_mask:0xf
	s_waitcnt lgkmcnt(0)
	v_add_f32_e32 v3, v3, v4
	s_nop 1
	v_mov_b32_dpp v4, v3 row_shl:4 row_mask:0xf bank_mask:0x5
	v_mov_b32_dpp v4, v3 row_shr:4 row_mask:0xf bank_mask:0xa
	s_nop 0
	v_add_f32_e32 v3, v3, v4
	s_nop 1
	v_mov_b32_dpp v4, v3 quad_perm:[2,3,0,1] row_mask:0xf bank_mask:0xf
	s_nop 0
	v_add_f32_e32 v3, v3, v4
	s_nop 1
	v_mov_b32_dpp v4, v3 quad_perm:[1,0,3,2] row_mask:0xf bank_mask:0xf
	s_and_saveexec_b64 s[0:1], vcc
	s_cbranch_execz .LBB0_1089
	v_lshl_add_u32 v2, v2, 2, 0
	s_waitcnt lgkmcnt(0)
	v_add_f32_e32 v3, v3, v4
	s_waitcnt vmcnt(0)
	v_sub_f32_e32 v4, v96, v1
	v_add_u32_e32 v5, 0x11c00, v2
	v_mul_f32_e32 v4, 0x3fb8aa3b, v4
	ds_read_b32 v5, v5
	v_exp_f32_e32 v4, v4
	s_waitcnt lgkmcnt(0)
	v_fmac_f32_e32 v3, v4, v5
	v_add_u32_e32 v5, 0x11e00, v2
	ds_write_b32 v5, v3
	v_add_u32_e32 v3, 0x12000, v2
	ds_write_b32 v3, v4
	v_add_u32_e32 v3, 0x11800, v2
	ds_read_b32 v3, v3
	v_add_u32_e32 v2, 0x12200, v2
	s_waitcnt lgkmcnt(0)
	v_add_f32_e32 v1, v1, v3
	v_mul_f32_e32 v1, 0xbfb8aa3b, v1
	v_exp_f32_e32 v1, v1
	ds_write_b32 v2, v1

.LBB0_1097:
	s_or_b64 exec, exec, s[6:7]
	v_add_f32_e32 v7, 0, v4
	v_add_f32_e32 v7, v7, v3
	v_add_f32_e32 v7, v7, v6
	v_add_f32_e32 v7, v7, v5
	v_cvt_pk_bf16_f32 v4, v4, v3
	v_cvt_pk_bf16_f32 v5, v6, v5
	ds_write_b64 v0, v[4:5] offset:42160
	v_mov_b32_e32 v0, v7
	v_mov_b32_e32 v255, v7
	s_nop 1
	v_permlane16_swap_b32_e32 v0, v255
	s_nop 1
	s_nop 0
	s_waitcnt lgkmcnt(0)
	v_add_f32_e32 v0, v0, v255
	s_nop 1
	v_mov_b32_dpp v3, v0 row_ror:8 row_mask:0xf bank_mask:0xf
	s_nop 0
	v_add_f32_e32 v0, v0, v3
	s_nop 1
	v_mov_b32_dpp v3, v0 row_shl:4 row_mask:0xf bank_mask:0x5
	v_mov_b32_dpp v3, v0 row_shr:4 row_mask:0xf bank_mask:0xa
	s_nop 0
	v_add_f32_e32 v0, v0, v3
	s_nop 1
	v_mov_b32_dpp v3, v0 quad_perm:[2,3,0,1] row_mask:0xf bank_mask:0xf
	s_nop 0
	v_add_f32_e32 v0, v0, v3
	s_nop 1
	v_mov_b32_dpp v3, v0 quad_perm:[1,0,3,2] row_mask:0xf bank_mask:0xf
	s_and_saveexec_b64 s[0:1], vcc
	s_cbranch_execz .LBB0_1099
	v_lshl_add_u32 v2, v2, 2, 0
	s_waitcnt lgkmcnt(0)
	v_add_f32_e32 v0, v0, v3
	s_waitcnt vmcnt(0)
	v_sub_f32_e32 v3, v96, v1
	v_add_u32_e32 v4, 0x11c00, v2
	v_mul_f32_e32 v3, 0x3fb8aa3b, v3
	ds_read_b32 v4, v4
	v_exp_f32_e32 v3, v3
	s_waitcnt lgkmcnt(0)
	v_fmac_f32_e32 v0, v3, v4
	v_add_u32_e32 v4, 0x11e00, v2
	ds_write_b32 v4, v0
	v_add_u32_e32 v0, 0x12000, v2
	ds_write_b32 v0, v3
	v_add_u32_e32 v0, 0x11800, v2
	ds_read_b32 v0, v0
	s_waitcnt lgkmcnt(0)
	v_add_f32_e32 v0, v1, v0
	v_mul_f32_e32 v0, 0xbfb8aa3b, v0
	v_exp_f32_e32 v0, v0
	v_add_u32_e32 v1, 0x12200, v2
	ds_write_b32 v1, v0

.LBB0_1107:
	ds_read_b128 v[100:103], v98
	ds_read_b128 v[104:107], v96
	s_add_i32 s0, s0, 32
	s_cmpk_lt_u32 s0, 0x70
	s_waitcnt lgkmcnt(0)
	v_mfma_f32_32x32x16_bf16 v[0:15], v[100:103], v[104:107], v[0:15]
	ds_read_b128 v[104:107], v96 offset:8704
	s_waitcnt lgkmcnt(0)
	v_mfma_f32_32x32x16_bf16 v[16:31], v[100:103], v[104:107], v[16:31]
	ds_read_b128 v[104:107], v96 offset:17408
	s_waitcnt lgkmcnt(0)
	v_mfma_f32_32x32x16_bf16 v[32:47], v[100:103], v[104:107], v[32:47]
	ds_read_b128 v[104:107], v96 offset:26112
	s_waitcnt lgkmcnt(0)
	v_mfma_f32_32x32x16_bf16 v[48:63], v[100:103], v[104:107], v[48:63]
	ds_read_b128 v[100:103], v98 offset:32
	ds_read_b128 v[104:107], v96 offset:32
	v_add_u32_e32 v98, 64, v98
	s_waitcnt lgkmcnt(0)
	v_mfma_f32_32x32x16_bf16 v[0:15], v[100:103], v[104:107], v[0:15]
	ds_read_b128 v[104:107], v96 offset:8736
	s_waitcnt lgkmcnt(0)
	v_mfma_f32_32x32x16_bf16 v[16:31], v[100:103], v[104:107], v[16:31]
	ds_read_b128 v[104:107], v96 offset:17440
	s_waitcnt lgkmcnt(0)
	v_mfma_f32_32x32x16_bf16 v[32:47], v[100:103], v[104:107], v[32:47]
	ds_read_b128 v[104:107], v96 offset:26144
	v_add_u32_e32 v96, 64, v96
	s_waitcnt lgkmcnt(0)
	v_mfma_f32_32x32x16_bf16 v[48:63], v[100:103], v[104:107], v[48:63]
	s_cbranch_scc1 .LBB0_1107
	v_mov_b32_e32 v96, v128
	s_mov_b64 s[0:1], -1
	v_ashrrev_i32_e32 v98, 3, v96
	v_and_b32_e32 v98, -4, v98
	v_and_b32_e32 v103, 31, v96
	v_add_u32_e32 v105, v98, v129
	v_lshlrev_b32_e32 v96, 2, v103
	v_lshl_add_u64 v[98:99], s[56:57], 0, v[96:97]
	v_add_u32_e32 v100, s61, v105
	v_or_b32_e32 v96, 1, v105
	v_or_b32_e32 v102, 2, v105
	s_andn2_b64 vcc, exec, s[54:55]
	v_lshlrev_b32_e32 v237, 2, v105
	v_ashrrev_i32_e32 v101, 31, v100
	v_lshlrev_b32_e32 v236, 2, v96
	v_add_u32_e32 v104, s61, v96
	v_lshlrev_b32_e32 v235, 2, v102
	v_add_u32_e32 v102, s61, v102
	v_or_b32_e32 v234, 3, v105
	s_cbranch_vccnz .LBB0_1110
	s_add_i32 s0, 0, 0x11e00
	s_add_i32 s1, 0, 0x12200
	v_add_u32_e32 v238, s0, v237
	v_add_u32_e32 v239, s1, v237
	ds_read_b32 v96, v238
	ds_read_b32 v105, v239
	v_mov_b32_e32 v110, v0
	v_mov_b32_e32 v111, v16
	v_or_b32_e32 v103, s75, v103
	s_waitcnt lgkmcnt(1)
	v_max_f32_e64 v96, |v96|, |v96|
	s_waitcnt lgkmcnt(0)
	v_max_f32_e32 v105, v105, v105
	v_max_f32_e32 v96, v96, v105
	v_div_scale_f32 v105, s[6:7], v96, v96, 1.0
	v_rcp_f32_e32 v106, v105
	v_readlane_b32 s6, v249, 7
	v_readlane_b32 s7, v249, 8
	v_readlane_b32 s12, v251, 20
	v_fma_f32 v107, -v105, v106, 1.0
	v_fmac_f32_e32 v106, v107, v106
	v_div_scale_f32 v107, vcc, 1.0, v96, 1.0
	v_mul_f32_e32 v108, v107, v106
	v_fma_f32 v109, -v105, v108, v107
	v_fmac_f32_e32 v108, v109, v106
	v_fma_f32 v105, -v105, v108, v107
	v_div_fmas_f32 v105, v105, v106, v108
	v_lshlrev_b64 v[106:107], 11, v[100:101]
	v_lshl_add_u64 v[106:107], v[98:99], 0, v[106:107]
	global_load_dword v108, v[106:107], off
	global_load_dword v109, v[106:107], off offset:128
	global_load_dword v112, v[106:107], off offset:256
	global_load_dword v113, v[106:107], off offset:384
	v_div_fixup_f32 v96, v105, v96, 1.0
	v_mov_b32_e32 v106, v32
	v_mov_b32_e32 v107, v48
	v_readlane_b32 s18, v251, 26
	v_readlane_b32 s19, v251, 27
	v_readlane_b32 s14, v251, 22
	v_readlane_b32 s15, v251, 23
	v_readlane_b32 s16, v251, 24
	v_readlane_b32 s17, v251, 25
	v_readlane_b32 s20, v251, 28
	v_readlane_b32 s21, v251, 29
	v_readlane_b32 s22, v251, 30
	v_readlane_b32 s23, v251, 31
	v_readlane_b32 s25, v251, 33
	v_readlane_b32 s14, v248, 4
	s_mov_b64 s[16:17], s[82:83]
	s_mov_b32 s25, 0x85000
	s_mov_b32 s23, 0x59000
	s_mov_b32 s22, 0x2d000
	s_mov_b32 s21, 0x84000
	s_mov_b32 s20, 0x58000
	s_movk_i32 s29, 0x47ff
	s_mov_b32 s28, 0x4800000
	v_readlane_b32 s15, v248, 5
	v_readlane_b32 s13, v251, 21
	v_readlane_b32 s24, v251, 32
	v_readlane_b32 s26, v251, 34
	v_readlane_b32 s27, v251, 35
	s_waitcnt vmcnt(2)
	v_pk_fma_f32 v[110:111], v[110:111], v[96:97], v[108:109] op_sel_hi:[1,0,1]
	s_nop 0
	v_pk_mul_f32 v[108:109], v[110:111], v[110:111]
	s_waitcnt vmcnt(0)
	v_pk_fma_f32 v[124:125], v[106:107], v[96:97], v[112:113] op_sel_hi:[1,0,1]
	v_add_f32_e32 v96, v108, v109
	v_pk_mul_f32 v[106:107], v[124:125], v[124:125]
	s_nop 0
	v_add_f32_e32 v96, v96, v106
	v_add_f32_e32 v96, v96, v107
	v_mov_b32_e32 v105, v96
	v_mov_b32_e32 v255, v96
	s_nop 1
	v_permlane16_swap_b32_e32 v105, v255
	s_nop 1
	v_mov_b32_dpp v105, v255 quad_perm:[0,1,2,3] row_mask:0x5 bank_mask:0xf
	v_mov_b64_e32 v[106:107], s[6:7]
	v_mad_i64_i32 v[108:109], s[6:7], v100, s74, v[106:107]
	v_lshl_add_u64 v[126:127], v[108:109], 0, s[96:97]
	s_nop 0
	v_add_f32_e32 v96, v96, v105
	s_nop 1
	v_mov_b32_dpp v105, v96 row_ror:8 row_mask:0xf bank_mask:0xf
	v_lshlrev_b64 v[108:109], 10, v[100:101]
	v_lshl_add_u64 v[112:113], s[66:67], 0, v[108:109]
	s_nop 0
	v_add_f32_e32 v96, v96, v105
	s_nop 1
	v_mov_b32_dpp v105, v96 row_shl:4 row_mask:0xf bank_mask:0x5
	v_mov_b32_dpp v105, v96 row_shr:4 row_mask:0xf bank_mask:0xa
	s_nop 0
	v_add_f32_e32 v96, v96, v105
	s_nop 1
	v_mov_b32_dpp v105, v96 quad_perm:[2,3,0,1] row_mask:0xf bank_mask:0xf
	s_nop 0
	v_add_f32_e32 v96, v96, v105
	s_nop 1
	s_nop 0
	s_nop 0
	v_add_f32_dpp v96, v96, v96 quad_perm:[1,0,3,2] row_mask:0xf bank_mask:0xf
	v_fmamk_f32 v96, v96, 0x3c000000, v163
	v_cmp_gt_f32_e32 vcc, s86, v96
	v_mul_f32_e32 v105, 0x4b800000, v96
	s_nop 0
	v_cndmask_b32_e32 v96, v96, v105, vcc
	v_rsq_f32_e32 v96, v96
	s_nop 0
	v_mul_f32_e32 v105, 0x45800000, v96
	v_cndmask_b32_e32 v105, v96, v105, vcc
	v_lshlrev_b32_e32 v96, 1, v103
	v_lshl_add_u64 v[108:109], v[126:127], 0, v[96:97]
	global_load_ushort v108, v[108:109], off
	v_mov_b32_e32 v109, v97
	v_mul_f32_e32 v110, v110, v105
	v_lshl_add_u64 v[122:123], v[112:113], 0, v[96:97]
	v_or_b32_e32 v112, 64, v96
	v_mov_b32_e32 v113, v97
	s_waitcnt vmcnt(0)
	v_lshlrev_b32_e32 v108, 16, v108
	v_mul_f32_e32 v108, 0xbfb8aa3b, v108
	v_exp_f32_e32 v108, v108
	s_nop 0
	v_add_f32_e32 v108, 1.0, v108
	v_rcp_f32_e32 v118, v108
	v_or_b32_e32 v108, s34, v103
	v_lshl_add_u64 v[108:109], v[108:109], 2, s[18:19]
	global_load_dword v119, v[108:109], off
	s_waitcnt vmcnt(0)
	v_mul_f32_e32 v110, v119, v110
	v_mul_f32_e32 v110, v118, v110
	v_cvt_pk_bf16_f32 v110, v110, s0
	v_lshl_add_u64 v[118:119], v[126:127], 0, v[112:113]
	global_store_short v[122:123], v110, off
	global_load_ushort v110, v[118:119], off
	v_mul_f32_e32 v119, v111, v105
	v_mov_b32_e32 v111, v97
	s_waitcnt vmcnt(0)
	v_lshlrev_b32_e32 v110, 16, v110
	v_mul_f32_e32 v110, 0xbfb8aa3b, v110
	v_exp_f32_e32 v110, v110
	s_nop 0
	v_add_f32_e32 v110, 1.0, v110
	v_rcp_f32_e32 v118, v110
	v_add_u32_e32 v110, s34, v103
	v_lshl_add_u64 v[110:111], v[110:111], 2, s[18:19]
	global_load_dword v103, v[110:111], off offset:128
	s_mov_b32 s19, 0x2c000
	s_movk_i32 s18, 0x1600
	s_waitcnt vmcnt(0)
	v_mul_f32_e32 v103, v103, v119
	v_mul_f32_e32 v103, v118, v103
	v_or_b32_e32 v118, 0x80, v96
	v_mov_b32_e32 v119, v97
	v_cvt_pk_bf16_f32 v103, v103, s0
	v_lshl_add_u64 v[120:121], v[126:127], 0, v[118:119]
	global_store_short v[122:123], v103, off offset:64
	global_load_ushort v103, v[120:121], off
	v_mul_f32_e32 v120, v124, v105
	global_load_dword v121, v[110:111], off offset:256
	global_load_dword v124, v[110:111], off offset:384
	v_mul_f32_e32 v105, v125, v105
	s_waitcnt vmcnt(2)
	v_lshlrev_b32_e32 v103, 16, v103
	v_mul_f32_e32 v103, 0xbfb8aa3b, v103
	v_exp_f32_e32 v103, v103
	s_waitcnt vmcnt(1)
	v_mul_f32_e32 v120, v121, v120
	v_mov_b32_e32 v121, v97
	s_waitcnt vmcnt(0)
	v_mul_f32_e32 v105, v124, v105
	v_add_f32_e32 v103, 1.0, v103
	v_rcp_f32_e32 v103, v103
	s_nop 0
	v_mul_f32_e32 v103, v120, v103
	v_or_b32_e32 v120, 0xc0, v96
	v_cvt_pk_bf16_f32 v103, v103, s0
	v_lshl_add_u64 v[126:127], v[126:127], 0, v[120:121]
	global_store_short v[122:123], v103, off offset:128
	global_load_ushort v103, v[126:127], off
	s_waitcnt vmcnt(0)
	v_lshlrev_b32_e32 v103, 16, v103
	v_mul_f32_e32 v103, 0xbfb8aa3b, v103
	v_exp_f32_e32 v103, v103
	s_nop 0
	v_add_f32_e32 v103, 1.0, v103
	v_rcp_f32_e32 v103, v103
	s_nop 0
	v_mul_f32_e32 v103, v105, v103
	v_cvt_pk_bf16_f32 v103, v103, s0
	global_store_short v[122:123], v103, off offset:192
	v_add_u32_e32 v103, s0, v236
	v_add_u32_e32 v105, s1, v236
	ds_read_b32 v103, v103
	ds_read_b32 v105, v105
	v_mov_b32_e32 v242, v1
	v_mov_b32_e32 v243, v17
	s_waitcnt lgkmcnt(1)
	v_max_f32_e64 v103, |v103|, |v103|
	s_waitcnt lgkmcnt(0)
	v_max_f32_e32 v105, v105, v105
	v_max_f32_e32 v103, v103, v105
	v_div_scale_f32 v105, s[6:7], v103, v103, 1.0
	v_rcp_f32_e32 v122, v105
	s_nop 0
	v_fma_f32 v123, -v105, v122, 1.0
	v_fmac_f32_e32 v122, v123, v122
	v_div_scale_f32 v123, vcc, 1.0, v103, 1.0
	v_mul_f32_e32 v124, v123, v122
	v_fma_f32 v125, -v105, v124, v123
	v_fmac_f32_e32 v124, v125, v122
	v_fma_f32 v105, -v105, v124, v123
	v_div_fmas_f32 v105, v105, v122, v124
	v_div_fixup_f32 v122, v105, v103, 1.0
	v_ashrrev_i32_e32 v105, 31, v104
	v_lshlrev_b64 v[124:125], 11, v[104:105]
	v_lshl_add_u64 v[124:125], v[98:99], 0, v[124:125]
	global_load_dword v126, v[124:125], off
	global_load_dword v127, v[124:125], off offset:128
	global_load_dword v244, v[124:125], off offset:256
	global_load_dword v245, v[124:125], off offset:384
	v_mov_b32_e32 v124, v33
	v_mov_b32_e32 v125, v49
	s_waitcnt vmcnt(2)
	v_pk_fma_f32 v[126:127], v[242:243], v[122:123], v[126:127] op_sel_hi:[1,0,1]
	s_nop 0
	v_pk_mul_f32 v[242:243], v[126:127], v[126:127]
	s_waitcnt vmcnt(0)
	v_pk_fma_f32 v[124:125], v[124:125], v[122:123], v[244:245] op_sel_hi:[1,0,1]
	v_add_f32_e32 v103, v242, v243
	v_pk_mul_f32 v[122:123], v[124:125], v[124:125]
	s_nop 0
	v_add_f32_e32 v103, v103, v122
	v_add_f32_e32 v103, v103, v123
	v_mov_b32_e32 v122, v103
	v_mov_b32_e32 v255, v103
	s_nop 1
	v_permlane16_swap_b32_e32 v122, v255
	s_nop 1
	v_mov_b32_dpp v122, v255 quad_perm:[0,1,2,3] row_mask:0x5 bank_mask:0xf
	s_nop 0
	v_add_f32_e32 v103, v103, v122
	s_nop 1
	v_mov_b32_dpp v122, v103 row_ror:8 row_mask:0xf bank_mask:0xf
	s_nop 0
	v_add_f32_e32 v103, v103, v122
	s_nop 1
	v_mov_b32_dpp v122, v103 row_shl:4 row_mask:0xf bank_mask:0x5
	v_mov_b32_dpp v122, v103 row_shr:4 row_mask:0xf bank_mask:0xa
	s_nop 0
	v_add_f32_e32 v103, v103, v122
	s_nop 1
	v_mov_b32_dpp v122, v103 quad_perm:[2,3,0,1] row_mask:0xf bank_mask:0xf
	s_nop 0
	v_add_f32_e32 v103, v103, v122
	s_nop 1
	s_nop 0
	s_nop 0
	v_add_f32_dpp v103, v103, v103 quad_perm:[1,0,3,2] row_mask:0xf bank_mask:0xf
	v_fmamk_f32 v103, v103, 0x3c000000, v163
	v_cmp_gt_f32_e32 vcc, s86, v103
	v_mul_f32_e32 v122, 0x4b800000, v103
	s_nop 0
	v_cndmask_b32_e32 v103, v103, v122, vcc
	v_rsq_f32_e32 v103, v103
	s_nop 0
	v_mul_f32_e32 v122, 0x45800000, v103
	v_cndmask_b32_e32 v103, v103, v122, vcc
	v_mad_i64_i32 v[122:123], s[6:7], v104, s74, v[106:107]
	v_lshl_add_u64 v[242:243], v[122:123], 0, s[96:97]
	v_lshl_add_u64 v[244:245], v[242:243], 0, v[96:97]
	v_lshlrev_b64 v[122:123], 10, v[104:105]
	global_load_ushort v105, v[244:245], off
	v_mul_f32_e32 v126, v126, v103
	global_load_dword v244, v[108:109], off
	v_lshl_add_u64 v[122:123], s[66:67], 0, v[122:123]
	v_lshl_add_u64 v[122:123], v[122:123], 0, v[96:97]
	v_mul_f32_e32 v124, v124, v103
	s_waitcnt vmcnt(1)
	v_lshlrev_b32_e32 v105, 16, v105
	v_mul_f32_e32 v105, 0xbfb8aa3b, v105
	v_exp_f32_e32 v105, v105
	s_waitcnt vmcnt(0)
	v_mul_f32_e32 v126, v244, v126
	v_lshl_add_u64 v[244:245], v[242:243], 0, v[112:113]
	v_add_f32_e32 v105, 1.0, v105
	v_rcp_f32_e32 v105, v105
	s_nop 0
	v_mul_f32_e32 v105, v105, v126
	v_cvt_pk_bf16_f32 v105, v105, s0
	global_store_short v[122:123], v105, off
	global_load_ushort v105, v[244:245], off
	v_mul_f32_e32 v126, v127, v103
	global_load_dword v127, v[110:111], off offset:128
	v_mul_f32_e32 v103, v125, v103
	s_waitcnt vmcnt(1)
	v_lshlrev_b32_e32 v105, 16, v105
	v_mul_f32_e32 v105, 0xbfb8aa3b, v105
	v_exp_f32_e32 v105, v105
	s_waitcnt vmcnt(0)
	v_mul_f32_e32 v126, v127, v126
	v_add_f32_e32 v105, 1.0, v105
	v_rcp_f32_e32 v105, v105
	s_nop 0
	v_mul_f32_e32 v105, v105, v126
	v_cvt_pk_bf16_f32 v105, v105, s0
	v_lshl_add_u64 v[126:127], v[242:243], 0, v[118:119]
	global_store_short v[122:123], v105, off offset:64
	global_load_ushort v105, v[126:127], off
	s_waitcnt vmcnt(0)
	v_lshlrev_b32_e32 v105, 16, v105
	global_load_dword v126, v[110:111], off offset:256
	v_mul_f32_e32 v105, 0xbfb8aa3b, v105
	v_exp_f32_e32 v105, v105
	s_waitcnt vmcnt(0)
	v_mul_f32_e32 v124, v126, v124
	v_add_f32_e32 v105, 1.0, v105
	v_rcp_f32_e32 v105, v105
	v_lshl_add_u64 v[126:127], v[242:243], 0, v[120:121]
	v_mul_f32_e32 v105, v124, v105
	v_cvt_pk_bf16_f32 v105, v105, s0
	global_store_short v[122:123], v105, off offset:128
	global_load_ushort v105, v[126:127], off
	s_waitcnt vmcnt(0)
	v_lshlrev_b32_e32 v105, 16, v105
	global_load_dword v124, v[110:111], off offset:384
	v_mul_f32_e32 v105, 0xbfb8aa3b, v105
	v_exp_f32_e32 v105, v105
	s_waitcnt vmcnt(0)
	v_mul_f32_e32 v103, v124, v103
	v_add_f32_e32 v105, 1.0, v105
	v_rcp_f32_e32 v105, v105
	s_nop 0
	v_mul_f32_e32 v103, v103, v105
	v_cvt_pk_bf16_f32 v103, v103, s0
	global_store_short v[122:123], v103, off offset:192
	v_add_u32_e32 v103, s0, v235
	v_add_u32_e32 v105, s1, v235
	ds_read_b32 v103, v103
	ds_read_b32 v105, v105
	v_mov_b32_e32 v242, v2
	v_mov_b32_e32 v243, v18
	s_waitcnt lgkmcnt(1)
	v_max_f32_e64 v103, |v103|, |v103|
	s_waitcnt lgkmcnt(0)
	v_max_f32_e32 v105, v105, v105
	v_max_f32_e32 v103, v103, v105
	v_div_scale_f32 v105, s[6:7], v103, v103, 1.0
	v_rcp_f32_e32 v122, v105
	s_nop 0
	v_fma_f32 v123, -v105, v122, 1.0
	v_fmac_f32_e32 v122, v123, v122
	v_div_scale_f32 v123, vcc, 1.0, v103, 1.0
	v_mul_f32_e32 v124, v123, v122
	v_fma_f32 v125, -v105, v124, v123
	v_fmac_f32_e32 v124, v125, v122
	v_fma_f32 v105, -v105, v124, v123
	v_div_fmas_f32 v105, v105, v122, v124
	v_div_fixup_f32 v122, v105, v103, 1.0
	v_ashrrev_i32_e32 v103, 31, v102
	v_lshlrev_b64 v[124:125], 11, v[102:103]
	v_lshl_add_u64 v[124:125], v[98:99], 0, v[124:125]
	global_load_dword v126, v[124:125], off
	global_load_dword v127, v[124:125], off offset:128
	global_load_dword v244, v[124:125], off offset:256
	global_load_dword v245, v[124:125], off offset:384
	v_mov_b32_e32 v124, v34
	v_mov_b32_e32 v125, v50
	s_waitcnt vmcnt(2)
	v_pk_fma_f32 v[126:127], v[242:243], v[122:123], v[126:127] op_sel_hi:[1,0,1]
	s_nop 0
	v_pk_mul_f32 v[242:243], v[126:127], v[126:127]
	s_waitcnt vmcnt(0)
	v_pk_fma_f32 v[124:125], v[124:125], v[122:123], v[244:245] op_sel_hi:[1,0,1]
	v_add_f32_e32 v105, v242, v243
	v_pk_mul_f32 v[122:123], v[124:125], v[124:125]
	s_nop 0
	v_add_f32_e32 v105, v105, v122
	v_add_f32_e32 v105, v105, v123
	v_mov_b32_e32 v122, v105
	v_mov_b32_e32 v255, v105
	s_nop 1
	v_permlane16_swap_b32_e32 v122, v255
	s_nop 1
	v_mov_b32_dpp v122, v255 quad_perm:[0,1,2,3] row_mask:0x5 bank_mask:0xf
	s_nop 0
	v_add_f32_e32 v105, v105, v122
	s_nop 1
	v_mov_b32_dpp v122, v105 row_ror:8 row_mask:0xf bank_mask:0xf
	s_nop 0
	v_add_f32_e32 v105, v105, v122
	s_nop 1
	v_mov_b32_dpp v122, v105 row_shl:4 row_mask:0xf bank_mask:0x5
	v_mov_b32_dpp v122, v105 row_shr:4 row_mask:0xf bank_mask:0xa
	s_nop 0
	v_add_f32_e32 v105, v105, v122
	s_nop 1
	v_mov_b32_dpp v122, v105 quad_perm:[2,3,0,1] row_mask:0xf bank_mask:0xf
	s_nop 0
	v_add_f32_e32 v105, v105, v122
	s_nop 1
	s_nop 0
	s_nop 0
	v_add_f32_dpp v105, v105, v105 quad_perm:[1,0,3,2] row_mask:0xf bank_mask:0xf
	v_fmamk_f32 v105, v105, 0x3c000000, v163
	v_cmp_gt_f32_e32 vcc, s86, v105
	v_mul_f32_e32 v122, 0x4b800000, v105
	s_nop 0
	v_cndmask_b32_e32 v105, v105, v122, vcc
	v_rsq_f32_e32 v105, v105
	s_nop 0
	v_mul_f32_e32 v122, 0x45800000, v105
	v_cndmask_b32_e32 v105, v105, v122, vcc
	v_mad_i64_i32 v[122:123], s[6:7], v102, s74, v[106:107]
	v_lshl_add_u64 v[242:243], v[122:123], 0, s[96:97]
	v_lshl_add_u64 v[244:245], v[242:243], 0, v[96:97]
	v_lshlrev_b64 v[122:123], 10, v[102:103]
	global_load_ushort v103, v[244:245], off
	v_mul_f32_e32 v126, v126, v105
	global_load_dword v244, v[108:109], off
	v_lshl_add_u64 v[122:123], s[66:67], 0, v[122:123]
	v_lshl_add_u64 v[122:123], v[122:123], 0, v[96:97]
	v_mul_f32_e32 v124, v124, v105
	s_waitcnt vmcnt(1)
	v_lshlrev_b32_e32 v103, 16, v103
	v_mul_f32_e32 v103, 0xbfb8aa3b, v103
	v_exp_f32_e32 v103, v103
	s_waitcnt vmcnt(0)
	v_mul_f32_e32 v126, v244, v126
	v_lshl_add_u64 v[244:245], v[242:243], 0, v[112:113]
	v_add_f32_e32 v103, 1.0, v103
	v_rcp_f32_e32 v103, v103
	s_nop 0
	v_mul_f32_e32 v103, v103, v126
	v_cvt_pk_bf16_f32 v103, v103, s0
	global_store_short v[122:123], v103, off
	global_load_ushort v103, v[244:245], off
	v_mul_f32_e32 v126, v127, v105
	global_load_dword v127, v[110:111], off offset:128
	v_mul_f32_e32 v105, v125, v105
	s_waitcnt vmcnt(1)
	v_lshlrev_b32_e32 v103, 16, v103
	v_mul_f32_e32 v103, 0xbfb8aa3b, v103
	v_exp_f32_e32 v103, v103
	s_waitcnt vmcnt(0)
	v_mul_f32_e32 v126, v127, v126
	v_add_f32_e32 v103, 1.0, v103
	v_rcp_f32_e32 v103, v103
	s_nop 0
	v_mul_f32_e32 v103, v103, v126
	v_cvt_pk_bf16_f32 v103, v103, s0
	v_lshl_add_u64 v[126:127], v[242:243], 0, v[118:119]
	global_store_short v[122:123], v103, off offset:64
	global_load_ushort v103, v[126:127], off
	s_waitcnt vmcnt(0)
	v_lshlrev_b32_e32 v103, 16, v103
	global_load_dword v126, v[110:111], off offset:256
	v_mul_f32_e32 v103, 0xbfb8aa3b, v103
	v_exp_f32_e32 v103, v103
	s_waitcnt vmcnt(0)
	v_mul_f32_e32 v124, v126, v124
	v_add_f32_e32 v103, 1.0, v103
	v_rcp_f32_e32 v103, v103
	v_lshl_add_u64 v[126:127], v[242:243], 0, v[120:121]
	v_mul_f32_e32 v103, v124, v103
	v_cvt_pk_bf16_f32 v103, v103, s0
	global_store_short v[122:123], v103, off offset:128
	global_load_ushort v103, v[126:127], off
	s_waitcnt vmcnt(0)
	v_lshlrev_b32_e32 v103, 16, v103
	global_load_dword v124, v[110:111], off offset:384
	v_mul_f32_e32 v103, 0xbfb8aa3b, v103
	v_exp_f32_e32 v103, v103
	s_waitcnt vmcnt(0)
	v_mul_f32_e32 v105, v124, v105
	v_add_f32_e32 v103, 1.0, v103
	v_rcp_f32_e32 v103, v103
	s_nop 0
	v_mul_f32_e32 v103, v105, v103
	v_cvt_pk_bf16_f32 v103, v103, s0
	global_store_short v[122:123], v103, off offset:192
	v_lshlrev_b32_e32 v103, 2, v234
	v_add_u32_e32 v105, s0, v103
	v_add_u32_e32 v103, s1, v103
	ds_read_b32 v105, v105
	ds_read_b32 v103, v103
	v_add_u32_e32 v126, s61, v234
	v_ashrrev_i32_e32 v127, 31, v126
	v_mov_b32_e32 v244, v3
	s_waitcnt lgkmcnt(1)
	v_max_f32_e64 v105, |v105|, |v105|
	s_waitcnt lgkmcnt(0)
	v_max_f32_e32 v103, v103, v103
	v_max_f32_e32 v103, v105, v103
	v_div_scale_f32 v105, s[0:1], v103, v103, 1.0
	v_rcp_f32_e32 v122, v105
	v_mov_b32_e32 v245, v19
	v_fma_f32 v123, -v105, v122, 1.0
	v_fmac_f32_e32 v122, v123, v122
	v_div_scale_f32 v123, vcc, 1.0, v103, 1.0
	v_mul_f32_e32 v124, v123, v122
	v_fma_f32 v125, -v105, v124, v123
	v_fmac_f32_e32 v124, v125, v122
	v_fma_f32 v105, -v105, v124, v123
	v_div_fmas_f32 v105, v105, v122, v124
	v_lshlrev_b64 v[124:125], 11, v[126:127]
	v_lshl_add_u64 v[124:125], v[98:99], 0, v[124:125]
	global_load_dword v242, v[124:125], off
	global_load_dword v243, v[124:125], off offset:128
	global_load_dword v246, v[124:125], off offset:256
	global_load_dword v247, v[124:125], off offset:384
	v_div_fixup_f32 v122, v105, v103, 1.0
	v_mov_b32_e32 v124, v35
	v_mov_b32_e32 v125, v51
	s_waitcnt vmcnt(2)
	v_pk_fma_f32 v[242:243], v[244:245], v[122:123], v[242:243] op_sel_hi:[1,0,1]
	s_nop 0
	v_pk_mul_f32 v[244:245], v[242:243], v[242:243]
	s_waitcnt vmcnt(0)
	v_pk_fma_f32 v[124:125], v[124:125], v[122:123], v[246:247] op_sel_hi:[1,0,1]
	v_add_f32_e32 v103, v244, v245
	v_pk_mul_f32 v[122:123], v[124:125], v[124:125]
	s_nop 0
	v_add_f32_e32 v103, v103, v122
	v_add_f32_e32 v103, v103, v123
	v_mov_b32_e32 v105, v103
	v_mov_b32_e32 v255, v103
	s_nop 1
	v_permlane16_swap_b32_e32 v105, v255
	s_nop 1
	v_mov_b32_dpp v105, v255 quad_perm:[0,1,2,3] row_mask:0x5 bank_mask:0xf
	v_mad_i64_i32 v[122:123], s[0:1], v126, s74, v[106:107]
	v_lshl_add_u64 v[244:245], v[122:123], 0, s[96:97]
	v_lshlrev_b64 v[122:123], 10, v[126:127]
	s_nop 0
	v_add_f32_e32 v103, v103, v105
	s_nop 1
	v_mov_b32_dpp v105, v103 row_ror:8 row_mask:0xf bank_mask:0xf
	v_lshl_add_u64 v[126:127], v[244:245], 0, v[96:97]
	v_lshl_add_u64 v[122:123], s[66:67], 0, v[122:123]
	v_lshl_add_u64 v[122:123], v[122:123], 0, v[96:97]
	s_nop 0
	v_add_f32_e32 v103, v103, v105
	s_nop 1
	v_mov_b32_dpp v105, v103 row_shl:4 row_mask:0xf bank_mask:0x5
	v_mov_b32_dpp v105, v103 row_shr:4 row_mask:0xf bank_mask:0xa
	s_nop 0
	v_add_f32_e32 v103, v103, v105
	s_nop 1
	v_mov_b32_dpp v105, v103 quad_perm:[2,3,0,1] row_mask:0xf bank_mask:0xf
	s_nop 0
	v_add_f32_e32 v103, v103, v105
	s_nop 1
	s_nop 0
	s_nop 0
	v_add_f32_dpp v103, v103, v103 quad_perm:[1,0,3,2] row_mask:0xf bank_mask:0xf
	v_fmamk_f32 v103, v103, 0x3c000000, v163
	v_cmp_gt_f32_e32 vcc, s86, v103
	v_mul_f32_e32 v105, 0x4b800000, v103
	s_nop 0
	v_cndmask_b32_e32 v103, v103, v105, vcc
	v_rsq_f32_e32 v103, v103
	s_nop 0
	v_mul_f32_e32 v105, 0x45800000, v103
	v_cndmask_b32_e32 v103, v103, v105, vcc
	global_load_ushort v105, v[126:127], off
	v_mul_f32_e32 v126, v242, v103
	global_load_dword v127, v[108:109], off
	v_mul_f32_e32 v124, v124, v103
	s_waitcnt vmcnt(1)
	v_lshlrev_b32_e32 v105, 16, v105
	v_mul_f32_e32 v105, 0xbfb8aa3b, v105
	v_exp_f32_e32 v105, v105
	s_waitcnt vmcnt(0)
	v_mul_f32_e32 v126, v127, v126
	v_add_f32_e32 v105, 1.0, v105
	v_rcp_f32_e32 v105, v105
	s_nop 0
	v_mul_f32_e32 v105, v105, v126
	v_cvt_pk_bf16_f32 v105, v105, s0
	v_lshl_add_u64 v[126:127], v[244:245], 0, v[112:113]
	global_store_short v[122:123], v105, off
	global_load_ushort v105, v[126:127], off
	v_mul_f32_e32 v126, v243, v103
	global_load_dword v127, v[110:111], off offset:128
	v_mul_f32_e32 v103, v125, v103
	s_waitcnt vmcnt(1)
	v_lshlrev_b32_e32 v105, 16, v105
	v_mul_f32_e32 v105, 0xbfb8aa3b, v105
	v_exp_f32_e32 v105, v105
	s_waitcnt vmcnt(0)
	v_mul_f32_e32 v126, v127, v126
	v_add_f32_e32 v105, 1.0, v105
	v_rcp_f32_e32 v105, v105
	s_nop 0
	v_mul_f32_e32 v105, v105, v126
	v_cvt_pk_bf16_f32 v105, v105, s0
	v_lshl_add_u64 v[126:127], v[244:245], 0, v[118:119]
	global_store_short v[122:123], v105, off offset:64
	global_load_ushort v105, v[126:127], off
	s_waitcnt vmcnt(0)
	v_lshlrev_b32_e32 v105, 16, v105
	global_load_dword v126, v[110:111], off offset:256
	v_mul_f32_e32 v105, 0xbfb8aa3b, v105
	v_exp_f32_e32 v105, v105
	s_waitcnt vmcnt(0)
	v_mul_f32_e32 v124, v126, v124
	v_add_f32_e32 v105, 1.0, v105
	v_rcp_f32_e32 v105, v105
	v_lshl_add_u64 v[126:127], v[244:245], 0, v[120:121]
	v_mul_f32_e32 v105, v124, v105
	v_cvt_pk_bf16_f32 v105, v105, s0
	global_store_short v[122:123], v105, off offset:128
	global_load_ushort v105, v[126:127], off
	s_waitcnt vmcnt(0)
	v_lshlrev_b32_e32 v105, 16, v105
	global_load_dword v124, v[110:111], off offset:384
	v_mul_f32_e32 v105, 0xbfb8aa3b, v105
	v_exp_f32_e32 v105, v105
	s_waitcnt vmcnt(0)
	v_mul_f32_e32 v103, v124, v103
	v_add_f32_e32 v105, 1.0, v105
	v_rcp_f32_e32 v105, v105
	s_nop 0
	v_mul_f32_e32 v103, v103, v105
	v_cvt_pk_bf16_f32 v103, v103, s0
	global_store_short v[122:123], v103, off offset:192
	ds_read_b32 v103, v238 offset:32
	ds_read_b32 v105, v239 offset:32
	v_add_u32_e32 v126, 8, v100
	v_ashrrev_i32_e32 v127, 31, v126
	v_mov_b32_e32 v244, v4
	s_waitcnt lgkmcnt(1)
	v_max_f32_e64 v103, |v103|, |v103|
	s_waitcnt lgkmcnt(0)
	v_max_f32_e32 v105, v105, v105
	v_max_f32_e32 v103, v103, v105
	v_div_scale_f32 v105, s[0:1], v103, v103, 1.0
	v_rcp_f32_e32 v122, v105
	v_mov_b32_e32 v245, v20
	v_fma_f32 v123, -v105, v122, 1.0
	v_fmac_f32_e32 v122, v123, v122
	v_div_scale_f32 v123, vcc, 1.0, v103, 1.0
	v_mul_f32_e32 v124, v123, v122
	v_fma_f32 v125, -v105, v124, v123
	v_fmac_f32_e32 v124, v125, v122
	v_fma_f32 v105, -v105, v124, v123
	v_div_fmas_f32 v105, v105, v122, v124
	v_lshlrev_b64 v[124:125], 11, v[126:127]
	v_lshl_add_u64 v[124:125], v[98:99], 0, v[124:125]
	global_load_dword v242, v[124:125], off
	global_load_dword v243, v[124:125], off offset:128
	global_load_dword v246, v[124:125], off offset:256
	global_load_dword v247, v[124:125], off offset:384
	v_div_fixup_f32 v122, v105, v103, 1.0
	v_mov_b32_e32 v124, v36
	v_mov_b32_e32 v125, v52
	s_waitcnt vmcnt(2)
	v_pk_fma_f32 v[242:243], v[244:245], v[122:123], v[242:243] op_sel_hi:[1,0,1]
	s_nop 0
	v_pk_mul_f32 v[244:245], v[242:243], v[242:243]
	s_waitcnt vmcnt(0)
	v_pk_fma_f32 v[124:125], v[124:125], v[122:123], v[246:247] op_sel_hi:[1,0,1]
	v_add_f32_e32 v103, v244, v245
	v_pk_mul_f32 v[122:123], v[124:125], v[124:125]
	s_nop 0
	v_add_f32_e32 v103, v103, v122
	v_add_f32_e32 v103, v103, v123
	v_mov_b32_e32 v105, v103
	v_mov_b32_e32 v255, v103
	s_nop 1
	v_permlane16_swap_b32_e32 v105, v255
	s_nop 1
	v_mov_b32_dpp v105, v255 quad_perm:[0,1,2,3] row_mask:0x5 bank_mask:0xf
	v_mad_i64_i32 v[122:123], s[0:1], v126, s74, v[106:107]
	v_lshl_add_u64 v[244:245], v[122:123], 0, s[96:97]
	v_lshlrev_b64 v[122:123], 10, v[126:127]
	s_nop 0
	v_add_f32_e32 v103, v103, v105
	s_nop 1
	v_mov_b32_dpp v105, v103 row_ror:8 row_mask:0xf bank_mask:0xf
	v_lshl_add_u64 v[126:127], v[244:245], 0, v[96:97]
	v_lshl_add_u64 v[122:123], s[66:67], 0, v[122:123]
	v_lshl_add_u64 v[122:123], v[122:123], 0, v[96:97]
	s_nop 0
	v_add_f32_e32 v103, v103, v105
	s_nop 1
	v_mov_b32_dpp v105, v103 row_shl:4 row_mask:0xf bank_mask:0x5
	v_mov_b32_dpp v105, v103 row_shr:4 row_mask:0xf bank_mask:0xa
	s_nop 0
	v_add_f32_e32 v103, v103, v105
	s_nop 1
	v_mov_b32_dpp v105, v103 quad_perm:[2,3,0,1] row_mask:0xf bank_mask:0xf
	s_nop 0
	v_add_f32_e32 v103, v103, v105
	s_nop 1
	s_nop 0
	s_nop 0
	v_add_f32_dpp v103, v103, v103 quad_perm:[1,0,3,2] row_mask:0xf bank_mask:0xf
	v_fmamk_f32 v103, v103, 0x3c000000, v163
	v_cmp_gt_f32_e32 vcc, s86, v103
	v_mul_f32_e32 v105, 0x4b800000, v103
	s_nop 0
	v_cndmask_b32_e32 v103, v103, v105, vcc
	v_rsq_f32_e32 v103, v103
	s_nop 0
	v_mul_f32_e32 v105, 0x45800000, v103
	v_cndmask_b32_e32 v103, v103, v105, vcc
	global_load_ushort v105, v[126:127], off
	v_mul_f32_e32 v126, v242, v103
	global_load_dword v127, v[108:109], off
	v_mul_f32_e32 v124, v124, v103
	s_waitcnt vmcnt(1)
	v_lshlrev_b32_e32 v105, 16, v105
	v_mul_f32_e32 v105, 0xbfb8aa3b, v105
	v_exp_f32_e32 v105, v105
	s_waitcnt vmcnt(0)
	v_mul_f32_e32 v126, v127, v126
	v_add_f32_e32 v105, 1.0, v105
	v_rcp_f32_e32 v105, v105
	s_nop 0
	v_mul_f32_e32 v105, v105, v126
	v_cvt_pk_bf16_f32 v105, v105, s0
	v_lshl_add_u64 v[126:127], v[244:245], 0, v[112:113]
	global_store_short v[122:123], v105, off
	global_load_ushort v105, v[126:127], off
	v_mul_f32_e32 v126, v243, v103
	global_load_dword v127, v[110:111], off offset:128
	v_mul_f32_e32 v103, v125, v103
	s_waitcnt vmcnt(1)
	v_lshlrev_b32_e32 v105, 16, v105
	v_mul_f32_e32 v105, 0xbfb8aa3b, v105
	v_exp_f32_e32 v105, v105
	s_waitcnt vmcnt(0)
	v_mul_f32_e32 v126, v127, v126
	v_add_f32_e32 v105, 1.0, v105
	v_rcp_f32_e32 v105, v105
	s_nop 0
	v_mul_f32_e32 v105, v105, v126
	v_cvt_pk_bf16_f32 v105, v105, s0
	v_lshl_add_u64 v[126:127], v[244:245], 0, v[118:119]
	global_store_short v[122:123], v105, off offset:64
	global_load_ushort v105, v[126:127], off
	s_waitcnt vmcnt(0)
	v_lshlrev_b32_e32 v105, 16, v105
	global_load_dword v126, v[110:111], off offset:256
	v_mul_f32_e32 v105, 0xbfb8aa3b, v105
	v_exp_f32_e32 v105, v105
	s_waitcnt vmcnt(0)
	v_mul_f32_e32 v124, v126, v124
	v_add_f32_e32 v105, 1.0, v105
	v_rcp_f32_e32 v105, v105
	v_lshl_add_u64 v[126:127], v[244:245], 0, v[120:121]
	v_mul_f32_e32 v105, v124, v105
	v_cvt_pk_bf16_f32 v105, v105, s0
	global_store_short v[122:123], v105, off offset:128
	global_load_ushort v105, v[126:127], off
	s_waitcnt vmcnt(0)
	v_lshlrev_b32_e32 v105, 16, v105
	global_load_dword v124, v[110:111], off offset:384
	v_mul_f32_e32 v105, 0xbfb8aa3b, v105
	v_exp_f32_e32 v105, v105
	s_waitcnt vmcnt(0)
	v_mul_f32_e32 v103, v124, v103
	v_add_f32_e32 v105, 1.0, v105
	v_rcp_f32_e32 v105, v105
	s_nop 0
	v_mul_f32_e32 v103, v103, v105
	v_cvt_pk_bf16_f32 v103, v103, s0
	global_store_short v[122:123], v103, off offset:192
	ds_read_b32 v103, v238 offset:36
	ds_read_b32 v105, v239 offset:36
	v_add_u32_e32 v126, 9, v100
	v_ashrrev_i32_e32 v127, 31, v126
	v_mov_b32_e32 v244, v5
	s_waitcnt lgkmcnt(1)
	v_max_f32_e64 v103, |v103|, |v103|
	s_waitcnt lgkmcnt(0)
	v_max_f32_e32 v105, v105, v105
	v_max_f32_e32 v103, v103, v105
	v_div_scale_f32 v105, s[0:1], v103, v103, 1.0
	v_rcp_f32_e32 v122, v105
	v_mov_b32_e32 v245, v21
	v_fma_f32 v123, -v105, v122, 1.0
	v_fmac_f32_e32 v122, v123, v122
	v_div_scale_f32 v123, vcc, 1.0, v103, 1.0
	v_mul_f32_e32 v124, v123, v122
	v_fma_f32 v125, -v105, v124, v123
	v_fmac_f32_e32 v124, v125, v122
	v_fma_f32 v105, -v105, v124, v123
	v_div_fmas_f32 v105, v105, v122, v124
	v_lshlrev_b64 v[124:125], 11, v[126:127]
	v_lshl_add_u64 v[124:125], v[98:99], 0, v[124:125]
	global_load_dword v242, v[124:125], off
	global_load_dword v243, v[124:125], off offset:128
	global_load_dword v246, v[124:125], off offset:256
	global_load_dword v247, v[124:125], off offset:384
	v_div_fixup_f32 v122, v105, v103, 1.0
	v_mov_b32_e32 v124, v37
	v_mov_b32_e32 v125, v53
	s_waitcnt vmcnt(2)
	v_pk_fma_f32 v[242:243], v[244:245], v[122:123], v[242:243] op_sel_hi:[1,0,1]
	s_nop 0
	v_pk_mul_f32 v[244:245], v[242:243], v[242:243]
	s_waitcnt vmcnt(0)
	v_pk_fma_f32 v[124:125], v[124:125], v[122:123], v[246:247] op_sel_hi:[1,0,1]
	v_add_f32_e32 v103, v244, v245
	v_pk_mul_f32 v[122:123], v[124:125], v[124:125]
	s_nop 0
	v_add_f32_e32 v103, v103, v122
	v_add_f32_e32 v103, v103, v123
	v_mov_b32_e32 v105, v103
	v_mov_b32_e32 v255, v103
	s_nop 1
	v_permlane16_swap_b32_e32 v105, v255
	s_nop 1
	v_mov_b32_dpp v105, v255 quad_perm:[0,1,2,3] row_mask:0x5 bank_mask:0xf
	v_mad_i64_i32 v[122:123], s[0:1], v126, s74, v[106:107]
	v_lshl_add_u64 v[244:245], v[122:123], 0, s[96:97]
	v_lshlrev_b64 v[122:123], 10, v[126:127]
	s_nop 0
	v_add_f32_e32 v103, v103, v105
	s_nop 1
	v_mov_b32_dpp v105, v103 row_ror:8 row_mask:0xf bank_mask:0xf
	v_lshl_add_u64 v[126:127], v[244:245], 0, v[96:97]
	v_lshl_add_u64 v[122:123], s[66:67], 0, v[122:123]
	v_lshl_add_u64 v[122:123], v[122:123], 0, v[96:97]
	s_nop 0
	v_add_f32_e32 v103, v103, v105
	s_nop 1
	v_mov_b32_dpp v105, v103 row_shl:4 row_mask:0xf bank_mask:0x5
	v_mov_b32_dpp v105, v103 row_shr:4 row_mask:0xf bank_mask:0xa
	s_nop 0
	v_add_f32_e32 v103, v103, v105
	s_nop 1
	v_mov_b32_dpp v105, v103 quad_perm:[2,3,0,1] row_mask:0xf bank_mask:0xf
	s_nop 0
	v_add_f32_e32 v103, v103, v105
	s_nop 1
	s_nop 0
	s_nop 0
	v_add_f32_dpp v103, v103, v103 quad_perm:[1,0,3,2] row_mask:0xf bank_mask:0xf
	v_fmamk_f32 v103, v103, 0x3c000000, v163
	v_cmp_gt_f32_e32 vcc, s86, v103
	v_mul_f32_e32 v105, 0x4b800000, v103
	s_nop 0
	v_cndmask_b32_e32 v103, v103, v105, vcc
	v_rsq_f32_e32 v103, v103
	s_nop 0
	v_mul_f32_e32 v105, 0x45800000, v103
	v_cndmask_b32_e32 v103, v103, v105, vcc
	global_load_ushort v105, v[126:127], off
	v_mul_f32_e32 v126, v242, v103
	global_load_dword v127, v[108:109], off
	v_mul_f32_e32 v124, v124, v103
	s_waitcnt vmcnt(1)
	v_lshlrev_b32_e32 v105, 16, v105
	v_mul_f32_e32 v105, 0xbfb8aa3b, v105
	v_exp_f32_e32 v105, v105
	s_waitcnt vmcnt(0)
	v_mul_f32_e32 v126, v127, v126
	v_add_f32_e32 v105, 1.0, v105
	v_rcp_f32_e32 v105, v105
	s_nop 0
	v_mul_f32_e32 v105, v105, v126
	v_cvt_pk_bf16_f32 v105, v105, s0
	v_lshl_add_u64 v[126:127], v[244:245], 0, v[112:113]
	global_store_short v[122:123], v105, off
	global_load_ushort v105, v[126:127], off
	v_mul_f32_e32 v126, v243, v103
	global_load_dword v127, v[110:111], off offset:128
	v_mul_f32_e32 v103, v125, v103
	s_waitcnt vmcnt(1)
	v_lshlrev_b32_e32 v105, 16, v105
	v_mul_f32_e32 v105, 0xbfb8aa3b, v105
	v_exp_f32_e32 v105, v105
	s_waitcnt vmcnt(0)
	v_mul_f32_e32 v126, v127, v126
	v_add_f32_e32 v105, 1.0, v105
	v_rcp_f32_e32 v105, v105
	s_nop 0
	v_mul_f32_e32 v105, v105, v126
	v_cvt_pk_bf16_f32 v105, v105, s0
	v_lshl_add_u64 v[126:127], v[244:245], 0, v[118:119]
	global_store_short v[122:123], v105, off offset:64
	global_load_ushort v105, v[126:127], off
	s_waitcnt vmcnt(0)
	v_lshlrev_b32_e32 v105, 16, v105
	global_load_dword v126, v[110:111], off offset:256
	v_mul_f32_e32 v105, 0xbfb8aa3b, v105
	v_exp_f32_e32 v105, v105
	s_waitcnt vmcnt(0)
	v_mul_f32_e32 v124, v126, v124
	v_add_f32_e32 v105, 1.0, v105
	v_rcp_f32_e32 v105, v105
	v_lshl_add_u64 v[126:127], v[244:245], 0, v[120:121]
	v_mul_f32_e32 v105, v124, v105
	v_cvt_pk_bf16_f32 v105, v105, s0
	global_store_short v[122:123], v105, off offset:128
	global_load_ushort v105, v[126:127], off
	s_waitcnt vmcnt(0)
	v_lshlrev_b32_e32 v105, 16, v105
	global_load_dword v124, v[110:111], off offset:384
	v_mul_f32_e32 v105, 0xbfb8aa3b, v105
	v_exp_f32_e32 v105, v105
	s_waitcnt vmcnt(0)
	v_mul_f32_e32 v103, v124, v103
	v_add_f32_e32 v105, 1.0, v105
	v_rcp_f32_e32 v105, v105
	s_nop 0
	v_mul_f32_e32 v103, v103, v105
	v_cvt_pk_bf16_f32 v103, v103, s0
	global_store_short v[122:123], v103, off offset:192
	ds_read_b32 v103, v238 offset:40
	ds_read_b32 v105, v239 offset:40
	v_add_u32_e32 v126, 10, v100
	v_ashrrev_i32_e32 v127, 31, v126
	v_mov_b32_e32 v244, v6
	s_waitcnt lgkmcnt(1)
	v_max_f32_e64 v103, |v103|, |v103|
	s_waitcnt lgkmcnt(0)
	v_max_f32_e32 v105, v105, v105
	v_max_f32_e32 v103, v103, v105
	v_div_scale_f32 v105, s[0:1], v103, v103, 1.0
	v_rcp_f32_e32 v122, v105
	v_mov_b32_e32 v245, v22
	v_fma_f32 v123, -v105, v122, 1.0
	v_fmac_f32_e32 v122, v123, v122
	v_div_scale_f32 v123, vcc, 1.0, v103, 1.0
	v_mul_f32_e32 v124, v123, v122
	v_fma_f32 v125, -v105, v124, v123
	v_fmac_f32_e32 v124, v125, v122
	v_fma_f32 v105, -v105, v124, v123
	v_div_fmas_f32 v105, v105, v122, v124
	v_lshlrev_b64 v[124:125], 11, v[126:127]
	v_lshl_add_u64 v[124:125], v[98:99], 0, v[124:125]
	global_load_dword v242, v[124:125], off
	global_load_dword v243, v[124:125], off offset:128
	global_load_dword v246, v[124:125], off offset:256
	global_load_dword v247, v[124:125], off offset:384
	v_div_fixup_f32 v122, v105, v103, 1.0
	v_mov_b32_e32 v124, v38
	v_mov_b32_e32 v125, v54
	s_waitcnt vmcnt(2)
	v_pk_fma_f32 v[242:243], v[244:245], v[122:123], v[242:243] op_sel_hi:[1,0,1]
	s_nop 0
	v_pk_mul_f32 v[244:245], v[242:243], v[242:243]
	s_waitcnt vmcnt(0)
	v_pk_fma_f32 v[124:125], v[124:125], v[122:123], v[246:247] op_sel_hi:[1,0,1]
	v_add_f32_e32 v103, v244, v245
	v_pk_mul_f32 v[122:123], v[124:125], v[124:125]
	s_nop 0
	v_add_f32_e32 v103, v103, v122
	v_add_f32_e32 v103, v103, v123
	v_mov_b32_e32 v105, v103
	v_mov_b32_e32 v255, v103
	s_nop 1
	v_permlane16_swap_b32_e32 v105, v255
	s_nop 1
	v_mov_b32_dpp v105, v255 quad_perm:[0,1,2,3] row_mask:0x5 bank_mask:0xf
	v_mad_i64_i32 v[122:123], s[0:1], v126, s74, v[106:107]
	v_lshl_add_u64 v[244:245], v[122:123], 0, s[96:97]
	v_lshlrev_b64 v[122:123], 10, v[126:127]
	s_nop 0
	v_add_f32_e32 v103, v103, v105
	s_nop 1
	v_mov_b32_dpp v105, v103 row_ror:8 row_mask:0xf bank_mask:0xf
	v_lshl_add_u64 v[126:127], v[244:245], 0, v[96:97]
	v_lshl_add_u64 v[122:123], s[66:67], 0, v[122:123]
	v_lshl_add_u64 v[122:123], v[122:123], 0, v[96:97]
	s_nop 0
	v_add_f32_e32 v103, v103, v105
	s_nop 1
	v_mov_b32_dpp v105, v103 row_shl:4 row_mask:0xf bank_mask:0x5
	v_mov_b32_dpp v105, v103 row_shr:4 row_mask:0xf bank_mask:0xa
	s_nop 0
	v_add_f32_e32 v103, v103, v105
	s_nop 1
	v_mov_b32_dpp v105, v103 quad_perm:[2,3,0,1] row_mask:0xf bank_mask:0xf
	s_nop 0
	v_add_f32_e32 v103, v103, v105
	s_nop 1
	s_nop 0
	s_nop 0
	v_add_f32_dpp v103, v103, v103 quad_perm:[1,0,3,2] row_mask:0xf bank_mask:0xf
	v_fmamk_f32 v103, v103, 0x3c000000, v163
	v_cmp_gt_f32_e32 vcc, s86, v103
	v_mul_f32_e32 v105, 0x4b800000, v103
	s_nop 0
	v_cndmask_b32_e32 v103, v103, v105, vcc
	v_rsq_f32_e32 v103, v103
	s_nop 0
	v_mul_f32_e32 v105, 0x45800000, v103
	v_cndmask_b32_e32 v103, v103, v105, vcc
	global_load_ushort v105, v[126:127], off
	v_mul_f32_e32 v126, v242, v103
	global_load_dword v127, v[108:109], off
	v_mul_f32_e32 v124, v124, v103
	s_waitcnt vmcnt(1)
	v_lshlrev_b32_e32 v105, 16, v105
	v_mul_f32_e32 v105, 0xbfb8aa3b, v105
	v_exp_f32_e32 v105, v105
	s_waitcnt vmcnt(0)
	v_mul_f32_e32 v126, v127, v126
	v_add_f32_e32 v105, 1.0, v105
	v_rcp_f32_e32 v105, v105
	s_nop 0
	v_mul_f32_e32 v105, v105, v126
	v_cvt_pk_bf16_f32 v105, v105, s0
	v_lshl_add_u64 v[126:127], v[244:245], 0, v[112:113]
	global_store_short v[122:123], v105, off
	global_load_ushort v105, v[126:127], off
	v_mul_f32_e32 v126, v243, v103
	global_load_dword v127, v[110:111], off offset:128
	v_mul_f32_e32 v103, v125, v103
	s_waitcnt vmcnt(1)
	v_lshlrev_b32_e32 v105, 16, v105
	v_mul_f32_e32 v105, 0xbfb8aa3b, v105
	v_exp_f32_e32 v105, v105
	s_waitcnt vmcnt(0)
	v_mul_f32_e32 v126, v127, v126
	v_add_f32_e32 v105, 1.0, v105
	v_rcp_f32_e32 v105, v105
	s_nop 0
	v_mul_f32_e32 v105, v105, v126
	v_cvt_pk_bf16_f32 v105, v105, s0
	v_lshl_add_u64 v[126:127], v[244:245], 0, v[118:119]
	global_store_short v[122:123], v105, off offset:64
	global_load_ushort v105, v[126:127], off
	s_waitcnt vmcnt(0)
	v_lshlrev_b32_e32 v105, 16, v105
	global_load_dword v126, v[110:111], off offset:256
	v_mul_f32_e32 v105, 0xbfb8aa3b, v105
	v_exp_f32_e32 v105, v105
	s_waitcnt vmcnt(0)
	v_mul_f32_e32 v124, v126, v124
	v_add_f32_e32 v105, 1.0, v105
	v_rcp_f32_e32 v105, v105
	v_lshl_add_u64 v[126:127], v[244:245], 0, v[120:121]
	v_mul_f32_e32 v105, v124, v105
	v_cvt_pk_bf16_f32 v105, v105, s0
	global_store_short v[122:123], v105, off offset:128
	global_load_ushort v105, v[126:127], off
	s_waitcnt vmcnt(0)
	v_lshlrev_b32_e32 v105, 16, v105
	global_load_dword v124, v[110:111], off offset:384
	v_mul_f32_e32 v105, 0xbfb8aa3b, v105
	v_exp_f32_e32 v105, v105
	s_waitcnt vmcnt(0)
	v_mul_f32_e32 v103, v124, v103
	v_add_f32_e32 v105, 1.0, v105
	v_rcp_f32_e32 v105, v105
	s_nop 0
	v_mul_f32_e32 v103, v103, v105
	v_cvt_pk_bf16_f32 v103, v103, s0
	global_store_short v[122:123], v103, off offset:192
	ds_read_b32 v103, v238 offset:44
	ds_read_b32 v105, v239 offset:44
	v_add_u32_e32 v126, 11, v100
	v_ashrrev_i32_e32 v127, 31, v126
	v_mov_b32_e32 v244, v7
	s_waitcnt lgkmcnt(1)
	v_max_f32_e64 v103, |v103|, |v103|
	s_waitcnt lgkmcnt(0)
	v_max_f32_e32 v105, v105, v105
	v_max_f32_e32 v103, v103, v105
	v_div_scale_f32 v105, s[0:1], v103, v103, 1.0
	v_rcp_f32_e32 v122, v105
	v_mov_b32_e32 v245, v23
	v_fma_f32 v123, -v105, v122, 1.0
	v_fmac_f32_e32 v122, v123, v122
	v_div_scale_f32 v123, vcc, 1.0, v103, 1.0
	v_mul_f32_e32 v124, v123, v122
	v_fma_f32 v125, -v105, v124, v123
	v_fmac_f32_e32 v124, v125, v122
	v_fma_f32 v105, -v105, v124, v123
	v_div_fmas_f32 v105, v105, v122, v124
	v_lshlrev_b64 v[124:125], 11, v[126:127]
	v_lshl_add_u64 v[124:125], v[98:99], 0, v[124:125]
	global_load_dword v242, v[124:125], off
	global_load_dword v243, v[124:125], off offset:128
	global_load_dword v246, v[124:125], off offset:256
	global_load_dword v247, v[124:125], off offset:384
	v_div_fixup_f32 v122, v105, v103, 1.0
	v_mov_b32_e32 v124, v39
	v_mov_b32_e32 v125, v55
	s_waitcnt vmcnt(2)
	v_pk_fma_f32 v[242:243], v[244:245], v[122:123], v[242:243] op_sel_hi:[1,0,1]
	s_nop 0
	v_pk_mul_f32 v[244:245], v[242:243], v[242:243]
	s_waitcnt vmcnt(0)
	v_pk_fma_f32 v[124:125], v[124:125], v[122:123], v[246:247] op_sel_hi:[1,0,1]
	v_add_f32_e32 v103, v244, v245
	v_pk_mul_f32 v[122:123], v[124:125], v[124:125]
	s_nop 0
	v_add_f32_e32 v103, v103, v122
	v_add_f32_e32 v103, v103, v123
	v_mov_b32_e32 v105, v103
	v_mov_b32_e32 v255, v103
	s_nop 1
	v_permlane16_swap_b32_e32 v105, v255
	s_nop 1
	v_mov_b32_dpp v105, v255 quad_perm:[0,1,2,3] row_mask:0x5 bank_mask:0xf
	v_mad_i64_i32 v[122:123], s[0:1], v126, s74, v[106:107]
	v_lshl_add_u64 v[244:245], v[122:123], 0, s[96:97]
	v_lshlrev_b64 v[122:123], 10, v[126:127]
	s_nop 0
	v_add_f32_e32 v103, v103, v105
	s_nop 1
	v_mov_b32_dpp v105, v103 row_ror:8 row_mask:0xf bank_mask:0xf
	v_lshl_add_u64 v[126:127], v[244:245], 0, v[96:97]
	v_lshl_add_u64 v[122:123], s[66:67], 0, v[122:123]
	v_lshl_add_u64 v[122:123], v[122:123], 0, v[96:97]
	s_nop 0
	v_add_f32_e32 v103, v103, v105
	s_nop 1
	v_mov_b32_dpp v105, v103 row_shl:4 row_mask:0xf bank_mask:0x5
	v_mov_b32_dpp v105, v103 row_shr:4 row_mask:0xf bank_mask:0xa
	s_nop 0
	v_add_f32_e32 v103, v103, v105
	s_nop 1
	v_mov_b32_dpp v105, v103 quad_perm:[2,3,0,1] row_mask:0xf bank_mask:0xf
	s_nop 0
	v_add_f32_e32 v103, v103, v105
	s_nop 1
	s_nop 0
	s_nop 0
	v_add_f32_dpp v103, v103, v103 quad_perm:[1,0,3,2] row_mask:0xf bank_mask:0xf
	v_fmamk_f32 v103, v103, 0x3c000000, v163
	v_cmp_gt_f32_e32 vcc, s86, v103
	v_mul_f32_e32 v105, 0x4b800000, v103
	s_nop 0
	v_cndmask_b32_e32 v103, v103, v105, vcc
	v_rsq_f32_e32 v103, v103
	s_nop 0
	v_mul_f32_e32 v105, 0x45800000, v103
	v_cndmask_b32_e32 v103, v103, v105, vcc
	global_load_ushort v105, v[126:127], off
	v_mul_f32_e32 v126, v242, v103
	global_load_dword v127, v[108:109], off
	v_mul_f32_e32 v124, v124, v103
	s_waitcnt vmcnt(1)
	v_lshlrev_b32_e32 v105, 16, v105
	v_mul_f32_e32 v105, 0xbfb8aa3b, v105
	v_exp_f32_e32 v105, v105
	s_waitcnt vmcnt(0)
	v_mul_f32_e32 v126, v127, v126
	v_add_f32_e32 v105, 1.0, v105
	v_rcp_f32_e32 v105, v105
	s_nop 0
	v_mul_f32_e32 v105, v105, v126
	v_cvt_pk_bf16_f32 v105, v105, s0
	v_lshl_add_u64 v[126:127], v[244:245], 0, v[112:113]
	global_store_short v[122:123], v105, off
	global_load_ushort v105, v[126:127], off
	v_mul_f32_e32 v126, v243, v103
	global_load_dword v127, v[110:111], off offset:128
	v_mul_f32_e32 v103, v125, v103
	s_waitcnt vmcnt(1)
	v_lshlrev_b32_e32 v105, 16, v105
	v_mul_f32_e32 v105, 0xbfb8aa3b, v105
	v_exp_f32_e32 v105, v105
	s_waitcnt vmcnt(0)
	v_mul_f32_e32 v126, v127, v126
	v_add_f32_e32 v105, 1.0, v105
	v_rcp_f32_e32 v105, v105
	s_nop 0
	v_mul_f32_e32 v105, v105, v126
	v_cvt_pk_bf16_f32 v105, v105, s0
	v_lshl_add_u64 v[126:127], v[244:245], 0, v[118:119]
	global_store_short v[122:123], v105, off offset:64
	global_load_ushort v105, v[126:127], off
	s_waitcnt vmcnt(0)
	v_lshlrev_b32_e32 v105, 16, v105
	global_load_dword v126, v[110:111], off offset:256
	v_mul_f32_e32 v105, 0xbfb8aa3b, v105
	v_exp_f32_e32 v105, v105
	s_waitcnt vmcnt(0)
	v_mul_f32_e32 v124, v126, v124
	v_add_f32_e32 v105, 1.0, v105
	v_rcp_f32_e32 v105, v105
	v_lshl_add_u64 v[126:127], v[244:245], 0, v[120:121]
	v_mul_f32_e32 v105, v124, v105
	v_cvt_pk_bf16_f32 v105, v105, s0
	global_store_short v[122:123], v105, off offset:128
	global_load_ushort v105, v[126:127], off
	s_waitcnt vmcnt(0)
	v_lshlrev_b32_e32 v105, 16, v105
	global_load_dword v124, v[110:111], off offset:384
	v_mul_f32_e32 v105, 0xbfb8aa3b, v105
	v_exp_f32_e32 v105, v105
	s_waitcnt vmcnt(0)
	v_mul_f32_e32 v103, v124, v103
	v_add_f32_e32 v105, 1.0, v105
	v_rcp_f32_e32 v105, v105
	s_nop 0
	v_mul_f32_e32 v103, v103, v105
	v_cvt_pk_bf16_f32 v103, v103, s0
	global_store_short v[122:123], v103, off offset:192
	ds_read_b32 v103, v238 offset:64
	ds_read_b32 v105, v239 offset:64
	v_add_u32_e32 v126, 16, v100
	v_ashrrev_i32_e32 v127, 31, v126
	v_mov_b32_e32 v244, v8
	s_waitcnt lgkmcnt(1)
	v_max_f32_e64 v103, |v103|, |v103|
	s_waitcnt lgkmcnt(0)
	v_max_f32_e32 v105, v105, v105
	v_max_f32_e32 v103, v103, v105
	v_div_scale_f32 v105, s[0:1], v103, v103, 1.0
	v_rcp_f32_e32 v122, v105
	v_mov_b32_e32 v245, v24
	v_fma_f32 v123, -v105, v122, 1.0
	v_fmac_f32_e32 v122, v123, v122
	v_div_scale_f32 v123, vcc, 1.0, v103, 1.0
	v_mul_f32_e32 v124, v123, v122
	v_fma_f32 v125, -v105, v124, v123
	v_fmac_f32_e32 v124, v125, v122
	v_fma_f32 v105, -v105, v124, v123
	v_div_fmas_f32 v105, v105, v122, v124
	v_lshlrev_b64 v[124:125], 11, v[126:127]
	v_lshl_add_u64 v[124:125], v[98:99], 0, v[124:125]
	global_load_dword v242, v[124:125], off
	global_load_dword v243, v[124:125], off offset:128
	global_load_dword v246, v[124:125], off offset:256
	global_load_dword v247, v[124:125], off offset:384
	v_div_fixup_f32 v122, v105, v103, 1.0
	v_mov_b32_e32 v124, v40
	v_mov_b32_e32 v125, v56
	s_waitcnt vmcnt(2)
	v_pk_fma_f32 v[242:243], v[244:245], v[122:123], v[242:243] op_sel_hi:[1,0,1]
	s_nop 0
	v_pk_mul_f32 v[244:245], v[242:243], v[242:243]
	s_waitcnt vmcnt(0)
	v_pk_fma_f32 v[124:125], v[124:125], v[122:123], v[246:247] op_sel_hi:[1,0,1]
	v_add_f32_e32 v103, v244, v245
	v_pk_mul_f32 v[122:123], v[124:125], v[124:125]
	s_nop 0
	v_add_f32_e32 v103, v103, v122
	v_add_f32_e32 v103, v103, v123
	v_mov_b32_e32 v105, v103
	v_mov_b32_e32 v255, v103
	s_nop 1
	v_permlane16_swap_b32_e32 v105, v255
	s_nop 1
	v_mov_b32_dpp v105, v255 quad_perm:[0,1,2,3] row_mask:0x5 bank_mask:0xf
	v_mad_i64_i32 v[122:123], s[0:1], v126, s74, v[106:107]
	v_lshl_add_u64 v[244:245], v[122:123], 0, s[96:97]
	v_lshlrev_b64 v[122:123], 10, v[126:127]
	s_nop 0
	v_add_f32_e32 v103, v103, v105
	s_nop 1
	v_mov_b32_dpp v105, v103 row_ror:8 row_mask:0xf bank_mask:0xf
	v_lshl_add_u64 v[126:127], v[244:245], 0, v[96:97]
	v_lshl_add_u64 v[122:123], s[66:67], 0, v[122:123]
	v_lshl_add_u64 v[122:123], v[122:123], 0, v[96:97]
	s_nop 0
	v_add_f32_e32 v103, v103, v105
	s_nop 1
	v_mov_b32_dpp v105, v103 row_shl:4 row_mask:0xf bank_mask:0x5
	v_mov_b32_dpp v105, v103 row_shr:4 row_mask:0xf bank_mask:0xa
	s_nop 0
	v_add_f32_e32 v103, v103, v105
	s_nop 1
	v_mov_b32_dpp v105, v103 quad_perm:[2,3,0,1] row_mask:0xf bank_mask:0xf
	s_nop 0
	v_add_f32_e32 v103, v103, v105
	s_nop 1
	s_nop 0
	s_nop 0
	v_add_f32_dpp v103, v103, v103 quad_perm:[1,0,3,2] row_mask:0xf bank_mask:0xf
	v_fmamk_f32 v103, v103, 0x3c000000, v163
	v_cmp_gt_f32_e32 vcc, s86, v103
	v_mul_f32_e32 v105, 0x4b800000, v103
	s_nop 0
	v_cndmask_b32_e32 v103, v103, v105, vcc
	v_rsq_f32_e32 v103, v103
	s_nop 0
	v_mul_f32_e32 v105, 0x45800000, v103
	v_cndmask_b32_e32 v103, v103, v105, vcc
	global_load_ushort v105, v[126:127], off
	v_mul_f32_e32 v126, v242, v103
	global_load_dword v127, v[108:109], off
	v_mul_f32_e32 v124, v124, v103
	s_waitcnt vmcnt(1)
	v_lshlrev_b32_e32 v105, 16, v105
	v_mul_f32_e32 v105, 0xbfb8aa3b, v105
	v_exp_f32_e32 v105, v105
	s_waitcnt vmcnt(0)
	v_mul_f32_e32 v126, v127, v126
	v_add_f32_e32 v105, 1.0, v105
	v_rcp_f32_e32 v105, v105
	s_nop 0
	v_mul_f32_e32 v105, v105, v126
	v_cvt_pk_bf16_f32 v105, v105, s0
	v_lshl_add_u64 v[126:127], v[244:245], 0, v[112:113]
	global_store_short v[122:123], v105, off
	global_load_ushort v105, v[126:127], off
	v_mul_f32_e32 v126, v243, v103
	global_load_dword v127, v[110:111], off offset:128
	v_mul_f32_e32 v103, v125, v103
	s_waitcnt vmcnt(1)
	v_lshlrev_b32_e32 v105, 16, v105
	v_mul_f32_e32 v105, 0xbfb8aa3b, v105
	v_exp_f32_e32 v105, v105
	s_waitcnt vmcnt(0)
	v_mul_f32_e32 v126, v127, v126
	v_add_f32_e32 v105, 1.0, v105
	v_rcp_f32_e32 v105, v105
	s_nop 0
	v_mul_f32_e32 v105, v105, v126
	v_cvt_pk_bf16_f32 v105, v105, s0
	v_lshl_add_u64 v[126:127], v[244:245], 0, v[118:119]
	global_store_short v[122:123], v105, off offset:64
	global_load_ushort v105, v[126:127], off
	s_waitcnt vmcnt(0)
	v_lshlrev_b32_e32 v105, 16, v105
	global_load_dword v126, v[110:111], off offset:256
	v_mul_f32_e32 v105, 0xbfb8aa3b, v105
	v_exp_f32_e32 v105, v105
	s_waitcnt vmcnt(0)
	v_mul_f32_e32 v124, v126, v124
	v_add_f32_e32 v105, 1.0, v105
	v_rcp_f32_e32 v105, v105
	v_lshl_add_u64 v[126:127], v[244:245], 0, v[120:121]
	v_mul_f32_e32 v105, v124, v105
	v_cvt_pk_bf16_f32 v105, v105, s0
	global_store_short v[122:123], v105, off offset:128
	global_load_ushort v105, v[126:127], off
	s_waitcnt vmcnt(0)
	v_lshlrev_b32_e32 v105, 16, v105
	global_load_dword v124, v[110:111], off offset:384
	v_mul_f32_e32 v105, 0xbfb8aa3b, v105
	v_exp_f32_e32 v105, v105
	s_waitcnt vmcnt(0)
	v_mul_f32_e32 v103, v124, v103
	v_add_f32_e32 v105, 1.0, v105
	v_rcp_f32_e32 v105, v105
	s_nop 0
	v_mul_f32_e32 v103, v103, v105
	v_cvt_pk_bf16_f32 v103, v103, s0
	global_store_short v[122:123], v103, off offset:192
	ds_read_b32 v103, v238 offset:68
	ds_read_b32 v105, v239 offset:68
	v_add_u32_e32 v126, 17, v100
	v_ashrrev_i32_e32 v127, 31, v126
	v_mov_b32_e32 v244, v9
	s_waitcnt lgkmcnt(1)
	v_max_f32_e64 v103, |v103|, |v103|
	s_waitcnt lgkmcnt(0)
	v_max_f32_e32 v105, v105, v105
	v_max_f32_e32 v103, v103, v105
	v_div_scale_f32 v105, s[0:1], v103, v103, 1.0
	v_rcp_f32_e32 v122, v105
	v_mov_b32_e32 v245, v25
	v_fma_f32 v123, -v105, v122, 1.0
	v_fmac_f32_e32 v122, v123, v122
	v_div_scale_f32 v123, vcc, 1.0, v103, 1.0
	v_mul_f32_e32 v124, v123, v122
	v_fma_f32 v125, -v105, v124, v123
	v_fmac_f32_e32 v124, v125, v122
	v_fma_f32 v105, -v105, v124, v123
	v_div_fmas_f32 v105, v105, v122, v124
	v_lshlrev_b64 v[124:125], 11, v[126:127]
	v_lshl_add_u64 v[124:125], v[98:99], 0, v[124:125]
	global_load_dword v242, v[124:125], off
	global_load_dword v243, v[124:125], off offset:128
	global_load_dword v246, v[124:125], off offset:256
	global_load_dword v247, v[124:125], off offset:384
	v_div_fixup_f32 v122, v105, v103, 1.0
	v_mov_b32_e32 v124, v41
	v_mov_b32_e32 v125, v57
	s_waitcnt vmcnt(2)
	v_pk_fma_f32 v[242:243], v[244:245], v[122:123], v[242:243] op_sel_hi:[1,0,1]
	s_nop 0
	v_pk_mul_f32 v[244:245], v[242:243], v[242:243]
	s_waitcnt vmcnt(0)
	v_pk_fma_f32 v[124:125], v[124:125], v[122:123], v[246:247] op_sel_hi:[1,0,1]
	v_add_f32_e32 v103, v244, v245
	v_pk_mul_f32 v[122:123], v[124:125], v[124:125]
	s_nop 0
	v_add_f32_e32 v103, v103, v122
	v_add_f32_e32 v103, v103, v123
	v_mov_b32_e32 v105, v103
	v_mov_b32_e32 v255, v103
	s_nop 1
	v_permlane16_swap_b32_e32 v105, v255
	s_nop 1
	v_mov_b32_dpp v105, v255 quad_perm:[0,1,2,3] row_mask:0x5 bank_mask:0xf
	v_mad_i64_i32 v[122:123], s[0:1], v126, s74, v[106:107]
	v_lshl_add_u64 v[244:245], v[122:123], 0, s[96:97]
	v_lshlrev_b64 v[122:123], 10, v[126:127]
	s_nop 0
	v_add_f32_e32 v103, v103, v105
	s_nop 1
	v_mov_b32_dpp v105, v103 row_ror:8 row_mask:0xf bank_mask:0xf
	v_lshl_add_u64 v[126:127], v[244:245], 0, v[96:97]
	v_lshl_add_u64 v[122:123], s[66:67], 0, v[122:123]
	v_lshl_add_u64 v[122:123], v[122:123], 0, v[96:97]
	s_nop 0
	v_add_f32_e32 v103, v103, v105
	s_nop 1
	v_mov_b32_dpp v105, v103 row_shl:4 row_mask:0xf bank_mask:0x5
	v_mov_b32_dpp v105, v103 row_shr:4 row_mask:0xf bank_mask:0xa
	s_nop 0
	v_add_f32_e32 v103, v103, v105
	s_nop 1
	v_mov_b32_dpp v105, v103 quad_perm:[2,3,0,1] row_mask:0xf bank_mask:0xf
	s_nop 0
	v_add_f32_e32 v103, v103, v105
	s_nop 1
	s_nop 0
	s_nop 0
	v_add_f32_dpp v103, v103, v103 quad_perm:[1,0,3,2] row_mask:0xf bank_mask:0xf
	v_fmamk_f32 v103, v103, 0x3c000000, v163
	v_cmp_gt_f32_e32 vcc, s86, v103
	v_mul_f32_e32 v105, 0x4b800000, v103
	s_nop 0
	v_cndmask_b32_e32 v103, v103, v105, vcc
	v_rsq_f32_e32 v103, v103
	s_nop 0
	v_mul_f32_e32 v105, 0x45800000, v103
	v_cndmask_b32_e32 v103, v103, v105, vcc
	global_load_ushort v105, v[126:127], off
	v_mul_f32_e32 v126, v242, v103
	global_load_dword v127, v[108:109], off
	v_mul_f32_e32 v124, v124, v103
	s_waitcnt vmcnt(1)
	v_lshlrev_b32_e32 v105, 16, v105
	v_mul_f32_e32 v105, 0xbfb8aa3b, v105
	v_exp_f32_e32 v105, v105
	s_waitcnt vmcnt(0)
	v_mul_f32_e32 v126, v127, v126
	v_add_f32_e32 v105, 1.0, v105
	v_rcp_f32_e32 v105, v105
	s_nop 0
	v_mul_f32_e32 v105, v105, v126
	v_cvt_pk_bf16_f32 v105, v105, s0
	v_lshl_add_u64 v[126:127], v[244:245], 0, v[112:113]
	global_store_short v[122:123], v105, off
	global_load_ushort v105, v[126:127], off
	v_mul_f32_e32 v126, v243, v103
	global_load_dword v127, v[110:111], off offset:128
	v_mul_f32_e32 v103, v125, v103
	s_waitcnt vmcnt(1)
	v_lshlrev_b32_e32 v105, 16, v105
	v_mul_f32_e32 v105, 0xbfb8aa3b, v105
	v_exp_f32_e32 v105, v105
	s_waitcnt vmcnt(0)
	v_mul_f32_e32 v126, v127, v126
	v_add_f32_e32 v105, 1.0, v105
	v_rcp_f32_e32 v105, v105
	s_nop 0
	v_mul_f32_e32 v105, v105, v126
	v_cvt_pk_bf16_f32 v105, v105, s0
	v_lshl_add_u64 v[126:127], v[244:245], 0, v[118:119]
	global_store_short v[122:123], v105, off offset:64
	global_load_ushort v105, v[126:127], off
	s_waitcnt vmcnt(0)
	v_lshlrev_b32_e32 v105, 16, v105
	global_load_dword v126, v[110:111], off offset:256
	v_mul_f32_e32 v105, 0xbfb8aa3b, v105
	v_exp_f32_e32 v105, v105
	s_waitcnt vmcnt(0)
	v_mul_f32_e32 v124, v126, v124
	v_add_f32_e32 v105, 1.0, v105
	v_rcp_f32_e32 v105, v105
	v_lshl_add_u64 v[126:127], v[244:245], 0, v[120:121]
	v_mul_f32_e32 v105, v124, v105
	v_cvt_pk_bf16_f32 v105, v105, s0
	global_store_short v[122:123], v105, off offset:128
	global_load_ushort v105, v[126:127], off
	s_waitcnt vmcnt(0)
	v_lshlrev_b32_e32 v105, 16, v105
	global_load_dword v124, v[110:111], off offset:384
	v_mul_f32_e32 v105, 0xbfb8aa3b, v105
	v_exp_f32_e32 v105, v105
	s_waitcnt vmcnt(0)
	v_mul_f32_e32 v103, v124, v103
	v_add_f32_e32 v105, 1.0, v105
	v_rcp_f32_e32 v105, v105
	s_nop 0
	v_mul_f32_e32 v103, v103, v105
	v_cvt_pk_bf16_f32 v103, v103, s0
	global_store_short v[122:123], v103, off offset:192
	ds_read_b32 v103, v238 offset:72
	ds_read_b32 v105, v239 offset:72
	v_add_u32_e32 v126, 18, v100
	v_ashrrev_i32_e32 v127, 31, v126
	v_mov_b32_e32 v244, v10
	s_waitcnt lgkmcnt(1)
	v_max_f32_e64 v103, |v103|, |v103|
	s_waitcnt lgkmcnt(0)
	v_max_f32_e32 v105, v105, v105
	v_max_f32_e32 v103, v103, v105
	v_div_scale_f32 v105, s[0:1], v103, v103, 1.0
	v_rcp_f32_e32 v122, v105
	v_mov_b32_e32 v245, v26
	v_fma_f32 v123, -v105, v122, 1.0
	v_fmac_f32_e32 v122, v123, v122
	v_div_scale_f32 v123, vcc, 1.0, v103, 1.0
	v_mul_f32_e32 v124, v123, v122
	v_fma_f32 v125, -v105, v124, v123
	v_fmac_f32_e32 v124, v125, v122
	v_fma_f32 v105, -v105, v124, v123
	v_div_fmas_f32 v105, v105, v122, v124
	v_lshlrev_b64 v[124:125], 11, v[126:127]
	v_lshl_add_u64 v[124:125], v[98:99], 0, v[124:125]
	global_load_dword v242, v[124:125], off
	global_load_dword v243, v[124:125], off offset:128
	global_load_dword v246, v[124:125], off offset:256
	global_load_dword v247, v[124:125], off offset:384
	v_div_fixup_f32 v122, v105, v103, 1.0
	v_mov_b32_e32 v124, v42
	v_mov_b32_e32 v125, v58
	s_waitcnt vmcnt(2)
	v_pk_fma_f32 v[242:243], v[244:245], v[122:123], v[242:243] op_sel_hi:[1,0,1]
	s_nop 0
	v_pk_mul_f32 v[244:245], v[242:243], v[242:243]
	s_waitcnt vmcnt(0)
	v_pk_fma_f32 v[124:125], v[124:125], v[122:123], v[246:247] op_sel_hi:[1,0,1]
	v_add_f32_e32 v103, v244, v245
	v_pk_mul_f32 v[122:123], v[124:125], v[124:125]
	s_nop 0
	v_add_f32_e32 v103, v103, v122
	v_add_f32_e32 v103, v103, v123
	v_mov_b32_e32 v105, v103
	v_mov_b32_e32 v255, v103
	s_nop 1
	v_permlane16_swap_b32_e32 v105, v255
	s_nop 1
	v_mov_b32_dpp v105, v255 quad_perm:[0,1,2,3] row_mask:0x5 bank_mask:0xf
	v_mad_i64_i32 v[122:123], s[0:1], v126, s74, v[106:107]
	v_lshl_add_u64 v[244:245], v[122:123], 0, s[96:97]
	v_lshlrev_b64 v[122:123], 10, v[126:127]
	s_nop 0
	v_add_f32_e32 v103, v103, v105
	s_nop 1
	v_mov_b32_dpp v105, v103 row_ror:8 row_mask:0xf bank_mask:0xf
	v_lshl_add_u64 v[126:127], v[244:245], 0, v[96:97]
	v_lshl_add_u64 v[122:123], s[66:67], 0, v[122:123]
	v_lshl_add_u64 v[122:123], v[122:123], 0, v[96:97]
	s_nop 0
	v_add_f32_e32 v103, v103, v105
	s_nop 1
	v_mov_b32_dpp v105, v103 row_shl:4 row_mask:0xf bank_mask:0x5
	v_mov_b32_dpp v105, v103 row_shr:4 row_mask:0xf bank_mask:0xa
	s_nop 0
	v_add_f32_e32 v103, v103, v105
	s_nop 1
	v_mov_b32_dpp v105, v103 quad_perm:[2,3,0,1] row_mask:0xf bank_mask:0xf
	s_nop 0
	v_add_f32_e32 v103, v103, v105
	s_nop 1
	s_nop 0
	s_nop 0
	v_add_f32_dpp v103, v103, v103 quad_perm:[1,0,3,2] row_mask:0xf bank_mask:0xf
	v_fmamk_f32 v103, v103, 0x3c000000, v163
	v_cmp_gt_f32_e32 vcc, s86, v103
	v_mul_f32_e32 v105, 0x4b800000, v103
	s_nop 0
	v_cndmask_b32_e32 v103, v103, v105, vcc
	v_rsq_f32_e32 v103, v103
	s_nop 0
	v_mul_f32_e32 v105, 0x45800000, v103
	v_cndmask_b32_e32 v103, v103, v105, vcc
	global_load_ushort v105, v[126:127], off
	v_mul_f32_e32 v126, v242, v103
	global_load_dword v127, v[108:109], off
	v_mul_f32_e32 v124, v124, v103
	s_waitcnt vmcnt(1)
	v_lshlrev_b32_e32 v105, 16, v105
	v_mul_f32_e32 v105, 0xbfb8aa3b, v105
	v_exp_f32_e32 v105, v105
	s_waitcnt vmcnt(0)
	v_mul_f32_e32 v126, v127, v126
	v_add_f32_e32 v105, 1.0, v105
	v_rcp_f32_e32 v105, v105
	s_nop 0
	v_mul_f32_e32 v105, v105, v126
	v_cvt_pk_bf16_f32 v105, v105, s0
	v_lshl_add_u64 v[126:127], v[244:245], 0, v[112:113]
	global_store_short v[122:123], v105, off
	global_load_ushort v105, v[126:127], off
	v_mul_f32_e32 v126, v243, v103
	global_load_dword v127, v[110:111], off offset:128
	v_mul_f32_e32 v103, v125, v103
	s_waitcnt vmcnt(1)
	v_lshlrev_b32_e32 v105, 16, v105
	v_mul_f32_e32 v105, 0xbfb8aa3b, v105
	v_exp_f32_e32 v105, v105
	s_waitcnt vmcnt(0)
	v_mul_f32_e32 v126, v127, v126
	v_add_f32_e32 v105, 1.0, v105
	v_rcp_f32_e32 v105, v105
	s_nop 0
	v_mul_f32_e32 v105, v105, v126
	v_cvt_pk_bf16_f32 v105, v105, s0
	v_lshl_add_u64 v[126:127], v[244:245], 0, v[118:119]
	global_store_short v[122:123], v105, off offset:64
	global_load_ushort v105, v[126:127], off
	s_waitcnt vmcnt(0)
	v_lshlrev_b32_e32 v105, 16, v105
	global_load_dword v126, v[110:111], off offset:256
	v_mul_f32_e32 v105, 0xbfb8aa3b, v105
	v_exp_f32_e32 v105, v105
	s_waitcnt vmcnt(0)
	v_mul_f32_e32 v124, v126, v124
	v_add_f32_e32 v105, 1.0, v105
	v_rcp_f32_e32 v105, v105
	v_lshl_add_u64 v[126:127], v[244:245], 0, v[120:121]
	v_mul_f32_e32 v105, v124, v105
	v_cvt_pk_bf16_f32 v105, v105, s0
	global_store_short v[122:123], v105, off offset:128
	global_load_ushort v105, v[126:127], off
	s_waitcnt vmcnt(0)
	v_lshlrev_b32_e32 v105, 16, v105
	global_load_dword v124, v[110:111], off offset:384
	v_mul_f32_e32 v105, 0xbfb8aa3b, v105
	v_exp_f32_e32 v105, v105
	s_waitcnt vmcnt(0)
	v_mul_f32_e32 v103, v124, v103
	v_add_f32_e32 v105, 1.0, v105
	v_rcp_f32_e32 v105, v105
	s_nop 0
	v_mul_f32_e32 v103, v103, v105
	v_cvt_pk_bf16_f32 v103, v103, s0
	global_store_short v[122:123], v103, off offset:192
	ds_read_b32 v103, v238 offset:76
	ds_read_b32 v105, v239 offset:76
	v_add_u32_e32 v126, 19, v100
	v_ashrrev_i32_e32 v127, 31, v126
	v_mov_b32_e32 v244, v11
	s_waitcnt lgkmcnt(1)
	v_max_f32_e64 v103, |v103|, |v103|
	s_waitcnt lgkmcnt(0)
	v_max_f32_e32 v105, v105, v105
	v_max_f32_e32 v103, v103, v105
	v_div_scale_f32 v105, s[0:1], v103, v103, 1.0
	v_rcp_f32_e32 v122, v105
	v_mov_b32_e32 v245, v27
	v_fma_f32 v123, -v105, v122, 1.0
	v_fmac_f32_e32 v122, v123, v122
	v_div_scale_f32 v123, vcc, 1.0, v103, 1.0
	v_mul_f32_e32 v124, v123, v122
	v_fma_f32 v125, -v105, v124, v123
	v_fmac_f32_e32 v124, v125, v122
	v_fma_f32 v105, -v105, v124, v123
	v_div_fmas_f32 v105, v105, v122, v124
	v_lshlrev_b64 v[124:125], 11, v[126:127]
	v_lshl_add_u64 v[124:125], v[98:99], 0, v[124:125]
	global_load_dword v242, v[124:125], off
	global_load_dword v243, v[124:125], off offset:128
	global_load_dword v246, v[124:125], off offset:256
	global_load_dword v247, v[124:125], off offset:384
	v_div_fixup_f32 v122, v105, v103, 1.0
	v_mov_b32_e32 v124, v43
	v_mov_b32_e32 v125, v59
	s_waitcnt vmcnt(2)
	v_pk_fma_f32 v[242:243], v[244:245], v[122:123], v[242:243] op_sel_hi:[1,0,1]
	s_nop 0
	v_pk_mul_f32 v[244:245], v[242:243], v[242:243]
	s_waitcnt vmcnt(0)
	v_pk_fma_f32 v[124:125], v[124:125], v[122:123], v[246:247] op_sel_hi:[1,0,1]
	v_add_f32_e32 v103, v244, v245
	v_pk_mul_f32 v[122:123], v[124:125], v[124:125]
	s_nop 0
	v_add_f32_e32 v103, v103, v122
	v_add_f32_e32 v103, v103, v123
	v_mov_b32_e32 v105, v103
	v_mov_b32_e32 v255, v103
	s_nop 1
	v_permlane16_swap_b32_e32 v105, v255
	s_nop 1
	v_mov_b32_dpp v105, v255 quad_perm:[0,1,2,3] row_mask:0x5 bank_mask:0xf
	v_mad_i64_i32 v[122:123], s[0:1], v126, s74, v[106:107]
	v_lshl_add_u64 v[244:245], v[122:123], 0, s[96:97]
	v_lshlrev_b64 v[122:123], 10, v[126:127]
	s_nop 0
	v_add_f32_e32 v103, v103, v105
	s_nop 1
	v_mov_b32_dpp v105, v103 row_ror:8 row_mask:0xf bank_mask:0xf
	v_lshl_add_u64 v[126:127], v[244:245], 0, v[96:97]
	v_lshl_add_u64 v[122:123], s[66:67], 0, v[122:123]
	v_lshl_add_u64 v[122:123], v[122:123], 0, v[96:97]
	s_nop 0
	v_add_f32_e32 v103, v103, v105
	s_nop 1
	v_mov_b32_dpp v105, v103 row_shl:4 row_mask:0xf bank_mask:0x5
	v_mov_b32_dpp v105, v103 row_shr:4 row_mask:0xf bank_mask:0xa
	s_nop 0
	v_add_f32_e32 v103, v103, v105
	s_nop 1
	v_mov_b32_dpp v105, v103 quad_perm:[2,3,0,1] row_mask:0xf bank_mask:0xf
	s_nop 0
	v_add_f32_e32 v103, v103, v105
	s_nop 1
	s_nop 0
	s_nop 0
	v_add_f32_dpp v103, v103, v103 quad_perm:[1,0,3,2] row_mask:0xf bank_mask:0xf
	v_fmamk_f32 v103, v103, 0x3c000000, v163
	v_cmp_gt_f32_e32 vcc, s86, v103
	v_mul_f32_e32 v105, 0x4b800000, v103
	s_nop 0
	v_cndmask_b32_e32 v103, v103, v105, vcc
	v_rsq_f32_e32 v103, v103
	s_nop 0
	v_mul_f32_e32 v105, 0x45800000, v103
	v_cndmask_b32_e32 v103, v103, v105, vcc
	global_load_ushort v105, v[126:127], off
	v_mul_f32_e32 v126, v242, v103
	global_load_dword v127, v[108:109], off
	v_mul_f32_e32 v124, v124, v103
	s_waitcnt vmcnt(1)
	v_lshlrev_b32_e32 v105, 16, v105
	v_mul_f32_e32 v105, 0xbfb8aa3b, v105
	v_exp_f32_e32 v105, v105
	s_waitcnt vmcnt(0)
	v_mul_f32_e32 v126, v127, v126
	v_add_f32_e32 v105, 1.0, v105
	v_rcp_f32_e32 v105, v105
	s_nop 0
	v_mul_f32_e32 v105, v105, v126
	v_cvt_pk_bf16_f32 v105, v105, s0
	v_lshl_add_u64 v[126:127], v[244:245], 0, v[112:113]
	global_store_short v[122:123], v105, off
	global_load_ushort v105, v[126:127], off
	v_mul_f32_e32 v126, v243, v103
	global_load_dword v127, v[110:111], off offset:128
	v_mul_f32_e32 v103, v125, v103
	s_waitcnt vmcnt(1)
	v_lshlrev_b32_e32 v105, 16, v105
	v_mul_f32_e32 v105, 0xbfb8aa3b, v105
	v_exp_f32_e32 v105, v105
	s_waitcnt vmcnt(0)
	v_mul_f32_e32 v126, v127, v126
	v_add_f32_e32 v105, 1.0, v105
	v_rcp_f32_e32 v105, v105
	s_nop 0
	v_mul_f32_e32 v105, v105, v126
	v_cvt_pk_bf16_f32 v105, v105, s0
	v_lshl_add_u64 v[126:127], v[244:245], 0, v[118:119]
	global_store_short v[122:123], v105, off offset:64
	global_load_ushort v105, v[126:127], off
	s_waitcnt vmcnt(0)
	v_lshlrev_b32_e32 v105, 16, v105
	global_load_dword v126, v[110:111], off offset:256
	v_mul_f32_e32 v105, 0xbfb8aa3b, v105
	v_exp_f32_e32 v105, v105
	s_waitcnt vmcnt(0)
	v_mul_f32_e32 v124, v126, v124
	v_add_f32_e32 v105, 1.0, v105
	v_rcp_f32_e32 v105, v105
	v_lshl_add_u64 v[126:127], v[244:245], 0, v[120:121]
	v_mul_f32_e32 v105, v124, v105
	v_cvt_pk_bf16_f32 v105, v105, s0
	global_store_short v[122:123], v105, off offset:128
	global_load_ushort v105, v[126:127], off
	s_waitcnt vmcnt(0)
	v_lshlrev_b32_e32 v105, 16, v105
	global_load_dword v124, v[110:111], off offset:384
	v_mul_f32_e32 v105, 0xbfb8aa3b, v105
	v_exp_f32_e32 v105, v105
	s_waitcnt vmcnt(0)
	v_mul_f32_e32 v103, v124, v103
	v_add_f32_e32 v105, 1.0, v105
	v_rcp_f32_e32 v105, v105
	s_nop 0
	v_mul_f32_e32 v103, v103, v105
	v_cvt_pk_bf16_f32 v103, v103, s0
	global_store_short v[122:123], v103, off offset:192
	ds_read_b32 v103, v238 offset:96
	ds_read_b32 v105, v239 offset:96
	v_add_u32_e32 v126, 24, v100
	v_ashrrev_i32_e32 v127, 31, v126
	v_mov_b32_e32 v244, v12
	s_waitcnt lgkmcnt(1)
	v_max_f32_e64 v103, |v103|, |v103|
	s_waitcnt lgkmcnt(0)
	v_max_f32_e32 v105, v105, v105
	v_max_f32_e32 v103, v103, v105
	v_div_scale_f32 v105, s[0:1], v103, v103, 1.0
	v_rcp_f32_e32 v122, v105
	v_mov_b32_e32 v245, v28
	v_fma_f32 v123, -v105, v122, 1.0
	v_fmac_f32_e32 v122, v123, v122
	v_div_scale_f32 v123, vcc, 1.0, v103, 1.0
	v_mul_f32_e32 v124, v123, v122
	v_fma_f32 v125, -v105, v124, v123
	v_fmac_f32_e32 v124, v125, v122
	v_fma_f32 v105, -v105, v124, v123
	v_div_fmas_f32 v105, v105, v122, v124
	v_lshlrev_b64 v[124:125], 11, v[126:127]
	v_lshl_add_u64 v[124:125], v[98:99], 0, v[124:125]
	global_load_dword v242, v[124:125], off
	global_load_dword v243, v[124:125], off offset:128
	global_load_dword v246, v[124:125], off offset:256
	global_load_dword v247, v[124:125], off offset:384
	v_div_fixup_f32 v122, v105, v103, 1.0
	v_mov_b32_e32 v124, v44
	v_mov_b32_e32 v125, v60
	s_waitcnt vmcnt(2)
	v_pk_fma_f32 v[242:243], v[244:245], v[122:123], v[242:243] op_sel_hi:[1,0,1]
	s_nop 0
	v_pk_mul_f32 v[244:245], v[242:243], v[242:243]
	s_waitcnt vmcnt(0)
	v_pk_fma_f32 v[124:125], v[124:125], v[122:123], v[246:247] op_sel_hi:[1,0,1]
	v_add_f32_e32 v103, v244, v245
	v_pk_mul_f32 v[122:123], v[124:125], v[124:125]
	s_nop 0
	v_add_f32_e32 v103, v103, v122
	v_add_f32_e32 v103, v103, v123
	v_mov_b32_e32 v105, v103
	v_mov_b32_e32 v255, v103
	s_nop 1
	v_permlane16_swap_b32_e32 v105, v255
	s_nop 1
	v_mov_b32_dpp v105, v255 quad_perm:[0,1,2,3] row_mask:0x5 bank_mask:0xf
	v_mad_i64_i32 v[122:123], s[0:1], v126, s74, v[106:107]
	v_lshl_add_u64 v[244:245], v[122:123], 0, s[96:97]
	v_lshlrev_b64 v[122:123], 10, v[126:127]
	s_nop 0
	v_add_f32_e32 v103, v103, v105
	s_nop 1
	v_mov_b32_dpp v105, v103 row_ror:8 row_mask:0xf bank_mask:0xf
	v_lshl_add_u64 v[126:127], v[244:245], 0, v[96:97]
	v_lshl_add_u64 v[122:123], s[66:67], 0, v[122:123]
	v_lshl_add_u64 v[122:123], v[122:123], 0, v[96:97]
	s_nop 0
	v_add_f32_e32 v103, v103, v105
	s_nop 1
	v_mov_b32_dpp v105, v103 row_shl:4 row_mask:0xf bank_mask:0x5
	v_mov_b32_dpp v105, v103 row_shr:4 row_mask:0xf bank_mask:0xa
	s_nop 0
	v_add_f32_e32 v103, v103, v105
	s_nop 1
	v_mov_b32_dpp v105, v103 quad_perm:[2,3,0,1] row_mask:0xf bank_mask:0xf
	s_nop 0
	v_add_f32_e32 v103, v103, v105
	s_nop 1
	s_nop 0
	s_nop 0
	v_add_f32_dpp v103, v103, v103 quad_perm:[1,0,3,2] row_mask:0xf bank_mask:0xf
	v_fmamk_f32 v103, v103, 0x3c000000, v163
	v_cmp_gt_f32_e32 vcc, s86, v103
	v_mul_f32_e32 v105, 0x4b800000, v103
	s_nop 0
	v_cndmask_b32_e32 v103, v103, v105, vcc
	v_rsq_f32_e32 v103, v103
	s_nop 0
	v_mul_f32_e32 v105, 0x45800000, v103
	v_cndmask_b32_e32 v103, v103, v105, vcc
	global_load_ushort v105, v[126:127], off
	v_mul_f32_e32 v126, v242, v103
	global_load_dword v127, v[108:109], off
	v_mul_f32_e32 v124, v124, v103
	s_waitcnt vmcnt(1)
	v_lshlrev_b32_e32 v105, 16, v105
	v_mul_f32_e32 v105, 0xbfb8aa3b, v105
	v_exp_f32_e32 v105, v105
	s_waitcnt vmcnt(0)
	v_mul_f32_e32 v126, v127, v126
	v_add_f32_e32 v105, 1.0, v105
	v_rcp_f32_e32 v105, v105
	s_nop 0
	v_mul_f32_e32 v105, v105, v126
	v_cvt_pk_bf16_f32 v105, v105, s0
	v_lshl_add_u64 v[126:127], v[244:245], 0, v[112:113]
	global_store_short v[122:123], v105, off
	global_load_ushort v105, v[126:127], off
	v_mul_f32_e32 v126, v243, v103
	global_load_dword v127, v[110:111], off offset:128
	v_mul_f32_e32 v103, v125, v103
	s_waitcnt vmcnt(1)
	v_lshlrev_b32_e32 v105, 16, v105
	v_mul_f32_e32 v105, 0xbfb8aa3b, v105
	v_exp_f32_e32 v105, v105
	s_waitcnt vmcnt(0)
	v_mul_f32_e32 v126, v127, v126
	v_add_f32_e32 v105, 1.0, v105
	v_rcp_f32_e32 v105, v105
	s_nop 0
	v_mul_f32_e32 v105, v105, v126
	v_cvt_pk_bf16_f32 v105, v105, s0
	v_lshl_add_u64 v[126:127], v[244:245], 0, v[118:119]
	global_store_short v[122:123], v105, off offset:64
	global_load_ushort v105, v[126:127], off
	s_waitcnt vmcnt(0)
	v_lshlrev_b32_e32 v105, 16, v105
	global_load_dword v126, v[110:111], off offset:256
	v_mul_f32_e32 v105, 0xbfb8aa3b, v105
	v_exp_f32_e32 v105, v105
	s_waitcnt vmcnt(0)
	v_mul_f32_e32 v124, v126, v124
	v_add_f32_e32 v105, 1.0, v105
	v_rcp_f32_e32 v105, v105
	v_lshl_add_u64 v[126:127], v[244:245], 0, v[120:121]
	v_mul_f32_e32 v105, v124, v105
	v_cvt_pk_bf16_f32 v105, v105, s0
	global_store_short v[122:123], v105, off offset:128
	global_load_ushort v105, v[126:127], off
	s_waitcnt vmcnt(0)
	v_lshlrev_b32_e32 v105, 16, v105
	global_load_dword v124, v[110:111], off offset:384
	v_mul_f32_e32 v105, 0xbfb8aa3b, v105
	v_exp_f32_e32 v105, v105
	s_waitcnt vmcnt(0)
	v_mul_f32_e32 v103, v124, v103
	v_add_f32_e32 v105, 1.0, v105
	v_rcp_f32_e32 v105, v105
	s_nop 0
	v_mul_f32_e32 v103, v103, v105
	v_cvt_pk_bf16_f32 v103, v103, s0
	global_store_short v[122:123], v103, off offset:192
	ds_read_b32 v103, v238 offset:100
	ds_read_b32 v105, v239 offset:100
	v_add_u32_e32 v126, 25, v100
	v_ashrrev_i32_e32 v127, 31, v126
	v_mov_b32_e32 v244, v13
	s_waitcnt lgkmcnt(1)
	v_max_f32_e64 v103, |v103|, |v103|
	s_waitcnt lgkmcnt(0)
	v_max_f32_e32 v105, v105, v105
	v_max_f32_e32 v103, v103, v105
	v_div_scale_f32 v105, s[0:1], v103, v103, 1.0
	v_rcp_f32_e32 v122, v105
	v_mov_b32_e32 v245, v29
	v_fma_f32 v123, -v105, v122, 1.0
	v_fmac_f32_e32 v122, v123, v122
	v_div_scale_f32 v123, vcc, 1.0, v103, 1.0
	v_mul_f32_e32 v124, v123, v122
	v_fma_f32 v125, -v105, v124, v123
	v_fmac_f32_e32 v124, v125, v122
	v_fma_f32 v105, -v105, v124, v123
	v_div_fmas_f32 v105, v105, v122, v124
	v_lshlrev_b64 v[124:125], 11, v[126:127]
	v_lshl_add_u64 v[124:125], v[98:99], 0, v[124:125]
	global_load_dword v242, v[124:125], off
	global_load_dword v243, v[124:125], off offset:128
	global_load_dword v246, v[124:125], off offset:256
	global_load_dword v247, v[124:125], off offset:384
	v_div_fixup_f32 v122, v105, v103, 1.0
	v_mov_b32_e32 v124, v45
	v_mov_b32_e32 v125, v61
	s_waitcnt vmcnt(2)
	v_pk_fma_f32 v[242:243], v[244:245], v[122:123], v[242:243] op_sel_hi:[1,0,1]
	s_nop 0
	v_pk_mul_f32 v[244:245], v[242:243], v[242:243]
	s_waitcnt vmcnt(0)
	v_pk_fma_f32 v[124:125], v[124:125], v[122:123], v[246:247] op_sel_hi:[1,0,1]
	v_add_f32_e32 v103, v244, v245
	v_pk_mul_f32 v[122:123], v[124:125], v[124:125]
	s_nop 0
	v_add_f32_e32 v103, v103, v122
	v_add_f32_e32 v103, v103, v123
	v_mov_b32_e32 v105, v103
	v_mov_b32_e32 v255, v103
	s_nop 1
	v_permlane16_swap_b32_e32 v105, v255
	s_nop 1
	v_mov_b32_dpp v105, v255 quad_perm:[0,1,2,3] row_mask:0x5 bank_mask:0xf
	v_mad_i64_i32 v[122:123], s[0:1], v126, s74, v[106:107]
	v_lshl_add_u64 v[244:245], v[122:123], 0, s[96:97]
	v_lshlrev_b64 v[122:123], 10, v[126:127]
	s_nop 0
	v_add_f32_e32 v103, v103, v105
	s_nop 1
	v_mov_b32_dpp v105, v103 row_ror:8 row_mask:0xf bank_mask:0xf
	v_lshl_add_u64 v[126:127], v[244:245], 0, v[96:97]
	v_lshl_add_u64 v[122:123], s[66:67], 0, v[122:123]
	v_lshl_add_u64 v[122:123], v[122:123], 0, v[96:97]
	s_nop 0
	v_add_f32_e32 v103, v103, v105
	s_nop 1
	v_mov_b32_dpp v105, v103 row_shl:4 row_mask:0xf bank_mask:0x5
	v_mov_b32_dpp v105, v103 row_shr:4 row_mask:0xf bank_mask:0xa
	s_nop 0
	v_add_f32_e32 v103, v103, v105
	s_nop 1
	v_mov_b32_dpp v105, v103 quad_perm:[2,3,0,1] row_mask:0xf bank_mask:0xf
	s_nop 0
	v_add_f32_e32 v103, v103, v105
	s_nop 1
	s_nop 0
	s_nop 0
	v_add_f32_dpp v103, v103, v103 quad_perm:[1,0,3,2] row_mask:0xf bank_mask:0xf
	v_fmamk_f32 v103, v103, 0x3c000000, v163
	v_cmp_gt_f32_e32 vcc, s86, v103
	v_mul_f32_e32 v105, 0x4b800000, v103
	s_nop 0
	v_cndmask_b32_e32 v103, v103, v105, vcc
	v_rsq_f32_e32 v103, v103
	s_nop 0
	v_mul_f32_e32 v105, 0x45800000, v103
	v_cndmask_b32_e32 v103, v103, v105, vcc
	global_load_ushort v105, v[126:127], off
	v_mul_f32_e32 v126, v242, v103
	global_load_dword v127, v[108:109], off
	v_mul_f32_e32 v124, v124, v103
	s_waitcnt vmcnt(1)
	v_lshlrev_b32_e32 v105, 16, v105
	v_mul_f32_e32 v105, 0xbfb8aa3b, v105
	v_exp_f32_e32 v105, v105
	s_waitcnt vmcnt(0)
	v_mul_f32_e32 v126, v127, v126
	v_add_f32_e32 v105, 1.0, v105
	v_rcp_f32_e32 v105, v105
	s_nop 0
	v_mul_f32_e32 v105, v105, v126
	v_cvt_pk_bf16_f32 v105, v105, s0
	v_lshl_add_u64 v[126:127], v[244:245], 0, v[112:113]
	global_store_short v[122:123], v105, off
	global_load_ushort v105, v[126:127], off
	v_mul_f32_e32 v126, v243, v103
	global_load_dword v127, v[110:111], off offset:128
	v_mul_f32_e32 v103, v125, v103
	s_waitcnt vmcnt(1)
	v_lshlrev_b32_e32 v105, 16, v105
	v_mul_f32_e32 v105, 0xbfb8aa3b, v105
	v_exp_f32_e32 v105, v105
	s_waitcnt vmcnt(0)
	v_mul_f32_e32 v126, v127, v126
	v_add_f32_e32 v105, 1.0, v105
	v_rcp_f32_e32 v105, v105
	s_nop 0
	v_mul_f32_e32 v105, v105, v126
	v_cvt_pk_bf16_f32 v105, v105, s0
	v_lshl_add_u64 v[126:127], v[244:245], 0, v[118:119]
	global_store_short v[122:123], v105, off offset:64
	global_load_ushort v105, v[126:127], off
	s_waitcnt vmcnt(0)
	v_lshlrev_b32_e32 v105, 16, v105
	global_load_dword v126, v[110:111], off offset:256
	v_mul_f32_e32 v105, 0xbfb8aa3b, v105
	v_exp_f32_e32 v105, v105
	s_waitcnt vmcnt(0)
	v_mul_f32_e32 v124, v126, v124
	v_add_f32_e32 v105, 1.0, v105
	v_rcp_f32_e32 v105, v105
	v_lshl_add_u64 v[126:127], v[244:245], 0, v[120:121]
	v_mul_f32_e32 v105, v124, v105
	v_cvt_pk_bf16_f32 v105, v105, s0
	global_store_short v[122:123], v105, off offset:128
	global_load_ushort v105, v[126:127], off
	s_waitcnt vmcnt(0)
	v_lshlrev_b32_e32 v105, 16, v105
	global_load_dword v124, v[110:111], off offset:384
	v_mul_f32_e32 v105, 0xbfb8aa3b, v105
	v_exp_f32_e32 v105, v105
	s_waitcnt vmcnt(0)
	v_mul_f32_e32 v103, v124, v103
	v_add_f32_e32 v105, 1.0, v105
	v_rcp_f32_e32 v105, v105
	s_nop 0
	v_mul_f32_e32 v103, v103, v105
	v_cvt_pk_bf16_f32 v103, v103, s0
	global_store_short v[122:123], v103, off offset:192
	ds_read_b32 v103, v238 offset:104
	ds_read_b32 v105, v239 offset:104
	v_add_u32_e32 v126, 26, v100
	v_ashrrev_i32_e32 v127, 31, v126
	v_mov_b32_e32 v244, v14
	s_waitcnt lgkmcnt(1)
	v_max_f32_e64 v103, |v103|, |v103|
	s_waitcnt lgkmcnt(0)
	v_max_f32_e32 v105, v105, v105
	v_max_f32_e32 v103, v103, v105
	v_div_scale_f32 v105, s[0:1], v103, v103, 1.0
	v_rcp_f32_e32 v122, v105
	v_mov_b32_e32 v245, v30
	v_fma_f32 v123, -v105, v122, 1.0
	v_fmac_f32_e32 v122, v123, v122
	v_div_scale_f32 v123, vcc, 1.0, v103, 1.0
	v_mul_f32_e32 v124, v123, v122
	v_fma_f32 v125, -v105, v124, v123
	v_fmac_f32_e32 v124, v125, v122
	v_fma_f32 v105, -v105, v124, v123
	v_div_fmas_f32 v105, v105, v122, v124
	v_lshlrev_b64 v[124:125], 11, v[126:127]
	v_lshl_add_u64 v[124:125], v[98:99], 0, v[124:125]
	global_load_dword v242, v[124:125], off
	global_load_dword v243, v[124:125], off offset:128
	global_load_dword v246, v[124:125], off offset:256
	global_load_dword v247, v[124:125], off offset:384
	v_div_fixup_f32 v122, v105, v103, 1.0
	v_mov_b32_e32 v124, v46
	v_mov_b32_e32 v125, v62
	s_waitcnt vmcnt(2)
	v_pk_fma_f32 v[242:243], v[244:245], v[122:123], v[242:243] op_sel_hi:[1,0,1]
	s_nop 0
	v_pk_mul_f32 v[244:245], v[242:243], v[242:243]
	s_waitcnt vmcnt(0)
	v_pk_fma_f32 v[124:125], v[124:125], v[122:123], v[246:247] op_sel_hi:[1,0,1]
	v_add_f32_e32 v103, v244, v245
	v_pk_mul_f32 v[122:123], v[124:125], v[124:125]
	s_nop 0
	v_add_f32_e32 v103, v103, v122
	v_add_f32_e32 v103, v103, v123
	v_mov_b32_e32 v105, v103
	v_mov_b32_e32 v255, v103
	s_nop 1
	v_permlane16_swap_b32_e32 v105, v255
	s_nop 1
	v_mov_b32_dpp v105, v255 quad_perm:[0,1,2,3] row_mask:0x5 bank_mask:0xf
	v_mad_i64_i32 v[122:123], s[0:1], v126, s74, v[106:107]
	v_lshl_add_u64 v[244:245], v[122:123], 0, s[96:97]
	v_lshlrev_b64 v[122:123], 10, v[126:127]
	s_nop 0
	v_add_f32_e32 v103, v103, v105
	s_nop 1
	v_mov_b32_dpp v105, v103 row_ror:8 row_mask:0xf bank_mask:0xf
	v_lshl_add_u64 v[126:127], v[244:245], 0, v[96:97]
	v_lshl_add_u64 v[122:123], s[66:67], 0, v[122:123]
	v_lshl_add_u64 v[122:123], v[122:123], 0, v[96:97]
	s_nop 0
	v_add_f32_e32 v103, v103, v105
	s_nop 1
	v_mov_b32_dpp v105, v103 row_shl:4 row_mask:0xf bank_mask:0x5
	v_mov_b32_dpp v105, v103 row_shr:4 row_mask:0xf bank_mask:0xa
	s_nop 0
	v_add_f32_e32 v103, v103, v105
	s_nop 1
	v_mov_b32_dpp v105, v103 quad_perm:[2,3,0,1] row_mask:0xf bank_mask:0xf
	s_nop 0
	v_add_f32_e32 v103, v103, v105
	s_nop 1
	s_nop 0
	s_nop 0
	v_add_f32_dpp v103, v103, v103 quad_perm:[1,0,3,2] row_mask:0xf bank_mask:0xf
	v_fmamk_f32 v103, v103, 0x3c000000, v163
	v_cmp_gt_f32_e32 vcc, s86, v103
	v_mul_f32_e32 v105, 0x4b800000, v103
	s_nop 0
	v_cndmask_b32_e32 v103, v103, v105, vcc
	v_rsq_f32_e32 v103, v103
	s_nop 0
	v_mul_f32_e32 v105, 0x45800000, v103
	v_cndmask_b32_e32 v103, v103, v105, vcc
	global_load_ushort v105, v[126:127], off
	v_mul_f32_e32 v126, v242, v103
	global_load_dword v127, v[108:109], off
	v_mul_f32_e32 v124, v124, v103
	s_waitcnt vmcnt(1)
	v_lshlrev_b32_e32 v105, 16, v105
	v_mul_f32_e32 v105, 0xbfb8aa3b, v105
	v_exp_f32_e32 v105, v105
	s_waitcnt vmcnt(0)
	v_mul_f32_e32 v126, v127, v126
	v_add_f32_e32 v105, 1.0, v105
	v_rcp_f32_e32 v105, v105
	s_nop 0
	v_mul_f32_e32 v105, v105, v126
	v_cvt_pk_bf16_f32 v105, v105, s0
	v_lshl_add_u64 v[126:127], v[244:245], 0, v[112:113]
	global_store_short v[122:123], v105, off
	global_load_ushort v105, v[126:127], off
	v_mul_f32_e32 v126, v243, v103
	global_load_dword v127, v[110:111], off offset:128
	v_mul_f32_e32 v103, v125, v103
	s_waitcnt vmcnt(1)
	v_lshlrev_b32_e32 v105, 16, v105
	v_mul_f32_e32 v105, 0xbfb8aa3b, v105
	v_exp_f32_e32 v105, v105
	s_waitcnt vmcnt(0)
	v_mul_f32_e32 v126, v127, v126
	v_add_f32_e32 v105, 1.0, v105
	v_rcp_f32_e32 v105, v105
	s_nop 0
	v_mul_f32_e32 v105, v105, v126
	v_cvt_pk_bf16_f32 v105, v105, s0
	v_lshl_add_u64 v[126:127], v[244:245], 0, v[118:119]
	global_store_short v[122:123], v105, off offset:64
	global_load_ushort v105, v[126:127], off
	s_waitcnt vmcnt(0)
	v_lshlrev_b32_e32 v105, 16, v105
	global_load_dword v126, v[110:111], off offset:256
	v_mul_f32_e32 v105, 0xbfb8aa3b, v105
	v_exp_f32_e32 v105, v105
	s_waitcnt vmcnt(0)
	v_mul_f32_e32 v124, v126, v124
	v_add_f32_e32 v105, 1.0, v105
	v_rcp_f32_e32 v105, v105
	v_lshl_add_u64 v[126:127], v[244:245], 0, v[120:121]
	v_mul_f32_e32 v105, v124, v105
	v_cvt_pk_bf16_f32 v105, v105, s0
	global_store_short v[122:123], v105, off offset:128
	global_load_ushort v105, v[126:127], off
	s_waitcnt vmcnt(0)
	v_lshlrev_b32_e32 v105, 16, v105
	global_load_dword v124, v[110:111], off offset:384
	v_mul_f32_e32 v105, 0xbfb8aa3b, v105
	v_exp_f32_e32 v105, v105
	s_waitcnt vmcnt(0)
	v_mul_f32_e32 v103, v124, v103
	v_add_f32_e32 v105, 1.0, v105
	v_rcp_f32_e32 v105, v105
	s_nop 0
	v_mul_f32_e32 v103, v103, v105
	v_cvt_pk_bf16_f32 v103, v103, s0
	global_store_short v[122:123], v103, off offset:192
	v_add_u32_e32 v122, 27, v100
	v_ashrrev_i32_e32 v123, 31, v122
	v_lshlrev_b64 v[124:125], 11, v[122:123]
	v_lshl_add_u64 v[124:125], v[98:99], 0, v[124:125]
	global_load_dword v126, v[124:125], off
	global_load_dword v127, v[124:125], off offset:128
	global_load_dword v242, v[124:125], off offset:256
	global_load_dword v243, v[124:125], off offset:384
	v_mad_i64_i32 v[106:107], s[0:1], v122, s74, v[106:107]
	v_lshl_add_u64 v[106:107], v[106:107], 0, s[96:97]
	v_lshl_add_u64 v[124:125], v[106:107], 0, v[96:97]
	global_load_ushort v103, v[124:125], off
	v_lshl_add_u64 v[112:113], v[106:107], 0, v[112:113]
	v_lshl_add_u64 v[118:119], v[106:107], 0, v[118:119]
	v_lshl_add_u64 v[106:107], v[106:107], 0, v[120:121]
	global_load_ushort v105, v[112:113], off
	s_nop 0
	global_load_ushort v118, v[118:119], off
	s_nop 0
	global_load_ushort v119, v[106:107], off
	global_load_dword v120, v[108:109], off
	global_load_dword v121, v[110:111], off offset:128
	global_load_dword v124, v[110:111], off offset:256
	global_load_dword v125, v[110:111], off offset:384
	ds_read_b32 v109, v239 offset:108
	ds_read_b32 v110, v238 offset:108
	v_mov_b32_e32 v106, v15
	v_mov_b32_e32 v107, v31
	v_mov_b32_e32 v108, v47
	s_waitcnt lgkmcnt(1)
	v_max_f32_e32 v109, v109, v109
	s_waitcnt lgkmcnt(0)
	v_max_f32_e64 v110, |v110|, |v110|
	v_max_f32_e32 v110, v110, v109
	v_div_scale_f32 v111, s[0:1], v110, v110, 1.0
	v_rcp_f32_e32 v112, v111
	v_div_scale_f32 v113, vcc, 1.0, v110, 1.0
	v_mov_b32_e32 v109, v63
	v_fma_f32 v238, -v111, v112, 1.0
	v_fmac_f32_e32 v112, v238, v112
	v_mul_f32_e32 v238, v113, v112
	v_fma_f32 v239, -v111, v238, v113
	v_fmac_f32_e32 v238, v239, v112
	v_fma_f32 v111, -v111, v238, v113
	v_div_fmas_f32 v111, v111, v112, v238
	v_div_fixup_f32 v110, v111, v110, 1.0
	s_waitcnt vmcnt(10)
	v_pk_fma_f32 v[106:107], v[106:107], v[110:111], v[126:127] op_sel_hi:[1,0,1]
	s_waitcnt vmcnt(8)
	v_pk_fma_f32 v[108:109], v[108:109], v[110:111], v[242:243] op_sel_hi:[1,0,1]
	v_pk_mul_f32 v[110:111], v[106:107], v[106:107]
	v_pk_mul_f32 v[112:113], v[108:109], v[108:109]
	v_add_f32_e32 v110, v110, v111
	v_add_f32_e32 v110, v110, v112
	v_add_f32_e32 v112, v110, v113
	v_mov_b32_e32 v113, v112
	v_mov_b32_e32 v255, v112
	s_nop 1
	v_permlane16_swap_b32_e32 v113, v255
	s_nop 1
	s_nop 0
	v_lshlrev_b64 v[110:111], 10, v[122:123]
	v_lshl_add_u64 v[110:111], s[66:67], 0, v[110:111]
	v_lshl_add_u64 v[110:111], v[110:111], 0, v[96:97]
	s_waitcnt vmcnt(7)
	v_lshlrev_b32_e32 v96, 16, v103
	s_nop 0
	v_add_f32_e32 v103, v113, v255
	s_nop 1
	v_mov_b32_dpp v112, v103 row_ror:8 row_mask:0xf bank_mask:0xf
	s_waitcnt vmcnt(5)
	v_lshlrev_b32_e32 v113, 16, v118
	s_waitcnt vmcnt(4)
	v_lshlrev_b32_e32 v118, 16, v119
	v_lshlrev_b32_e32 v105, 16, v105
	v_mul_f32_e32 v96, 0xbfb8aa3b, v96
	s_nop 0
	v_add_f32_e32 v103, v103, v112
	s_nop 1
	v_mov_b32_dpp v112, v103 row_shl:4 row_mask:0xf bank_mask:0x5
	v_mov_b32_dpp v112, v103 row_shr:4 row_mask:0xf bank_mask:0xa
	v_mul_f32_e32 v113, 0xbfb8aa3b, v113
	v_mul_f32_e32 v118, 0xbfb8aa3b, v118
	v_mul_f32_e32 v105, 0xbfb8aa3b, v105
	v_exp_f32_e32 v96, v96
	s_nop 0
	v_add_f32_e32 v103, v103, v112
	s_nop 1
	v_mov_b32_dpp v112, v103 quad_perm:[2,3,0,1] row_mask:0xf bank_mask:0xf
	v_exp_f32_e32 v113, v113
	v_exp_f32_e32 v118, v118
	v_exp_f32_e32 v105, v105
	v_add_f32_e32 v96, 1.0, v96
	s_nop 0
	v_add_f32_e32 v103, v103, v112
	s_nop 1
	s_nop 0
	v_add_f32_e32 v113, 1.0, v113
	v_add_f32_e32 v118, 1.0, v118
	v_add_f32_e32 v105, 1.0, v105
	v_rcp_f32_e32 v96, v96
	s_nop 0
	v_add_f32_dpp v103, v103, v103 quad_perm:[1,0,3,2] row_mask:0xf bank_mask:0xf
	v_fmamk_f32 v103, v103, 0x3c000000, v163
	v_mul_f32_e32 v112, 0x4b800000, v103
	v_cmp_gt_f32_e32 vcc, s86, v103
	v_rcp_f32_e32 v105, v105
	s_nop 0
	v_cndmask_b32_e32 v103, v103, v112, vcc
	v_rsq_f32_e32 v103, v103
	v_rcp_f32_e32 v112, v113
	v_rcp_f32_e32 v113, v118
	v_mul_f32_e32 v118, 0x45800000, v103
	v_cndmask_b32_e32 v103, v103, v118, vcc
	v_mul_f32_e32 v106, v106, v103
	v_mul_f32_e32 v107, v107, v103
	v_mul_f32_e32 v108, v108, v103
	v_mul_f32_e32 v103, v109, v103
	s_waitcnt vmcnt(3)
	v_mul_f32_e32 v106, v120, v106
	s_waitcnt vmcnt(2)
	v_mul_f32_e32 v107, v121, v107
	s_waitcnt vmcnt(1)
	v_mul_f32_e32 v108, v124, v108
	s_waitcnt vmcnt(0)
	v_mul_f32_e32 v103, v125, v103
	v_mul_f32_e32 v96, v96, v106
	v_mul_f32_e32 v105, v105, v107
	v_mul_f32_e32 v106, v108, v112
	v_mul_f32_e32 v103, v103, v113
	v_cvt_pk_bf16_f32 v96, v96, s0
	v_cvt_pk_bf16_f32 v105, v105, s0
	v_cvt_pk_bf16_f32 v106, v106, s0
	v_cvt_pk_bf16_f32 v103, v103, s0
	global_store_short v[110:111], v96, off
	global_store_short v[110:111], v105, off offset:64
	global_store_short v[110:111], v106, off offset:128
	global_store_short v[110:111], v103, off offset:192
	s_cbranch_execnz .LBB0_927
	s_branch .LBB0_1111

.LBB0_1296:
	v_min_i32_e32 v0, 0x4000, v12
	v_ashrrev_i32_e32 v0, 11, v0
	v_mul_hi_i32_i24_e32 v1, 0x9000, v0
	v_mul_i32_i24_e32 v0, 0x9000, v0
	v_lshl_add_u64 v[0:1], s[6:7], 0, v[0:1]
	v_lshl_add_u64 v[26:27], v[0:1], 0, s[16:17]
	v_lshl_add_u64 v[58:59], s[92:93], 0, v[20:21]
	v_lshl_add_u64 v[4:5], v[26:27], 0, v[96:97]
	v_lshl_add_u64 v[24:25], v[0:1], 0, v[96:97]
	global_load_dwordx4 v[38:41], v[58:59], off offset:16
	global_load_dwordx4 v[8:11], v[58:59], off
	global_load_dwordx4 v[42:45], v[16:17], off offset:16
	global_load_dwordx4 v[46:49], v[16:17], off
	global_load_dwordx4 v[50:53], v[24:25], off offset:16
	global_load_dwordx4 v[54:57], v[24:25], off
	global_load_dwordx4 v[0:3], v[4:5], off offset:16
	s_nop 0
	global_load_dwordx4 v[4:7], v[4:5], off
	v_mov_b32_e32 v23, v97
	v_lshl_add_u64 v[26:27], v[26:27], 0, v[22:23]
	v_lshl_add_u64 v[30:31], s[92:93], 0, v[18:19]
	v_add_u32_e32 v12, s8, v12
	v_lshl_add_u64 v[18:19], v[18:19], 0, s[30:31]
	v_lshl_add_u64 v[20:21], v[20:21], 0, s[14:15]
	s_waitcnt vmcnt(7)
	v_mov_b32_e32 v67, v39
	s_waitcnt vmcnt(6)
	v_mov_b32_e32 v66, v9
	v_pk_mul_f32 v[66:67], v[66:67], v[66:67]
	s_waitcnt vmcnt(1)
	v_pk_add_f32 v[60:61], v[0:1], 1.0 op_sel_hi:[1,0]
	s_waitcnt vmcnt(0)
	v_pk_add_f32 v[62:63], v[6:7], 1.0 op_sel_hi:[1,0]
	v_mov_b32_e32 v6, v8
	v_mov_b32_e32 v7, v38
	v_mov_b32_e32 v0, v10
	v_mov_b32_e32 v1, v40
	v_pk_fma_f32 v[6:7], v[6:7], v[6:7], v[66:67]
	v_pk_add_f32 v[64:65], v[4:5], 1.0 op_sel_hi:[1,0]
	v_mov_b32_e32 v4, v11
	v_mov_b32_e32 v5, v41
	v_pk_fma_f32 v[0:1], v[0:1], v[0:1], v[6:7]
	v_pk_add_f32 v[68:69], v[2:3], 1.0 op_sel_hi:[1,0]
	v_pk_fma_f32 v[66:67], v[4:5], v[4:5], v[0:1]
	global_load_dwordx4 v[0:3], v[58:59], off offset:2064
	global_load_dwordx4 v[4:7], v[58:59], off offset:2048
	global_load_dwordx4 v[86:89], v[14:15], off offset:16
	global_load_dwordx4 v[90:93], v[14:15], off
	global_load_dwordx4 v[98:101], v[24:25], off offset:2064
	global_load_dwordx4 v[106:109], v[24:25], off offset:2048
	global_load_dwordx4 v[110:113], v[26:27], off offset:16
	global_load_dwordx4 v[114:117], v[26:27], off
	v_add_f32_e32 v13, v66, v67
	s_waitcnt vmcnt(7)
	v_mov_b32_e32 v75, v1
	s_waitcnt vmcnt(6)
	v_mov_b32_e32 v74, v5
	v_mov_b32_e32 v72, v4
	v_mov_b32_e32 v73, v0
	v_pk_mul_f32 v[74:75], v[74:75], v[74:75]
	v_mov_b32_e32 v58, v6
	v_mov_b32_e32 v59, v2
	v_pk_fma_f32 v[72:73], v[72:73], v[72:73], v[74:75]
	v_mov_b32_e32 v70, v7
	v_mov_b32_e32 v71, v3
	v_pk_fma_f32 v[58:59], v[58:59], v[58:59], v[72:73]
	s_nop 0
	v_pk_fma_f32 v[58:59], v[70:71], v[70:71], v[58:59]
	s_nop 0
	v_add_f32_e32 v13, v13, v58
	v_add_f32_e32 v13, v13, v59
	v_mov_b32_e32 v23, v13
	v_mov_b32_e32 v255, v13
	s_nop 1
	v_permlane32_swap_b32_e32 v23, v255
	s_nop 1
	s_nop 0
	s_waitcnt lgkmcnt(0)
	v_add_f32_e32 v13, v23, v255
	v_mov_b32_e32 v23, v13
	v_mov_b32_e32 v255, v13
	s_nop 1
	v_permlane16_swap_b32_e32 v23, v255
	s_nop 1
	v_mov_b32_dpp v23, v255 quad_perm:[0,1,2,3] row_mask:0x5 bank_mask:0xf
	s_nop 0
	v_add_f32_e32 v13, v13, v23
	s_nop 1
	v_mov_b32_dpp v23, v13 row_ror:8 row_mask:0xf bank_mask:0xf
	s_nop 0
	v_add_f32_e32 v13, v13, v23
	s_nop 1
	v_mov_b32_dpp v23, v13 row_shl:4 row_mask:0xf bank_mask:0x5
	v_mov_b32_dpp v23, v13 row_shr:4 row_mask:0xf bank_mask:0xa
	s_nop 0
	v_add_f32_e32 v13, v13, v23
	s_nop 1
	v_mov_b32_dpp v23, v13 quad_perm:[2,3,0,1] row_mask:0xf bank_mask:0xf
	s_nop 0
	v_add_f32_e32 v13, v13, v23
	s_nop 1
	s_nop 0
	s_nop 0
	v_add_f32_dpp v13, v13, v13 quad_perm:[1,0,3,2] row_mask:0xf bank_mask:0xf
	v_fmamk_f32 v13, v13, 0x3a800000, v163
	v_cmp_gt_f32_e32 vcc, s86, v13
	v_mul_f32_e32 v23, 0x4b800000, v13
	s_nop 0
	v_cndmask_b32_e32 v13, v13, v23, vcc
	v_rsq_f32_e32 v13, v13
	s_nop 0
	v_mul_f32_e32 v23, 0x45800000, v13
	v_cndmask_b32_e32 v28, v13, v23, vcc
	v_pk_mul_f32 v[8:9], v[8:9], v[28:29] op_sel_hi:[1,0]
	v_pk_mul_f32 v[10:11], v[10:11], v[28:29] op_sel_hi:[1,0]
	v_pk_mul_f32 v[8:9], v[46:47], v[8:9]
	v_pk_mul_f32 v[10:11], v[48:49], v[10:11]
	v_pk_fma_f32 v[8:9], v[64:65], v[8:9], v[54:55]
	v_pk_fma_f32 v[10:11], v[62:63], v[10:11], v[56:57]
	v_cvt_pk_bf16_f32 v8, v8, v9
	v_cvt_pk_bf16_f32 v9, v10, v11
	v_pk_mul_f32 v[10:11], v[38:39], v[28:29] op_sel_hi:[1,0]
	v_pk_mul_f32 v[38:39], v[40:41], v[28:29] op_sel_hi:[1,0]
	v_pk_mul_f32 v[10:11], v[10:11], v[42:43]
	v_pk_mul_f32 v[38:39], v[38:39], v[44:45]
	v_pk_fma_f32 v[10:11], v[10:11], v[60:61], v[50:51]
	v_pk_fma_f32 v[38:39], v[38:39], v[68:69], v[52:53]
	v_add_co_u32_e32 v30, vcc, s28, v30
	v_cvt_pk_bf16_f32 v10, v10, v11
	v_cvt_pk_bf16_f32 v11, v38, v39
	v_addc_co_u32_e32 v31, vcc, 0, v31, vcc
	global_store_dwordx4 v[30:31], v[8:11], off
	s_nop 0
	s_nop 0
	v_pk_mul_f32 v[4:5], v[4:5], v[28:29] op_sel_hi:[1,0]
	v_pk_mul_f32 v[6:7], v[6:7], v[28:29] op_sel_hi:[1,0]
	v_pk_mul_f32 v[0:1], v[0:1], v[28:29] op_sel_hi:[1,0]
	v_pk_mul_f32 v[2:3], v[2:3], v[28:29] op_sel_hi:[1,0]
	v_cmp_le_i32_e32 vcc, s38, v12
	s_or_b64 s[12:13], vcc, s[12:13]
	s_waitcnt vmcnt(6)
	v_pk_mul_f32 v[0:1], v[0:1], v[86:87]
	s_waitcnt vmcnt(5)
	v_pk_mul_f32 v[4:5], v[4:5], v[90:91]
	v_pk_mul_f32 v[6:7], v[6:7], v[92:93]
	v_pk_mul_f32 v[2:3], v[2:3], v[88:89]
	s_waitcnt vmcnt(1)
	v_pk_add_f32 v[24:25], v[114:115], 1.0 op_sel_hi:[1,0]
	s_nop 0
	v_pk_fma_f32 v[4:5], v[4:5], v[24:25], v[106:107]
	v_pk_add_f32 v[24:25], v[116:117], 1.0 op_sel_hi:[1,0]
	v_cvt_pk_bf16_f32 v4, v4, v5
	v_pk_fma_f32 v[6:7], v[6:7], v[24:25], v[108:109]
	s_nop 0
	v_cvt_pk_bf16_f32 v5, v6, v7
	v_pk_add_f32 v[6:7], v[110:111], 1.0 op_sel_hi:[1,0]
	s_nop 0
	v_pk_fma_f32 v[0:1], v[0:1], v[6:7], v[98:99]
	v_pk_add_f32 v[6:7], v[112:113], 1.0 op_sel_hi:[1,0]
	s_nop 0
	v_pk_fma_f32 v[2:3], v[2:3], v[6:7], v[100:101]
	v_cvt_pk_bf16_f32 v6, v0, v1
	v_cvt_pk_bf16_f32 v7, v2, v3
	global_store_dwordx4 v[30:31], v[4:7], off offset:1024
	s_andn2_b64 exec, exec, s[12:13]
	s_cbranch_execnz .LBB0_1296
